# rename-safe N=1 + chain+snake MFMA order: accumulator pairs back to back, k order alternating so one operand is shared across every pair boundary (f32 sum order of the two k-steps swapped for every ot
# speedup vs baseline: 1.0173x; 1.0173x over previous
; #define PG8_STAGE(bufoff, gbase, voff) do { _Pragma("unroll") for (int _i = 0; _i < 2; ++_i) \
;         asm volatile("s_mov_b32 m0, %2\n\ts_nop 0\n\tglobal_load_lds_dwordx4 %0, %1" :: "v"((voff)[_i]), "s"((const char*)(gbase)), "s"(ldsbase + (unsigned)(bufoff) + ldsw + (unsigned)_i * 8192u) : "memory", "m0"); } while (0)
; #define PG8_LDA(dst, b, h) do { _Pragma("unroll") for (int m = 0; m < 4; ++m) _Pragma("unroll") for (int k = 0; k < 2; ++k) dst[m][k] = *(const PG8_LAS bf16x8*)(lds + PG8_SA(b, h) + aoff + m * 2048 + k * 1024); } while (0)
; #define PG8_WAIT_V(n) asm volatile("s_waitcnt vmcnt(" #n ")" ::: "memory")
; template <class Epi, class Sched, bool ALIGN_EPI = false, bool SP2 = false>
; __device__ __forceinline__ void gemm_phase(PG8_LAS unsigned char* lds, const Gemm g, const Sched& S, const Epi& E) {
;     ...
;             const bool last = (t == nt - 2);
;             const char* a1 = cA + (size_t)(t + 1) * kstep;
;             const char* a2 = last ? nA : cA + (size_t)(t + 2) * kstep; const char* b2 = last ? nB : cB + (size_t)(t + 2) * kstep;
;             const char* a3 = a2 + kstep; const char* b3 = b2 + kstep;
;             if (last && has_next) S.a_ready(nxt);
;             if constexpr (epi_has_mid<Epi>::value) { if (t == Epi::MID_T) E.mid(acc, cur, wr, wc, fr, fq); }
;             if constexpr (SP2) {
;             PG8_LDB(B0, 0, 0); PG8_LDB(B1, 0, 1); PG8_SCHED; PG8_LDA(At, 0, 0); PG8_STAGE(PG8_SA(1, 1), a1 + hstep, voffA);
;             PG8_WAIT_V(8); PG8_WAIT_L(0); PG8_BAR; PG8_MMA(0, 0, At, B0); PG8_MMA(0, 1, At, B1); PG8_BAR; PG8_SCHED;
;             PG8_LDA(At, 0, 1); PG8_STAGE(PG8_SB(0, 0), b2, voffB); PG8_STAGE(PG8_SB(0, 1), b2 + hstep, voffB); PG8_STAGE(PG8_SA(0, 0), a2, voffA);
;             PG8_WAIT_V(8); PG8_WAIT_L(0); PG8_BAR; PG8_MMA(1, 0, At, B0); PG8_MMA(1, 1, At, B1); PG8_BAR; PG8_SCHED;
;             PG8_LDB(B0, 1, 0); PG8_LDB(B1, 1, 1); PG8_SCHED; PG8_LDA(At, 1, 0); PG8_STAGE(PG8_SA(0, 1), a2 + hstep, voffA);
;             PG8_WAIT_V(8); PG8_WAIT_L(0); PG8_BAR; PG8_MMA(0, 0, At, B0); PG8_MMA(0, 1, At, B1); PG8_BAR; PG8_SCHED;
;             PG8_LDA(At, 1, 1); PG8_STAGE(PG8_SB(1, 0), b3, voffB); PG8_STAGE(PG8_SB(1, 1), b3 + hstep, voffB); PG8_STAGE(PG8_SA(1, 0), a3, voffA);
;             PG8_WAIT_V(8); PG8_WAIT_L(0); PG8_BAR; PG8_MMA(1, 0, At, B0); PG8_MMA(1, 1, At, B1); PG8_BAR; PG8_SCHED;
.LBB0_138:
	ds_read_b128 v[148:151], v142
	ds_read_b128 v[152:155], v142 offset:1024
	ds_read_b128 v[156:159], v142 offset:2048
	ds_read_b128 v[160:163], v142 offset:3072
	ds_read_b128 v[164:167], v143
	ds_read_b128 v[168:171], v143 offset:1024
	ds_read_b128 v[172:175], v143 offset:2048
	ds_read_b128 v[176:179], v143 offset:3072
	s_add_u32 s62, s66, 0x100
	s_addc_u32 s63, s67, 0
	s_cmp_eq_u32 s96, 60
	s_cselect_b32 s86, s92, s62
	s_cselect_b32 s87, s13, s63
	s_cselect_b32 s84, s93, s94
	s_cselect_b32 s85, s11, s95
	s_add_u32 s76, s86, 0x80
	s_addc_u32 s77, s87, 0
	ds_read_b128 v[180:183], v144
	ds_read_b128 v[184:187], v144 offset:1024
	ds_read_b128 v[188:191], v144 offset:2048
	ds_read_b128 v[192:195], v144 offset:3072
	ds_read_b128 v[196:199], v144 offset:4096
	ds_read_b128 v[200:203], v144 offset:5120
	ds_read_b128 v[204:207], v144 offset:6144
	ds_read_b128 v[208:211], v144 offset:7168
	s_add_u32 s66, s66, 0x100080
	s_addc_u32 s67, s67, 0
	s_mov_b32 m0, s83
	s_nop 0
	global_load_lds_dwordx4 v136, s[66:67]
	s_nop 0
	s_mov_b32 m0, s88
	s_nop 0
	global_load_lds_dwordx4 v138, s[66:67]
	s_waitcnt vmcnt(8)
	s_waitcnt lgkmcnt(0)
	s_barrier
	s_setprio 1
	s_waitcnt lgkmcnt(7)
	v_mfma_f32_16x16x32_bf16 v[126:129], v[148:151], v[180:183], v[126:129]
	v_mfma_f32_16x16x32_bf16 v[126:129], v[152:155], v[184:187], v[126:129]
	s_waitcnt lgkmcnt(5)
	v_mfma_f32_16x16x32_bf16 v[122:125], v[160:163], v[184:187], v[122:125]
	v_mfma_f32_16x16x32_bf16 v[122:125], v[156:159], v[180:183], v[122:125]
	s_waitcnt lgkmcnt(3)
	v_mfma_f32_16x16x32_bf16 v[106:109], v[156:159], v[188:191], v[106:109]
	v_mfma_f32_16x16x32_bf16 v[106:109], v[160:163], v[192:195], v[106:109]
	s_waitcnt lgkmcnt(1)
	v_mfma_f32_16x16x32_bf16 v[110:113], v[152:155], v[192:195], v[110:113]
	v_mfma_f32_16x16x32_bf16 v[110:113], v[148:151], v[188:191], v[110:113]
	v_mfma_f32_16x16x32_bf16 v[94:97], v[148:151], v[196:199], v[94:97]
	v_mfma_f32_16x16x32_bf16 v[94:97], v[152:155], v[200:203], v[94:97]
	v_mfma_f32_16x16x32_bf16 v[90:93], v[160:163], v[200:203], v[90:93]
	v_mfma_f32_16x16x32_bf16 v[90:93], v[156:159], v[196:199], v[90:93]
	v_mfma_f32_16x16x32_bf16 v[74:77], v[156:159], v[204:207], v[74:77]
	v_mfma_f32_16x16x32_bf16 v[74:77], v[160:163], v[208:211], v[74:77]
	s_waitcnt lgkmcnt(0)
	v_mfma_f32_16x16x32_bf16 v[78:81], v[152:155], v[208:211], v[78:81]
	v_mfma_f32_16x16x32_bf16 v[78:81], v[148:151], v[204:207], v[78:81]
	s_setprio 0
	s_setprio 1
	v_mfma_f32_16x16x32_bf16 v[118:121], v[164:167], v[180:183], v[118:121]
	v_mfma_f32_16x16x32_bf16 v[118:121], v[168:171], v[184:187], v[118:121]
	v_mfma_f32_16x16x32_bf16 v[114:117], v[176:179], v[184:187], v[114:117]
	v_mfma_f32_16x16x32_bf16 v[114:117], v[172:175], v[180:183], v[114:117]
	v_mfma_f32_16x16x32_bf16 v[98:101], v[172:175], v[188:191], v[98:101]
	v_mfma_f32_16x16x32_bf16 v[98:101], v[176:179], v[192:195], v[98:101]
	v_mfma_f32_16x16x32_bf16 v[102:105], v[168:171], v[192:195], v[102:105]
	v_mfma_f32_16x16x32_bf16 v[102:105], v[164:167], v[188:191], v[102:105]
	v_mfma_f32_16x16x32_bf16 v[86:89], v[164:167], v[196:199], v[86:89]
	v_mfma_f32_16x16x32_bf16 v[86:89], v[168:171], v[200:203], v[86:89]
	v_mfma_f32_16x16x32_bf16 v[82:85], v[176:179], v[200:203], v[82:85]
	v_mfma_f32_16x16x32_bf16 v[82:85], v[172:175], v[196:199], v[82:85]
	v_mfma_f32_16x16x32_bf16 v[66:69], v[172:175], v[204:207], v[66:69]
	v_mfma_f32_16x16x32_bf16 v[66:69], v[176:179], v[208:211], v[66:69]
	v_mfma_f32_16x16x32_bf16 v[70:73], v[168:171], v[208:211], v[70:73]
	s_setprio 2
	s_barrier
	v_mfma_f32_16x16x32_bf16 v[70:73], v[164:167], v[204:207], v[70:73]
	s_setprio 0
	ds_read_b128 v[180:183], v144 offset:16384
	ds_read_b128 v[184:187], v144 offset:17408
	ds_read_b128 v[188:191], v144 offset:18432
	ds_read_b128 v[192:195], v144 offset:19456
	ds_read_b128 v[196:199], v144 offset:20480
	ds_read_b128 v[200:203], v144 offset:21504
	ds_read_b128 v[252:255], v144 offset:22528
	ds_read_b128 v[208:211], v144 offset:23552
	s_mov_b32 m0, s55
	s_nop 0
	global_load_lds_dwordx4 v137, s[84:85]
	s_add_u32 s66, s84, 0x100000
	s_mov_b32 m0, s56
	s_nop 0
	global_load_lds_dwordx4 v139, s[84:85]
	s_addc_u32 s67, s85, 0
	s_mov_b32 m0, s57
	s_nop 0
	global_load_lds_dwordx4 v137, s[66:67]
	s_nop 0
	s_mov_b32 m0, s58
	s_nop 0
	global_load_lds_dwordx4 v139, s[66:67]
	s_nop 0
	s_mov_b32 m0, s54
	s_nop 0
	global_load_lds_dwordx4 v136, s[86:87]
	s_nop 0
	s_mov_b32 m0, s59
	s_nop 0
	global_load_lds_dwordx4 v138, s[86:87]
	s_waitcnt vmcnt(8)
	s_waitcnt lgkmcnt(0)
	s_barrier
; #define PG8_STAGE(bufoff, gbase, voff) do { _Pragma("unroll") for (int _i = 0; _i < 2; ++_i) \
;         asm volatile("s_mov_b32 m0, %2\n\ts_nop 0\n\tglobal_load_lds_dwordx4 %0, %1" :: "v"((voff)[_i]), "s"((const char*)(gbase)), "s"(ldsbase + (unsigned)(bufoff) + ldsw + (unsigned)_i * 8192u) : "memory", "m0"); } while (0)
; #define PG8_LDA(dst, b, h) do { _Pragma("unroll") for (int m = 0; m < 4; ++m) _Pragma("unroll") for (int k = 0; k < 2; ++k) dst[m][k] = *(const PG8_LAS bf16x8*)(lds + PG8_SA(b, h) + aoff + m * 2048 + k * 1024); } while (0)
; #define PG8_LDB(dst, b, h) do { _Pragma("unroll") for (int n = 0; n < 2; ++n) _Pragma("unroll") for (int k = 0; k < 2; ++k) dst[n][k] = *(const PG8_LAS bf16x8*)(lds + PG8_SB(b, h) + boff + n * 2048 + k * 1024); } while (0)
; #define PG8_MMA(ai, bj, At, Bt) do { __builtin_amdgcn_s_setprio(1); _Pragma("unroll") for (int m = 0; m < 4; ++m) _Pragma("unroll") for (int n = 0; n < 2; ++n) _Pragma("unroll") for (int k = 0; k < 2; ++k) \
;         acc[ai][bj][m][n] = __builtin_amdgcn_mfma_f32_16x16x32_bf16(Bt[n][k], At[m][k], acc[ai][bj][m][n], 0, 0, 0); __builtin_amdgcn_s_setprio(0); } while (0)
; template <class Epi, class Sched, bool ALIGN_EPI = false, bool SP2 = false>
; __device__ __forceinline__ void gemm_phase(PG8_LAS unsigned char* lds, const Gemm g, const Sched& S, const Epi& E) {
;     ...
;             PG8_LDB(B0, 0, 0); PG8_LDB(B1, 0, 1); PG8_SCHED; PG8_LDA(At, 0, 0); PG8_STAGE(PG8_SA(1, 1), a1 + hstep, voffA);
;             PG8_WAIT_V(8); PG8_WAIT_L(0); PG8_BAR; PG8_MMA(0, 0, At, B0); PG8_MMA(0, 1, At, B1); PG8_BAR; PG8_SCHED;
;             PG8_LDA(At, 0, 1); PG8_STAGE(PG8_SB(0, 0), b2, voffB); PG8_STAGE(PG8_SB(0, 1), b2 + hstep, voffB); PG8_STAGE(PG8_SA(0, 0), a2, voffA);
;             PG8_WAIT_V(8); PG8_WAIT_L(0); PG8_BAR; PG8_MMA(1, 0, At, B0); PG8_MMA(1, 1, At, B1); PG8_BAR; PG8_SCHED;
;             PG8_LDB(B0, 1, 0); PG8_LDB(B1, 1, 1); PG8_SCHED; PG8_LDA(At, 1, 0); PG8_STAGE(PG8_SA(0, 1), a2 + hstep, voffA);
;             PG8_WAIT_V(8); PG8_WAIT_L(0); PG8_BAR; PG8_MMA(0, 0, At, B0); PG8_MMA(0, 1, At, B1); PG8_BAR; PG8_SCHED;
;             PG8_LDA(At, 1, 1); PG8_STAGE(PG8_SB(1, 0), b3, voffB); PG8_STAGE(PG8_SB(1, 1), b3 + hstep, voffB); PG8_STAGE(PG8_SA(1, 0), a3, voffA);
;             PG8_WAIT_V(8); PG8_WAIT_L(0); PG8_BAR; PG8_MMA(1, 0, At, B0); PG8_MMA(1, 1, At, B1); PG8_BAR; PG8_SCHED;
	s_setprio 1
	s_waitcnt lgkmcnt(7)
	v_mfma_f32_16x16x32_bf16 v[62:65], v[148:151], v[180:183], v[62:65]
	v_mfma_f32_16x16x32_bf16 v[62:65], v[152:155], v[184:187], v[62:65]
	s_waitcnt lgkmcnt(5)
	v_mfma_f32_16x16x32_bf16 v[58:61], v[160:163], v[184:187], v[58:61]
	v_mfma_f32_16x16x32_bf16 v[58:61], v[156:159], v[180:183], v[58:61]
	s_waitcnt lgkmcnt(3)
	v_mfma_f32_16x16x32_bf16 v[42:45], v[156:159], v[188:191], v[42:45]
	v_mfma_f32_16x16x32_bf16 v[42:45], v[160:163], v[192:195], v[42:45]
	s_waitcnt lgkmcnt(1)
	v_mfma_f32_16x16x32_bf16 v[46:49], v[152:155], v[192:195], v[46:49]
	v_mfma_f32_16x16x32_bf16 v[46:49], v[148:151], v[188:191], v[46:49]
	v_mfma_f32_16x16x32_bf16 v[30:33], v[148:151], v[196:199], v[30:33]
	v_mfma_f32_16x16x32_bf16 v[30:33], v[152:155], v[200:203], v[30:33]
	v_mfma_f32_16x16x32_bf16 v[26:29], v[160:163], v[200:203], v[26:29]
	v_mfma_f32_16x16x32_bf16 v[26:29], v[156:159], v[196:199], v[26:29]
	v_mfma_f32_16x16x32_bf16 v[10:13], v[156:159], v[252:255], v[10:13]
	v_mfma_f32_16x16x32_bf16 v[10:13], v[160:163], v[208:211], v[10:13]
	s_waitcnt lgkmcnt(0)
	v_mfma_f32_16x16x32_bf16 v[14:17], v[152:155], v[208:211], v[14:17]
	v_mfma_f32_16x16x32_bf16 v[14:17], v[148:151], v[252:255], v[14:17]
	s_setprio 0
	s_setprio 1
	v_mfma_f32_16x16x32_bf16 v[54:57], v[164:167], v[180:183], v[54:57]
	v_mfma_f32_16x16x32_bf16 v[54:57], v[168:171], v[184:187], v[54:57]
	v_mfma_f32_16x16x32_bf16 v[50:53], v[176:179], v[184:187], v[50:53]
	v_mfma_f32_16x16x32_bf16 v[50:53], v[172:175], v[180:183], v[50:53]
	v_mfma_f32_16x16x32_bf16 v[34:37], v[172:175], v[188:191], v[34:37]
	v_mfma_f32_16x16x32_bf16 v[34:37], v[176:179], v[192:195], v[34:37]
	v_mfma_f32_16x16x32_bf16 v[38:41], v[168:171], v[192:195], v[38:41]
	v_mfma_f32_16x16x32_bf16 v[38:41], v[164:167], v[188:191], v[38:41]
	v_mfma_f32_16x16x32_bf16 v[22:25], v[164:167], v[196:199], v[22:25]
	v_mfma_f32_16x16x32_bf16 v[22:25], v[168:171], v[200:203], v[22:25]
	v_mfma_f32_16x16x32_bf16 v[18:21], v[176:179], v[200:203], v[18:21]
	v_mfma_f32_16x16x32_bf16 v[18:21], v[172:175], v[196:199], v[18:21]
	v_mfma_f32_16x16x32_bf16 v[2:5], v[172:175], v[252:255], v[2:5]
	v_mfma_f32_16x16x32_bf16 v[2:5], v[176:179], v[208:211], v[2:5]
	v_mfma_f32_16x16x32_bf16 v[6:9], v[168:171], v[208:211], v[6:9]
	s_setprio 2
	s_barrier
	v_mfma_f32_16x16x32_bf16 v[6:9], v[164:167], v[252:255], v[6:9]
	s_setprio 0
	ds_read_b128 v[148:151], v145
	ds_read_b128 v[152:155], v145 offset:1024
	ds_read_b128 v[156:159], v145 offset:2048
	ds_read_b128 v[160:163], v145 offset:3072
	ds_read_b128 v[248:251], v146
	ds_read_b128 v[168:171], v146 offset:1024
	ds_read_b128 v[172:175], v146 offset:2048
	ds_read_b128 v[176:179], v146 offset:3072
	ds_read_b128 v[180:183], v144 offset:32768
	ds_read_b128 v[184:187], v144 offset:33792
	ds_read_b128 v[188:191], v144 offset:34816
	ds_read_b128 v[192:195], v144 offset:35840
	ds_read_b128 v[196:199], v144 offset:36864
	ds_read_b128 v[200:203], v144 offset:37888
	ds_read_b128 v[204:207], v144 offset:38912
	ds_read_b128 v[208:211], v144 offset:39936
	s_add_u32 s66, s86, 0x100000
	s_addc_u32 s67, s87, 0
	s_mov_b32 m0, s60
	s_nop 0
	global_load_lds_dwordx4 v136, s[66:67]
	s_nop 0
	s_mov_b32 m0, s61
	s_nop 0
	global_load_lds_dwordx4 v138, s[66:67]
	s_waitcnt vmcnt(8)
	s_waitcnt lgkmcnt(0)
	s_barrier
	s_setprio 1
	s_waitcnt lgkmcnt(7)
	v_mfma_f32_16x16x32_bf16 v[126:129], v[148:151], v[180:183], v[126:129]
	v_mfma_f32_16x16x32_bf16 v[126:129], v[152:155], v[184:187], v[126:129]
	s_waitcnt lgkmcnt(5)
	v_mfma_f32_16x16x32_bf16 v[122:125], v[160:163], v[184:187], v[122:125]
	v_mfma_f32_16x16x32_bf16 v[122:125], v[156:159], v[180:183], v[122:125]
	s_waitcnt lgkmcnt(3)
	v_mfma_f32_16x16x32_bf16 v[106:109], v[156:159], v[188:191], v[106:109]
	v_mfma_f32_16x16x32_bf16 v[106:109], v[160:163], v[192:195], v[106:109]
	s_waitcnt lgkmcnt(1)
	v_mfma_f32_16x16x32_bf16 v[110:113], v[152:155], v[192:195], v[110:113]
	v_mfma_f32_16x16x32_bf16 v[110:113], v[148:151], v[188:191], v[110:113]
	v_mfma_f32_16x16x32_bf16 v[94:97], v[148:151], v[196:199], v[94:97]
	v_mfma_f32_16x16x32_bf16 v[94:97], v[152:155], v[200:203], v[94:97]
	v_mfma_f32_16x16x32_bf16 v[90:93], v[160:163], v[200:203], v[90:93]
	v_mfma_f32_16x16x32_bf16 v[90:93], v[156:159], v[196:199], v[90:93]
	v_mfma_f32_16x16x32_bf16 v[74:77], v[156:159], v[204:207], v[74:77]
	v_mfma_f32_16x16x32_bf16 v[74:77], v[160:163], v[208:211], v[74:77]
	s_waitcnt lgkmcnt(0)
	v_mfma_f32_16x16x32_bf16 v[78:81], v[152:155], v[208:211], v[78:81]
	v_mfma_f32_16x16x32_bf16 v[78:81], v[148:151], v[204:207], v[78:81]
	s_setprio 0
	s_setprio 1
	v_mfma_f32_16x16x32_bf16 v[118:121], v[248:251], v[180:183], v[118:121]
	v_mfma_f32_16x16x32_bf16 v[118:121], v[168:171], v[184:187], v[118:121]
	v_mfma_f32_16x16x32_bf16 v[114:117], v[176:179], v[184:187], v[114:117]
	v_mfma_f32_16x16x32_bf16 v[114:117], v[172:175], v[180:183], v[114:117]
	v_mfma_f32_16x16x32_bf16 v[98:101], v[172:175], v[188:191], v[98:101]
	v_mfma_f32_16x16x32_bf16 v[98:101], v[176:179], v[192:195], v[98:101]
	v_mfma_f32_16x16x32_bf16 v[102:105], v[168:171], v[192:195], v[102:105]
	v_mfma_f32_16x16x32_bf16 v[102:105], v[248:251], v[188:191], v[102:105]
	v_mfma_f32_16x16x32_bf16 v[86:89], v[248:251], v[196:199], v[86:89]
	v_mfma_f32_16x16x32_bf16 v[86:89], v[168:171], v[200:203], v[86:89]
	v_mfma_f32_16x16x32_bf16 v[82:85], v[176:179], v[200:203], v[82:85]
	v_mfma_f32_16x16x32_bf16 v[82:85], v[172:175], v[196:199], v[82:85]
	v_mfma_f32_16x16x32_bf16 v[66:69], v[172:175], v[204:207], v[66:69]
	v_mfma_f32_16x16x32_bf16 v[66:69], v[176:179], v[208:211], v[66:69]
	v_mfma_f32_16x16x32_bf16 v[70:73], v[168:171], v[208:211], v[70:73]
	s_setprio 2
	s_barrier
; __device__ __forceinline__ unsigned cvt_pk_bf16(float lo, float hi) { unsigned r; asm volatile("v_cvt_pk_bf16_f32 %0, %1, %2" : "=v"(r) : "v"(lo), "v"(hi)); return r; }
; __device__ __forceinline__ float silu_f(float x) { return x * sigmoid_f(x); }
;     __device__ __forceinline__ void operator()(const f32x4 (&acc)[2][2][4][2], const Unit& u, int wr, int wc, int fr, int fq) const {
;         const int row0 = u.pm * BM + wr * 64 + fr, col0 = u.pn * HALF + wc * 32 + 8 * fq;
; #pragma unroll
;         for (int ai = 0; ai < 2; ++ai)
; #pragma unroll
;             for (int m = 0; m < 4; ++m) { bf16_t* rowp = O + (size_t)(row0 + ai * HALF + m * 16) * ldc + col0;
;                 const f32x4 g0 = acc[ai][0][m][0], g1 = acc[ai][0][m][1], u0 = acc[ai][1][m][0], u1 = acc[ai][1][m][1];
;                 f32x4 v0, v1;
; #pragma unroll
;                 for (int j = 0; j < 4; ++j) { v0[j] = silu_f(g0[j]) * u0[j]; v1[j] = silu_f(g1[j]) * u1[j]; }
;                 u32x4 w; w.x = cvt_pk_bf16(v0[0], v0[1]); w.y = cvt_pk_bf16(v0[2], v0[3]); w.z = cvt_pk_bf16(v1[0], v1[1]); w.w = cvt_pk_bf16(v1[2], v1[3]);
;                 *(u32x4*)rowp = w; }
; template <class Epi, class Sched, bool ALIGN_EPI = false, bool SP2 = false>
; __device__ __forceinline__ void gemm_phase(PG8_LAS unsigned char* lds, const Gemm g, const Sched& S, const Epi& E) {
;     ...
;             PG8_LDB(B0, 0, 0); PG8_LDB(B1, 0, 1); PG8_SCHED; PG8_LDA(At, 0, 0); PG8_STAGE(PG8_SA(1, 1), a1 + hstep, voffA);
;             PG8_WAIT_V(8); PG8_WAIT_L(0); PG8_BAR; PG8_MMA(0, 0, At, B0); PG8_MMA(0, 1, At, B1); PG8_BAR; PG8_SCHED;
;             PG8_LDA(At, 0, 1); PG8_STAGE(PG8_SB(0, 0), b2, voffB); PG8_STAGE(PG8_SB(0, 1), b2 + hstep, voffB); PG8_STAGE(PG8_SA(0, 0), a2, voffA);
;             PG8_WAIT_V(8); PG8_WAIT_L(0); PG8_BAR; PG8_MMA(1, 0, At, B0); PG8_MMA(1, 1, At, B1); PG8_BAR; PG8_SCHED;
;             PG8_LDB(B0, 1, 0); PG8_LDB(B1, 1, 1); PG8_SCHED; PG8_LDA(At, 1, 0); PG8_STAGE(PG8_SA(0, 1), a2 + hstep, voffA);
;             PG8_WAIT_V(8); PG8_WAIT_L(0); PG8_BAR; PG8_MMA(0, 0, At, B0); PG8_MMA(0, 1, At, B1); PG8_BAR; PG8_SCHED;
;             PG8_LDA(At, 1, 1); PG8_STAGE(PG8_SB(1, 0), b3, voffB); PG8_STAGE(PG8_SB(1, 1), b3 + hstep, voffB); PG8_STAGE(PG8_SA(1, 0), a3, voffA);
;             PG8_WAIT_V(8); PG8_WAIT_L(0); PG8_BAR; PG8_MMA(1, 0, At, B0); PG8_MMA(1, 1, At, B1); PG8_BAR; PG8_SCHED;
	v_mfma_f32_16x16x32_bf16 v[70:73], v[248:251], v[204:207], v[70:73]
	s_setprio 0
	ds_read_b128 v[180:183], v144 offset:49152
	ds_read_b128 v[184:187], v144 offset:50176
	ds_read_b128 v[188:191], v144 offset:51200
	ds_read_b128 v[192:195], v144 offset:52224
	ds_read_b128 v[196:199], v144 offset:53248
	ds_read_b128 v[200:203], v144 offset:54272
	ds_read_b128 v[252:255], v144 offset:55296
	ds_read_b128 v[208:211], v144 offset:56320
	s_add_u32 s66, s84, 0x80
	s_addc_u32 s67, s85, 0
	s_mov_b32 m0, s64
	s_nop 0
	global_load_lds_dwordx4 v137, s[66:67]
	s_nop 0
	s_mov_b32 m0, s65
	s_nop 0
	global_load_lds_dwordx4 v139, s[66:67]
	s_add_u32 s66, s84, 0x100080
	s_addc_u32 s67, s85, 0
	s_mov_b32 m0, s70
	s_nop 0
	global_load_lds_dwordx4 v137, s[66:67]
	s_nop 0
	s_mov_b32 m0, s71
	s_nop 0
	global_load_lds_dwordx4 v139, s[66:67]
	s_nop 0
	s_mov_b32 m0, s68
	s_nop 0
	global_load_lds_dwordx4 v136, s[76:77]
	s_nop 0
	s_mov_b32 m0, s69
	s_nop 0
	global_load_lds_dwordx4 v138, s[76:77]
	s_waitcnt vmcnt(8)
	s_waitcnt lgkmcnt(0)
	s_barrier
	s_setprio 1
	s_waitcnt lgkmcnt(7)
	v_mfma_f32_16x16x32_bf16 v[62:65], v[148:151], v[180:183], v[62:65]
	v_mfma_f32_16x16x32_bf16 v[62:65], v[152:155], v[184:187], v[62:65]
	s_waitcnt lgkmcnt(5)
	v_mfma_f32_16x16x32_bf16 v[58:61], v[160:163], v[184:187], v[58:61]
	v_mfma_f32_16x16x32_bf16 v[58:61], v[156:159], v[180:183], v[58:61]
	s_waitcnt lgkmcnt(3)
	v_mfma_f32_16x16x32_bf16 v[42:45], v[156:159], v[188:191], v[42:45]
	v_mfma_f32_16x16x32_bf16 v[42:45], v[160:163], v[192:195], v[42:45]
	s_waitcnt lgkmcnt(1)
	v_mfma_f32_16x16x32_bf16 v[46:49], v[152:155], v[192:195], v[46:49]
	v_mfma_f32_16x16x32_bf16 v[46:49], v[148:151], v[188:191], v[46:49]
	v_mfma_f32_16x16x32_bf16 v[30:33], v[148:151], v[196:199], v[30:33]
	v_mfma_f32_16x16x32_bf16 v[30:33], v[152:155], v[200:203], v[30:33]
	v_mfma_f32_16x16x32_bf16 v[26:29], v[160:163], v[200:203], v[26:29]
	v_mfma_f32_16x16x32_bf16 v[26:29], v[156:159], v[196:199], v[26:29]
	v_mfma_f32_16x16x32_bf16 v[10:13], v[156:159], v[252:255], v[10:13]
	v_mfma_f32_16x16x32_bf16 v[10:13], v[160:163], v[208:211], v[10:13]
	s_waitcnt lgkmcnt(0)
	v_mfma_f32_16x16x32_bf16 v[14:17], v[152:155], v[208:211], v[14:17]
	v_mfma_f32_16x16x32_bf16 v[14:17], v[148:151], v[252:255], v[14:17]
	s_setprio 0
	s_setprio 1
	v_mfma_f32_16x16x32_bf16 v[54:57], v[248:251], v[180:183], v[54:57]
	v_mfma_f32_16x16x32_bf16 v[54:57], v[168:171], v[184:187], v[54:57]
	v_mfma_f32_16x16x32_bf16 v[50:53], v[176:179], v[184:187], v[50:53]
	v_mfma_f32_16x16x32_bf16 v[50:53], v[172:175], v[180:183], v[50:53]
	v_mfma_f32_16x16x32_bf16 v[34:37], v[172:175], v[188:191], v[34:37]
	v_mfma_f32_16x16x32_bf16 v[34:37], v[176:179], v[192:195], v[34:37]
	v_mfma_f32_16x16x32_bf16 v[38:41], v[168:171], v[192:195], v[38:41]
	v_mfma_f32_16x16x32_bf16 v[38:41], v[248:251], v[188:191], v[38:41]
	v_mfma_f32_16x16x32_bf16 v[22:25], v[248:251], v[196:199], v[22:25]
	v_mfma_f32_16x16x32_bf16 v[22:25], v[168:171], v[200:203], v[22:25]
	v_mfma_f32_16x16x32_bf16 v[18:21], v[176:179], v[200:203], v[18:21]
	v_mfma_f32_16x16x32_bf16 v[18:21], v[172:175], v[196:199], v[18:21]
	v_mfma_f32_16x16x32_bf16 v[2:5], v[172:175], v[252:255], v[2:5]
	v_mfma_f32_16x16x32_bf16 v[2:5], v[176:179], v[208:211], v[2:5]
	v_mfma_f32_16x16x32_bf16 v[6:9], v[168:171], v[208:211], v[6:9]
	s_setprio 2
	s_barrier
	v_mfma_f32_16x16x32_bf16 v[6:9], v[248:251], v[252:255], v[6:9]
	s_setprio 0
	s_add_i32 s96, s96, 2
	s_add_u32 s94, s94, 0x100
	s_addc_u32 s95, s95, 0
	s_cmp_gt_u32 s96, 61
	s_mov_b64 s[66:67], s[62:63]
	s_cbranch_scc0 .LBB0_138
	v_mul_f32_e32 v134, 0xbfb8aa3b, v126
	v_exp_f32_e32 v150, v134
	v_mul_f32_e32 v134, 0xbfb8aa3b, v122
	v_exp_f32_e32 v151, v134
	v_lshl_or_b32 v148, s91, 7, v141
	v_add_f32_e32 v150, 1.0, v150
	v_rcp_f32_e32 v152, v150
	v_add_f32_e32 v150, 1.0, v151
	v_rcp_f32_e32 v153, v150
	v_lshl_add_u32 v147, s82, 8, v140
	v_mul_f32_e32 v126, v126, v152
	v_mul_f32_e32 v118, v126, v118
	v_mul_f32_e32 v126, 0xbfb8aa3b, v127
	v_exp_f32_e32 v126, v126
	v_mul_f32_e32 v152, 0xbfb8aa3b, v123
	v_exp_f32_e32 v152, v152
	v_mul_f32_e32 v122, v122, v153
	v_mul_f32_e32 v122, v122, v114
	v_add_f32_e32 v114, 1.0, v126
	v_rcp_f32_e32 v114, v114
	v_add_f32_e32 v126, 1.0, v152
	v_mul_f32_e32 v152, 0xbfb8aa3b, v128
	v_rcp_f32_e32 v126, v126
	v_exp_f32_e32 v152, v152
	v_mul_f32_e32 v114, v127, v114
	v_mul_f32_e32 v119, v114, v119
	v_mul_f32_e32 v114, v123, v126
	v_add_f32_e32 v123, 1.0, v152
	v_rcp_f32_e32 v123, v123
	v_mul_f32_e32 v126, 0xbfb8aa3b, v124
	v_exp_f32_e32 v126, v126
	v_mul_f32_e32 v127, v114, v115
	v_mul_f32_e32 v114, v128, v123
	v_mul_f32_e32 v115, 0xbfb8aa3b, v129
	v_mul_f32_e32 v123, v114, v120
	v_exp_f32_e32 v115, v115
	v_mul_f32_e32 v120, 0xbfb8aa3b, v125
	v_exp_f32_e32 v120, v120
	v_add_f32_e32 v114, 1.0, v126
	v_rcp_f32_e32 v114, v114
	v_add_f32_e32 v115, 1.0, v115
	v_rcp_f32_e32 v115, v115
	v_add_f32_e32 v120, 1.0, v120
	v_rcp_f32_e32 v120, v120
	v_mul_f32_e32 v114, v124, v114
	v_mul_f32_e32 v124, v114, v116
	v_mul_f32_e32 v114, v129, v115
	v_ashrrev_i32_e32 v149, 31, v148
	v_mov_b64_e32 v[134:135], s[72:73]
	v_mul_f32_e32 v126, v114, v121
	v_mul_f32_e32 v114, v125, v120
	v_mad_i64_i32 v[150:151], s[62:63], v147, s90, v[134:135]
	v_mul_f32_e32 v125, v114, v117
	v_lshlrev_b64 v[114:115], 1, v[148:149]
	v_lshl_add_u64 v[120:121], v[150:151], 0, v[114:115]
	v_cvt_pk_bf16_f32 v116, v118, v119
	v_cvt_pk_bf16_f32 v117, v123, v126
	v_cvt_pk_bf16_f32 v118, v122, v127
	v_cvt_pk_bf16_f32 v119, v124, v125
	global_store_dwordx4 v[120:121], v[116:119], off
	s_and_b64 vcc, exec, s[0:1]
	s_mov_b32 s91, s10
	v_mul_f32_e32 v116, 0xbfb8aa3b, v110
	v_exp_f32_e32 v116, v116
; __device__ __forceinline__ unsigned cvt_pk_bf16(float lo, float hi) { unsigned r; asm volatile("v_cvt_pk_bf16_f32 %0, %1, %2" : "=v"(r) : "v"(lo), "v"(hi)); return r; }
; __device__ __forceinline__ float silu_f(float x) { return x * sigmoid_f(x); }
;     __device__ __forceinline__ void operator()(const f32x4 (&acc)[2][2][4][2], const Unit& u, int wr, int wc, int fr, int fq) const {
;     ...
;             for (int m = 0; m < 4; ++m) { bf16_t* rowp = O + (size_t)(row0 + ai * HALF + m * 16) * ldc + col0;
;                 const f32x4 g0 = acc[ai][0][m][0], g1 = acc[ai][0][m][1], u0 = acc[ai][1][m][0], u1 = acc[ai][1][m][1];
;                 f32x4 v0, v1;
; #pragma unroll
;                 for (int j = 0; j < 4; ++j) { v0[j] = silu_f(g0[j]) * u0[j]; v1[j] = silu_f(g1[j]) * u1[j]; }
;                 u32x4 w; w.x = cvt_pk_bf16(v0[0], v0[1]); w.y = cvt_pk_bf16(v0[2], v0[3]); w.z = cvt_pk_bf16(v1[0], v1[1]); w.w = cvt_pk_bf16(v1[2], v1[3]);
;                 *(u32x4*)rowp = w; }
	v_mul_f32_e32 v117, 0xbfb8aa3b, v106
	v_exp_f32_e32 v117, v117
	v_or_b32_e32 v118, 16, v147
	v_add_f32_e32 v116, 1.0, v116
	v_rcp_f32_e32 v119, v116
	v_add_f32_e32 v116, 1.0, v117
	v_rcp_f32_e32 v120, v116
	v_mad_i64_i32 v[116:117], s[62:63], v118, s90, v[134:135]
	v_mul_f32_e32 v110, v110, v119
	v_mul_f32_e32 v110, v110, v102
	v_mul_f32_e32 v102, v106, v120
	v_mul_f32_e32 v106, 0xbfb8aa3b, v111
	v_exp_f32_e32 v106, v106
	v_mul_f32_e32 v118, 0xbfb8aa3b, v107
	v_mul_f32_e32 v119, v102, v98
	v_exp_f32_e32 v118, v118
	v_add_f32_e32 v98, 1.0, v106
	v_rcp_f32_e32 v98, v98
	v_mul_f32_e32 v106, 0xbfb8aa3b, v112
	v_exp_f32_e32 v106, v106
	v_add_f32_e32 v102, 1.0, v118
	v_mul_f32_e32 v98, v111, v98
	v_rcp_f32_e32 v102, v102
	v_mul_f32_e32 v98, v98, v103
	v_add_f32_e32 v103, 1.0, v106
	v_rcp_f32_e32 v103, v103
	v_mul_f32_e32 v102, v107, v102
	v_mul_f32_e32 v106, 0xbfb8aa3b, v108
	v_mul_f32_e32 v107, v102, v99
	v_mul_f32_e32 v99, v112, v103
	v_exp_f32_e32 v106, v106
	v_mul_f32_e32 v99, v99, v104
	v_mul_f32_e32 v103, 0xbfb8aa3b, v113
	v_mul_f32_e32 v104, 0xbfb8aa3b, v109
	v_exp_f32_e32 v103, v103
	v_exp_f32_e32 v104, v104
	v_add_f32_e32 v102, 1.0, v106
	v_rcp_f32_e32 v102, v102
	v_add_f32_e32 v103, 1.0, v103
	v_add_f32_e32 v104, 1.0, v104
	v_rcp_f32_e32 v103, v103
	v_rcp_f32_e32 v104, v104
	v_mul_f32_e32 v102, v108, v102
	v_mul_f32_e32 v106, v102, v100
	v_mul_f32_e32 v100, v113, v103
	v_mul_f32_e32 v102, v109, v104
	v_mul_f32_e32 v100, v100, v105
	v_mul_f32_e32 v101, v102, v101
	v_lshl_add_u64 v[102:103], v[116:117], 0, v[114:115]
	v_cvt_pk_bf16_f32 v98, v110, v98
	v_cvt_pk_bf16_f32 v99, v99, v100
	v_cvt_pk_bf16_f32 v100, v119, v107
	v_cvt_pk_bf16_f32 v101, v106, v101
	global_store_dwordx4 v[102:103], v[98:101], off
	s_mov_b32 s82, s12
	s_mov_b64 s[66:67], s[14:15]
	v_mul_f32_e32 v98, 0xbfb8aa3b, v94
	v_exp_f32_e32 v98, v98
	v_mul_f32_e32 v99, 0xbfb8aa3b, v90
	v_exp_f32_e32 v99, v99
	v_or_b32_e32 v100, 32, v147
	v_add_f32_e32 v98, 1.0, v98
	v_rcp_f32_e32 v101, v98
	v_add_f32_e32 v98, 1.0, v99
	v_rcp_f32_e32 v102, v98
	v_mad_i64_i32 v[98:99], s[62:63], v100, s90, v[134:135]
	v_mul_f32_e32 v94, v94, v101
	v_mul_f32_e32 v94, v94, v86
	v_mul_f32_e32 v86, v90, v102
	v_mul_f32_e32 v90, 0xbfb8aa3b, v95
	v_exp_f32_e32 v90, v90
	v_mul_f32_e32 v100, 0xbfb8aa3b, v91
	v_mul_f32_e32 v101, v86, v82
	v_exp_f32_e32 v100, v100
	v_add_f32_e32 v82, 1.0, v90
	v_rcp_f32_e32 v82, v82
	v_mul_f32_e32 v90, 0xbfb8aa3b, v96
	v_exp_f32_e32 v90, v90
	v_add_f32_e32 v86, 1.0, v100
	v_mul_f32_e32 v82, v95, v82
	v_rcp_f32_e32 v86, v86
	v_mul_f32_e32 v82, v82, v87
	v_add_f32_e32 v87, 1.0, v90
	v_rcp_f32_e32 v87, v87
	v_mul_f32_e32 v86, v91, v86
	v_mul_f32_e32 v90, 0xbfb8aa3b, v92
	v_mul_f32_e32 v91, v86, v83
	v_mul_f32_e32 v83, v96, v87
	v_exp_f32_e32 v90, v90
	v_mul_f32_e32 v83, v83, v88
	v_mul_f32_e32 v87, 0xbfb8aa3b, v97
	v_mul_f32_e32 v88, 0xbfb8aa3b, v93
	v_exp_f32_e32 v87, v87
	v_exp_f32_e32 v88, v88
	v_add_f32_e32 v86, 1.0, v90
	v_rcp_f32_e32 v86, v86
	v_add_f32_e32 v87, 1.0, v87
	v_add_f32_e32 v88, 1.0, v88
	v_rcp_f32_e32 v87, v87
	v_rcp_f32_e32 v88, v88
	v_mul_f32_e32 v86, v92, v86
	v_mul_f32_e32 v90, v86, v84
	v_mul_f32_e32 v84, v97, v87
	v_mul_f32_e32 v86, v93, v88
	v_mul_f32_e32 v84, v84, v89
	v_mul_f32_e32 v85, v86, v85
	v_lshl_add_u64 v[86:87], v[98:99], 0, v[114:115]
	v_cvt_pk_bf16_f32 v82, v94, v82
	v_cvt_pk_bf16_f32 v83, v83, v84
	v_cvt_pk_bf16_f32 v84, v101, v91
	v_cvt_pk_bf16_f32 v85, v90, v85
	global_store_dwordx4 v[86:87], v[82:85], off
	s_nop 1
	v_mul_f32_e32 v82, 0xbfb8aa3b, v78
	v_exp_f32_e32 v82, v82
	v_mul_f32_e32 v83, 0xbfb8aa3b, v74
	v_exp_f32_e32 v83, v83
	v_or_b32_e32 v84, 48, v147
	v_add_f32_e32 v82, 1.0, v82
	v_rcp_f32_e32 v85, v82
	v_add_f32_e32 v82, 1.0, v83
	v_rcp_f32_e32 v86, v82
	v_mad_i64_i32 v[82:83], s[62:63], v84, s90, v[134:135]
	v_mul_f32_e32 v78, v78, v85
	v_mul_f32_e32 v78, v78, v70
	v_mul_f32_e32 v70, v74, v86
	v_mul_f32_e32 v74, 0xbfb8aa3b, v79
	v_exp_f32_e32 v74, v74
	v_mul_f32_e32 v84, 0xbfb8aa3b, v75
	v_mul_f32_e32 v85, v70, v66
	v_exp_f32_e32 v84, v84
	v_add_f32_e32 v66, 1.0, v74
	v_rcp_f32_e32 v66, v66
	v_mul_f32_e32 v74, 0xbfb8aa3b, v80
	v_exp_f32_e32 v74, v74
	v_add_f32_e32 v70, 1.0, v84
	v_mul_f32_e32 v66, v79, v66
	v_rcp_f32_e32 v70, v70
	v_mul_f32_e32 v66, v66, v71
	v_add_f32_e32 v71, 1.0, v74
	v_rcp_f32_e32 v71, v71
	v_mul_f32_e32 v70, v75, v70
	v_mul_f32_e32 v74, 0xbfb8aa3b, v76
	v_mul_f32_e32 v75, v70, v67
	v_mul_f32_e32 v67, v80, v71
	v_exp_f32_e32 v74, v74
	v_mul_f32_e32 v67, v67, v72
	v_mul_f32_e32 v71, 0xbfb8aa3b, v81
	v_mul_f32_e32 v72, 0xbfb8aa3b, v77
	v_exp_f32_e32 v71, v71
	v_exp_f32_e32 v72, v72
	v_add_f32_e32 v70, 1.0, v74
	v_rcp_f32_e32 v70, v70
	v_add_f32_e32 v71, 1.0, v71
	v_add_f32_e32 v72, 1.0, v72
	v_rcp_f32_e32 v71, v71
	v_rcp_f32_e32 v72, v72
	v_mul_f32_e32 v70, v76, v70
	v_mul_f32_e32 v74, v70, v68
	v_mul_f32_e32 v68, v81, v71
	v_mul_f32_e32 v70, v77, v72
	v_mul_f32_e32 v68, v68, v73
	v_mul_f32_e32 v69, v70, v69
	v_lshl_add_u64 v[70:71], v[82:83], 0, v[114:115]
	v_cvt_pk_bf16_f32 v66, v78, v66
	v_cvt_pk_bf16_f32 v67, v67, v68
	v_cvt_pk_bf16_f32 v68, v85, v75
	v_cvt_pk_bf16_f32 v69, v74, v69
	global_store_dwordx4 v[70:71], v[66:69], off
	s_nop 1
	v_mul_f32_e32 v66, 0xbfb8aa3b, v62
	v_exp_f32_e32 v66, v66
	v_mul_f32_e32 v67, 0xbfb8aa3b, v58
	v_exp_f32_e32 v67, v67
	v_add_u32_e32 v68, 0x80, v147
	v_add_f32_e32 v66, 1.0, v66
	v_rcp_f32_e32 v69, v66
	v_add_f32_e32 v66, 1.0, v67
	v_rcp_f32_e32 v70, v66
	v_mad_i64_i32 v[66:67], s[62:63], v68, s90, v[134:135]
	v_mul_f32_e32 v62, v62, v69
	v_mul_f32_e32 v62, v62, v54
	v_mul_f32_e32 v54, v58, v70
	v_mul_f32_e32 v58, 0xbfb8aa3b, v63
	v_exp_f32_e32 v58, v58
; __device__ __forceinline__ unsigned cvt_pk_bf16(float lo, float hi) { unsigned r; asm volatile("v_cvt_pk_bf16_f32 %0, %1, %2" : "=v"(r) : "v"(lo), "v"(hi)); return r; }
; __device__ __forceinline__ float silu_f(float x) { return x * sigmoid_f(x); }
; #define PG8_WAIT_V(n) asm volatile("s_waitcnt vmcnt(" #n ")" ::: "memory")
; #define PG8_BAR __builtin_amdgcn_s_barrier()
;     __device__ __forceinline__ void operator()(const f32x4 (&acc)[2][2][4][2], const Unit& u, int wr, int wc, int fr, int fq) const {
;     ...
;             for (int m = 0; m < 4; ++m) { bf16_t* rowp = O + (size_t)(row0 + ai * HALF + m * 16) * ldc + col0;
;                 const f32x4 g0 = acc[ai][0][m][0], g1 = acc[ai][0][m][1], u0 = acc[ai][1][m][0], u1 = acc[ai][1][m][1];
;                 f32x4 v0, v1;
; #pragma unroll
;                 for (int j = 0; j < 4; ++j) { v0[j] = silu_f(g0[j]) * u0[j]; v1[j] = silu_f(g1[j]) * u1[j]; }
;                 u32x4 w; w.x = cvt_pk_bf16(v0[0], v0[1]); w.y = cvt_pk_bf16(v0[2], v0[3]); w.z = cvt_pk_bf16(v1[0], v1[1]); w.w = cvt_pk_bf16(v1[2], v1[3]);
;                 *(u32x4*)rowp = w; }
; template <class Epi, class Sched, bool ALIGN_EPI = false, bool SP2 = false>
; __device__ __forceinline__ void gemm_phase(PG8_LAS unsigned char* lds, const Gemm g, const Sched& S, const Epi& E) {
;     ...
;     PG8_WAIT_V(0);
;     if constexpr (!ALIGN_EPI) { if (wr == 0) PG8_BAR; }
;     PG8_BAR;
	v_mul_f32_e32 v68, 0xbfb8aa3b, v59
	v_mul_f32_e32 v69, v54, v50
	v_exp_f32_e32 v68, v68
	v_add_f32_e32 v50, 1.0, v58
	v_rcp_f32_e32 v50, v50
	v_mul_f32_e32 v58, 0xbfb8aa3b, v64
	v_exp_f32_e32 v58, v58
	v_add_f32_e32 v54, 1.0, v68
	v_mul_f32_e32 v50, v63, v50
	v_rcp_f32_e32 v54, v54
	v_mul_f32_e32 v50, v50, v55
	v_add_f32_e32 v55, 1.0, v58
	v_rcp_f32_e32 v55, v55
	v_mul_f32_e32 v54, v59, v54
	v_mul_f32_e32 v58, 0xbfb8aa3b, v60
	v_mul_f32_e32 v59, v54, v51
	v_mul_f32_e32 v51, v64, v55
	v_exp_f32_e32 v58, v58
	v_mul_f32_e32 v51, v51, v56
	v_mul_f32_e32 v55, 0xbfb8aa3b, v65
	v_mul_f32_e32 v56, 0xbfb8aa3b, v61
	v_exp_f32_e32 v55, v55
	v_exp_f32_e32 v56, v56
	v_add_f32_e32 v54, 1.0, v58
	v_rcp_f32_e32 v54, v54
	v_add_f32_e32 v55, 1.0, v55
	v_add_f32_e32 v56, 1.0, v56
	v_rcp_f32_e32 v55, v55
	v_rcp_f32_e32 v56, v56
	v_mul_f32_e32 v54, v60, v54
	v_mul_f32_e32 v58, v54, v52
	v_mul_f32_e32 v52, v65, v55
	v_mul_f32_e32 v54, v61, v56
	v_mul_f32_e32 v52, v52, v57
	v_mul_f32_e32 v53, v54, v53
	v_lshl_add_u64 v[54:55], v[66:67], 0, v[114:115]
	v_cvt_pk_bf16_f32 v50, v62, v50
	v_cvt_pk_bf16_f32 v51, v51, v52
	v_cvt_pk_bf16_f32 v52, v69, v59
	v_cvt_pk_bf16_f32 v53, v58, v53
	global_store_dwordx4 v[54:55], v[50:53], off
	s_nop 1
	v_mul_f32_e32 v50, 0xbfb8aa3b, v46
	v_exp_f32_e32 v50, v50
	v_mul_f32_e32 v51, 0xbfb8aa3b, v42
	v_exp_f32_e32 v51, v51
	v_add_u32_e32 v52, 0x90, v147
	v_add_f32_e32 v50, 1.0, v50
	v_rcp_f32_e32 v53, v50
	v_add_f32_e32 v50, 1.0, v51
	v_rcp_f32_e32 v54, v50
	v_mad_i64_i32 v[50:51], s[62:63], v52, s90, v[134:135]
	v_mul_f32_e32 v46, v46, v53
	v_mul_f32_e32 v46, v46, v38
	v_mul_f32_e32 v38, v42, v54
	v_mul_f32_e32 v42, 0xbfb8aa3b, v47
	v_exp_f32_e32 v42, v42
	v_mul_f32_e32 v52, 0xbfb8aa3b, v43
	v_mul_f32_e32 v53, v38, v34
	v_exp_f32_e32 v52, v52
	v_add_f32_e32 v34, 1.0, v42
	v_rcp_f32_e32 v34, v34
	v_mul_f32_e32 v42, 0xbfb8aa3b, v48
	v_exp_f32_e32 v42, v42
	v_add_f32_e32 v38, 1.0, v52
	v_mul_f32_e32 v34, v47, v34
	v_rcp_f32_e32 v38, v38
	v_mul_f32_e32 v34, v34, v39
	v_add_f32_e32 v39, 1.0, v42
	v_rcp_f32_e32 v39, v39
	v_mul_f32_e32 v38, v43, v38
	v_mul_f32_e32 v42, 0xbfb8aa3b, v44
	v_mul_f32_e32 v43, v38, v35
	v_mul_f32_e32 v35, v48, v39
	v_exp_f32_e32 v42, v42
	v_mul_f32_e32 v35, v35, v40
	v_mul_f32_e32 v39, 0xbfb8aa3b, v49
	v_mul_f32_e32 v40, 0xbfb8aa3b, v45
	v_exp_f32_e32 v39, v39
	v_exp_f32_e32 v40, v40
	v_add_f32_e32 v38, 1.0, v42
	v_rcp_f32_e32 v38, v38
	v_add_f32_e32 v39, 1.0, v39
	v_add_f32_e32 v40, 1.0, v40
	v_rcp_f32_e32 v39, v39
	v_rcp_f32_e32 v40, v40
	v_mul_f32_e32 v38, v44, v38
	v_mul_f32_e32 v42, v38, v36
	v_mul_f32_e32 v36, v49, v39
	v_mul_f32_e32 v38, v45, v40
	v_mul_f32_e32 v36, v36, v41
	v_mul_f32_e32 v37, v38, v37
	v_lshl_add_u64 v[38:39], v[50:51], 0, v[114:115]
	v_cvt_pk_bf16_f32 v34, v46, v34
	v_cvt_pk_bf16_f32 v35, v35, v36
	v_cvt_pk_bf16_f32 v36, v53, v43
	v_cvt_pk_bf16_f32 v37, v42, v37
	global_store_dwordx4 v[38:39], v[34:37], off
	s_nop 1
	v_mul_f32_e32 v34, 0xbfb8aa3b, v30
	v_exp_f32_e32 v34, v34
	v_mul_f32_e32 v35, 0xbfb8aa3b, v26
	v_exp_f32_e32 v35, v35
	v_add_u32_e32 v36, 0xa0, v147
	v_add_f32_e32 v34, 1.0, v34
	v_rcp_f32_e32 v37, v34
	v_add_f32_e32 v34, 1.0, v35
	v_rcp_f32_e32 v38, v34
	v_mad_i64_i32 v[34:35], s[62:63], v36, s90, v[134:135]
	v_mul_f32_e32 v30, v30, v37
	v_mul_f32_e32 v30, v30, v22
	v_mul_f32_e32 v22, v26, v38
	v_mul_f32_e32 v26, 0xbfb8aa3b, v31
	v_exp_f32_e32 v26, v26
	v_mul_f32_e32 v36, 0xbfb8aa3b, v27
	v_mul_f32_e32 v37, v22, v18
	v_exp_f32_e32 v36, v36
	v_add_f32_e32 v18, 1.0, v26
	v_rcp_f32_e32 v18, v18
	v_mul_f32_e32 v26, 0xbfb8aa3b, v32
	v_exp_f32_e32 v26, v26
	v_add_f32_e32 v22, 1.0, v36
	v_mul_f32_e32 v18, v31, v18
	v_rcp_f32_e32 v22, v22
	v_mul_f32_e32 v18, v18, v23
	v_add_f32_e32 v23, 1.0, v26
	v_rcp_f32_e32 v23, v23
	v_mul_f32_e32 v22, v27, v22
	v_mul_f32_e32 v26, 0xbfb8aa3b, v28
	v_mul_f32_e32 v27, v22, v19
	v_mul_f32_e32 v19, v32, v23
	v_exp_f32_e32 v26, v26
	v_mul_f32_e32 v19, v19, v24
	v_mul_f32_e32 v23, 0xbfb8aa3b, v33
	v_mul_f32_e32 v24, 0xbfb8aa3b, v29
	v_exp_f32_e32 v23, v23
	v_exp_f32_e32 v24, v24
	v_add_f32_e32 v22, 1.0, v26
	v_rcp_f32_e32 v22, v22
	v_add_f32_e32 v23, 1.0, v23
	v_add_f32_e32 v24, 1.0, v24
	v_rcp_f32_e32 v23, v23
	v_rcp_f32_e32 v24, v24
	v_mul_f32_e32 v22, v28, v22
	v_mul_f32_e32 v26, v22, v20
	v_mul_f32_e32 v20, v33, v23
	v_mul_f32_e32 v22, v29, v24
	v_mul_f32_e32 v20, v20, v25
	v_mul_f32_e32 v21, v22, v21
	v_lshl_add_u64 v[22:23], v[34:35], 0, v[114:115]
	v_cvt_pk_bf16_f32 v18, v30, v18
	v_cvt_pk_bf16_f32 v19, v19, v20
	v_cvt_pk_bf16_f32 v20, v37, v27
	v_cvt_pk_bf16_f32 v21, v26, v21
	global_store_dwordx4 v[22:23], v[18:21], off
	s_nop 1
	v_mul_f32_e32 v18, 0xbfb8aa3b, v14
	v_exp_f32_e32 v18, v18
	v_mul_f32_e32 v19, 0xbfb8aa3b, v10
	v_exp_f32_e32 v19, v19
	v_add_u32_e32 v20, 0xb0, v147
	v_add_f32_e32 v18, 1.0, v18
	v_rcp_f32_e32 v21, v18
	v_add_f32_e32 v18, 1.0, v19
	v_rcp_f32_e32 v22, v18
	v_mad_i64_i32 v[18:19], s[62:63], v20, s90, v[134:135]
	v_mul_f32_e32 v14, v14, v21
	v_mul_f32_e32 v14, v14, v6
	v_mul_f32_e32 v6, v10, v22
	v_mul_f32_e32 v10, 0xbfb8aa3b, v15
	v_exp_f32_e32 v10, v10
	v_mul_f32_e32 v20, 0xbfb8aa3b, v11
	v_mul_f32_e32 v21, v6, v2
	v_exp_f32_e32 v20, v20
	v_add_f32_e32 v2, 1.0, v10
	v_rcp_f32_e32 v2, v2
	v_mul_f32_e32 v10, 0xbfb8aa3b, v16
	v_exp_f32_e32 v10, v10
	v_add_f32_e32 v6, 1.0, v20
	v_mul_f32_e32 v2, v15, v2
	v_rcp_f32_e32 v6, v6
	v_mul_f32_e32 v2, v2, v7
	v_add_f32_e32 v7, 1.0, v10
	v_rcp_f32_e32 v7, v7
	v_mul_f32_e32 v6, v11, v6
	v_mul_f32_e32 v10, 0xbfb8aa3b, v12
	v_mul_f32_e32 v11, v6, v3
	v_mul_f32_e32 v3, v16, v7
	v_exp_f32_e32 v10, v10
	v_mul_f32_e32 v3, v3, v8
	v_mul_f32_e32 v7, 0xbfb8aa3b, v17
	v_mul_f32_e32 v8, 0xbfb8aa3b, v13
	v_exp_f32_e32 v7, v7
	v_exp_f32_e32 v8, v8
	v_add_f32_e32 v6, 1.0, v10
	v_rcp_f32_e32 v6, v6
	v_add_f32_e32 v7, 1.0, v7
	v_add_f32_e32 v8, 1.0, v8
	v_rcp_f32_e32 v7, v7
	v_rcp_f32_e32 v8, v8
	v_mul_f32_e32 v6, v12, v6
	v_mul_f32_e32 v10, v6, v4
	v_mul_f32_e32 v4, v17, v7
	v_mul_f32_e32 v6, v13, v8
	v_mul_f32_e32 v4, v4, v9
	v_mul_f32_e32 v5, v6, v5
	v_lshl_add_u64 v[6:7], v[18:19], 0, v[114:115]
	s_mov_b64 s[62:63], s[16:17]
	v_cvt_pk_bf16_f32 v2, v14, v2
	v_cvt_pk_bf16_f32 v3, v3, v4
	v_cvt_pk_bf16_f32 v4, v21, v11
	v_cvt_pk_bf16_f32 v5, v10, v5
	global_store_dwordx4 v[6:7], v[2:5], off
	s_cbranch_vccz .LBB0_135
	s_waitcnt vmcnt(0)
	s_cmpk_gt_u32 s3, 0xff
	s_cbranch_scc1 .LBB0_142
	s_barrier

; #define PG8_STAGE(bufoff, gbase, voff) do { _Pragma("unroll") for (int _i = 0; _i < 2; ++_i) \
;         asm volatile("s_mov_b32 m0, %2\n\ts_nop 0\n\tglobal_load_lds_dwordx4 %0, %1" :: "v"((voff)[_i]), "s"((const char*)(gbase)), "s"(ldsbase + (unsigned)(bufoff) + ldsw + (unsigned)_i * 8192u) : "memory", "m0"); } while (0)
; #define PG8_LDA(dst, b, h) do { _Pragma("unroll") for (int m = 0; m < 4; ++m) _Pragma("unroll") for (int k = 0; k < 2; ++k) dst[m][k] = *(const PG8_LAS bf16x8*)(lds + PG8_SA(b, h) + aoff + m * 2048 + k * 1024); } while (0)
; #define PG8_LDB(dst, b, h) do { _Pragma("unroll") for (int n = 0; n < 2; ++n) _Pragma("unroll") for (int k = 0; k < 2; ++k) dst[n][k] = *(const PG8_LAS bf16x8*)(lds + PG8_SB(b, h) + boff + n * 2048 + k * 1024); } while (0)
; #define PG8_MMA(ai, bj, At, Bt) do { __builtin_amdgcn_s_setprio(1); _Pragma("unroll") for (int m = 0; m < 4; ++m) _Pragma("unroll") for (int n = 0; n < 2; ++n) _Pragma("unroll") for (int k = 0; k < 2; ++k) \
;         acc[ai][bj][m][n] = __builtin_amdgcn_mfma_f32_16x16x32_bf16(Bt[n][k], At[m][k], acc[ai][bj][m][n], 0, 0, 0); __builtin_amdgcn_s_setprio(0); } while (0)
; template <class Epi, class Sched, bool ALIGN_EPI = false, bool SP2 = false>
; __device__ __forceinline__ void gemm_phase(PG8_LAS unsigned char* lds, const Gemm g, const Sched& S, const Epi& E) {
;     ...
;             const bool last = (t == nt - 2);
;             const char* a1 = cA + (size_t)(t + 1) * kstep;
;             const char* a2 = last ? nA : cA + (size_t)(t + 2) * kstep; const char* b2 = last ? nB : cB + (size_t)(t + 2) * kstep;
;             const char* a3 = a2 + kstep; const char* b3 = b2 + kstep;
;             if (last && has_next) S.a_ready(nxt);
;             if constexpr (epi_has_mid<Epi>::value) { if (t == Epi::MID_T) E.mid(acc, cur, wr, wc, fr, fq); }
;             if constexpr (SP2) {
;             PG8_LDB(B0, 0, 0); PG8_LDB(B1, 0, 1); PG8_SCHED; PG8_LDA(At, 0, 0); PG8_STAGE(PG8_SA(1, 1), a1 + hstep, voffA);
;             PG8_WAIT_V(8); PG8_WAIT_L(0); PG8_BAR; PG8_MMA(0, 0, At, B0); PG8_MMA(0, 1, At, B1); PG8_BAR; PG8_SCHED;
;             PG8_LDA(At, 0, 1); PG8_STAGE(PG8_SB(0, 0), b2, voffB); PG8_STAGE(PG8_SB(0, 1), b2 + hstep, voffB); PG8_STAGE(PG8_SA(0, 0), a2, voffA);
;             PG8_WAIT_V(8); PG8_WAIT_L(0); PG8_BAR; PG8_MMA(1, 0, At, B0); PG8_MMA(1, 1, At, B1); PG8_BAR; PG8_SCHED;
.LBB0_234:
	ds_read_b128 v[134:137], v145
	ds_read_b128 v[152:155], v145 offset:1024
	ds_read_b128 v[156:159], v145 offset:2048
	ds_read_b128 v[160:163], v145 offset:3072
	ds_read_b128 v[164:167], v146
	ds_read_b128 v[168:171], v146 offset:1024
	ds_read_b128 v[172:175], v146 offset:2048
	ds_read_b128 v[176:179], v146 offset:3072
	s_cmpk_eq_i32 s57, 0xa8
	s_cselect_b32 s76, s4, s53
	s_cselect_b32 s77, s5, s54
	s_cselect_b32 s66, s46, s55
	s_cselect_b32 s67, s47, s56
	s_add_u32 s62, s76, 0x80
	s_addc_u32 s63, s77, 0
	ds_read_b128 v[180:183], v147
	ds_read_b128 v[184:187], v147 offset:1024
	ds_read_b128 v[188:191], v147 offset:2048
	ds_read_b128 v[192:195], v147 offset:3072
	ds_read_b128 v[196:199], v147 offset:4096
	ds_read_b128 v[200:203], v147 offset:5120
	ds_read_b128 v[204:207], v147 offset:6144
	ds_read_b128 v[208:211], v147 offset:7168
	s_mov_b32 m0, s94
	s_nop 0
	global_load_lds_dwordx4 v1, s[50:51]
	s_nop 0
	s_mov_b32 m0, s95
	s_nop 0
	global_load_lds_dwordx4 v141, s[50:51]
	s_waitcnt vmcnt(8)
	s_waitcnt lgkmcnt(0)
	s_barrier
	s_setprio 1
	s_waitcnt lgkmcnt(7)
	v_mfma_f32_16x16x32_bf16 v[126:129], v[134:137], v[180:183], v[126:129]
	v_mfma_f32_16x16x32_bf16 v[126:129], v[152:155], v[184:187], v[126:129]
	s_waitcnt lgkmcnt(5)
	v_mfma_f32_16x16x32_bf16 v[122:125], v[160:163], v[184:187], v[122:125]
	v_mfma_f32_16x16x32_bf16 v[122:125], v[156:159], v[180:183], v[122:125]
	s_waitcnt lgkmcnt(3)
	v_mfma_f32_16x16x32_bf16 v[106:109], v[156:159], v[188:191], v[106:109]
	v_mfma_f32_16x16x32_bf16 v[106:109], v[160:163], v[192:195], v[106:109]
	s_waitcnt lgkmcnt(1)
	v_mfma_f32_16x16x32_bf16 v[110:113], v[152:155], v[192:195], v[110:113]
	v_mfma_f32_16x16x32_bf16 v[110:113], v[134:137], v[188:191], v[110:113]
	v_mfma_f32_16x16x32_bf16 v[94:97], v[134:137], v[196:199], v[94:97]
	v_mfma_f32_16x16x32_bf16 v[94:97], v[152:155], v[200:203], v[94:97]
	v_mfma_f32_16x16x32_bf16 v[90:93], v[160:163], v[200:203], v[90:93]
	v_mfma_f32_16x16x32_bf16 v[90:93], v[156:159], v[196:199], v[90:93]
	v_mfma_f32_16x16x32_bf16 v[74:77], v[156:159], v[204:207], v[74:77]
	v_mfma_f32_16x16x32_bf16 v[74:77], v[160:163], v[208:211], v[74:77]
	s_waitcnt lgkmcnt(0)
	v_mfma_f32_16x16x32_bf16 v[78:81], v[152:155], v[208:211], v[78:81]
	v_mfma_f32_16x16x32_bf16 v[78:81], v[134:137], v[204:207], v[78:81]
	s_setprio 0
	s_setprio 1
	v_mfma_f32_16x16x32_bf16 v[118:121], v[164:167], v[180:183], v[118:121]
	v_mfma_f32_16x16x32_bf16 v[118:121], v[168:171], v[184:187], v[118:121]
	v_mfma_f32_16x16x32_bf16 v[114:117], v[176:179], v[184:187], v[114:117]
	v_mfma_f32_16x16x32_bf16 v[114:117], v[172:175], v[180:183], v[114:117]
	v_mfma_f32_16x16x32_bf16 v[98:101], v[172:175], v[188:191], v[98:101]
	v_mfma_f32_16x16x32_bf16 v[98:101], v[176:179], v[192:195], v[98:101]
	v_mfma_f32_16x16x32_bf16 v[102:105], v[168:171], v[192:195], v[102:105]
	v_mfma_f32_16x16x32_bf16 v[102:105], v[164:167], v[188:191], v[102:105]
	v_mfma_f32_16x16x32_bf16 v[86:89], v[164:167], v[196:199], v[86:89]
	v_mfma_f32_16x16x32_bf16 v[86:89], v[168:171], v[200:203], v[86:89]
	v_mfma_f32_16x16x32_bf16 v[82:85], v[176:179], v[200:203], v[82:85]
	v_mfma_f32_16x16x32_bf16 v[82:85], v[172:175], v[196:199], v[82:85]
	v_mfma_f32_16x16x32_bf16 v[66:69], v[172:175], v[204:207], v[66:69]
	v_mfma_f32_16x16x32_bf16 v[66:69], v[176:179], v[208:211], v[66:69]
	v_mfma_f32_16x16x32_bf16 v[70:73], v[168:171], v[208:211], v[70:73]
	s_setprio 2
	s_barrier
	v_mfma_f32_16x16x32_bf16 v[70:73], v[164:167], v[204:207], v[70:73]
	s_setprio 0
	ds_read_b128 v[180:183], v147 offset:16384
	ds_read_b128 v[184:187], v147 offset:17408
	ds_read_b128 v[188:191], v147 offset:18432
	ds_read_b128 v[192:195], v147 offset:19456
	ds_read_b128 v[196:199], v147 offset:20480
	ds_read_b128 v[200:203], v147 offset:21504
	ds_read_b128 v[252:255], v147 offset:22528
	ds_read_b128 v[208:211], v147 offset:23552
	s_mov_b32 m0, s64
	s_nop 0
	global_load_lds_dwordx4 v140, s[66:67]
	s_add_u32 s58, s66, 0x2b0000
	s_mov_b32 m0, s65
	s_nop 0
	global_load_lds_dwordx4 v142, s[66:67]
	s_addc_u32 s59, s67, 0
	s_mov_b32 m0, s82
	s_nop 0
	global_load_lds_dwordx4 v140, s[58:59]
	s_nop 0
	s_mov_b32 m0, s83
	s_nop 0
	global_load_lds_dwordx4 v142, s[58:59]
	s_nop 0
	s_mov_b32 m0, s35
	s_nop 0
	global_load_lds_dwordx4 v1, s[76:77]
	s_nop 0
	s_mov_b32 m0, s84
	s_nop 0
	global_load_lds_dwordx4 v141, s[76:77]
	s_waitcnt vmcnt(8)
	s_waitcnt lgkmcnt(0)
	s_barrier
	s_setprio 1
	s_waitcnt lgkmcnt(7)
	v_mfma_f32_16x16x32_bf16 v[62:65], v[134:137], v[180:183], v[62:65]
	v_mfma_f32_16x16x32_bf16 v[62:65], v[152:155], v[184:187], v[62:65]
	s_waitcnt lgkmcnt(5)
	v_mfma_f32_16x16x32_bf16 v[58:61], v[160:163], v[184:187], v[58:61]
	v_mfma_f32_16x16x32_bf16 v[58:61], v[156:159], v[180:183], v[58:61]
	s_waitcnt lgkmcnt(3)
	v_mfma_f32_16x16x32_bf16 v[42:45], v[156:159], v[188:191], v[42:45]
	v_mfma_f32_16x16x32_bf16 v[42:45], v[160:163], v[192:195], v[42:45]
	s_waitcnt lgkmcnt(1)
	v_mfma_f32_16x16x32_bf16 v[46:49], v[152:155], v[192:195], v[46:49]
	v_mfma_f32_16x16x32_bf16 v[46:49], v[134:137], v[188:191], v[46:49]
	v_mfma_f32_16x16x32_bf16 v[30:33], v[134:137], v[196:199], v[30:33]
	v_mfma_f32_16x16x32_bf16 v[30:33], v[152:155], v[200:203], v[30:33]
	v_mfma_f32_16x16x32_bf16 v[26:29], v[160:163], v[200:203], v[26:29]
	v_mfma_f32_16x16x32_bf16 v[26:29], v[156:159], v[196:199], v[26:29]
	v_mfma_f32_16x16x32_bf16 v[10:13], v[156:159], v[252:255], v[10:13]
	v_mfma_f32_16x16x32_bf16 v[10:13], v[160:163], v[208:211], v[10:13]
	s_waitcnt lgkmcnt(0)
	v_mfma_f32_16x16x32_bf16 v[14:17], v[152:155], v[208:211], v[14:17]
	v_mfma_f32_16x16x32_bf16 v[14:17], v[134:137], v[252:255], v[14:17]
	s_setprio 0
	s_setprio 1
	v_mfma_f32_16x16x32_bf16 v[54:57], v[164:167], v[180:183], v[54:57]
	v_mfma_f32_16x16x32_bf16 v[54:57], v[168:171], v[184:187], v[54:57]
	v_mfma_f32_16x16x32_bf16 v[50:53], v[176:179], v[184:187], v[50:53]
	v_mfma_f32_16x16x32_bf16 v[50:53], v[172:175], v[180:183], v[50:53]
	v_mfma_f32_16x16x32_bf16 v[34:37], v[172:175], v[188:191], v[34:37]
	v_mfma_f32_16x16x32_bf16 v[34:37], v[176:179], v[192:195], v[34:37]
	v_mfma_f32_16x16x32_bf16 v[38:41], v[168:171], v[192:195], v[38:41]
	v_mfma_f32_16x16x32_bf16 v[38:41], v[164:167], v[188:191], v[38:41]
	v_mfma_f32_16x16x32_bf16 v[22:25], v[164:167], v[196:199], v[22:25]
	v_mfma_f32_16x16x32_bf16 v[22:25], v[168:171], v[200:203], v[22:25]
	v_mfma_f32_16x16x32_bf16 v[18:21], v[176:179], v[200:203], v[18:21]
	v_mfma_f32_16x16x32_bf16 v[18:21], v[172:175], v[196:199], v[18:21]
	v_mfma_f32_16x16x32_bf16 v[2:5], v[172:175], v[252:255], v[2:5]
	v_mfma_f32_16x16x32_bf16 v[2:5], v[176:179], v[208:211], v[2:5]
	v_mfma_f32_16x16x32_bf16 v[6:9], v[168:171], v[208:211], v[6:9]
	s_setprio 2
	s_barrier
; #define PG8_STAGE(bufoff, gbase, voff) do { _Pragma("unroll") for (int _i = 0; _i < 2; ++_i) \
;         asm volatile("s_mov_b32 m0, %2\n\ts_nop 0\n\tglobal_load_lds_dwordx4 %0, %1" :: "v"((voff)[_i]), "s"((const char*)(gbase)), "s"(ldsbase + (unsigned)(bufoff) + ldsw + (unsigned)_i * 8192u) : "memory", "m0"); } while (0)
; #define PG8_LDA(dst, b, h) do { _Pragma("unroll") for (int m = 0; m < 4; ++m) _Pragma("unroll") for (int k = 0; k < 2; ++k) dst[m][k] = *(const PG8_LAS bf16x8*)(lds + PG8_SA(b, h) + aoff + m * 2048 + k * 1024); } while (0)
; #define PG8_LDB(dst, b, h) do { _Pragma("unroll") for (int n = 0; n < 2; ++n) _Pragma("unroll") for (int k = 0; k < 2; ++k) dst[n][k] = *(const PG8_LAS bf16x8*)(lds + PG8_SB(b, h) + boff + n * 2048 + k * 1024); } while (0)
; #define PG8_MMA(ai, bj, At, Bt) do { __builtin_amdgcn_s_setprio(1); _Pragma("unroll") for (int m = 0; m < 4; ++m) _Pragma("unroll") for (int n = 0; n < 2; ++n) _Pragma("unroll") for (int k = 0; k < 2; ++k) \
;         acc[ai][bj][m][n] = __builtin_amdgcn_mfma_f32_16x16x32_bf16(Bt[n][k], At[m][k], acc[ai][bj][m][n], 0, 0, 0); __builtin_amdgcn_s_setprio(0); } while (0)
; #define PG8_WAIT_V(n) asm volatile("s_waitcnt vmcnt(" #n ")" ::: "memory")
; #define PG8_WAIT_L(n) asm volatile("s_waitcnt lgkmcnt(" #n ")" ::: "memory")
; #define PG8_BAR __builtin_amdgcn_s_barrier()
; #define PG8_SCHED __builtin_amdgcn_sched_barrier(0)
; template <class Epi, class Sched, bool ALIGN_EPI = false, bool SP2 = false>
; __device__ __forceinline__ void gemm_phase(PG8_LAS unsigned char* lds, const Gemm g, const Sched& S, const Epi& E) {
;     ...
;             PG8_WAIT_V(8); PG8_WAIT_L(0); PG8_BAR; PG8_MMA(1, 0, At, B0); PG8_MMA(1, 1, At, B1); PG8_BAR; PG8_SCHED;
;             PG8_LDB(B0, 1, 0); PG8_LDB(B1, 1, 1); PG8_SCHED; PG8_LDA(At, 1, 0); PG8_STAGE(PG8_SA(0, 1), a2 + hstep, voffA);
;             PG8_WAIT_V(8); PG8_WAIT_L(0); PG8_BAR; PG8_MMA(0, 0, At, B0); PG8_MMA(0, 1, At, B1); PG8_BAR; PG8_SCHED;
	v_mfma_f32_16x16x32_bf16 v[6:9], v[164:167], v[252:255], v[6:9]
	s_setprio 0
	ds_read_b128 v[134:137], v148
	ds_read_b128 v[152:155], v148 offset:1024
	ds_read_b128 v[156:159], v148 offset:2048
	ds_read_b128 v[160:163], v148 offset:3072
	ds_read_b128 v[248:251], v149
	ds_read_b128 v[168:171], v149 offset:1024
	ds_read_b128 v[172:175], v149 offset:2048
	ds_read_b128 v[176:179], v149 offset:3072
	ds_read_b128 v[180:183], v147 offset:32768
	ds_read_b128 v[184:187], v147 offset:33792
	ds_read_b128 v[188:191], v147 offset:34816
	ds_read_b128 v[192:195], v147 offset:35840
	ds_read_b128 v[196:199], v147 offset:36864
	ds_read_b128 v[200:203], v147 offset:37888
	ds_read_b128 v[204:207], v147 offset:38912
	ds_read_b128 v[208:211], v147 offset:39936
	s_add_u32 s58, s76, 0x2b0000
	s_addc_u32 s59, s77, 0
	s_mov_b32 m0, s85
	s_nop 0
	global_load_lds_dwordx4 v1, s[58:59]
	s_nop 0
	s_mov_b32 m0, s86
	s_nop 0
	global_load_lds_dwordx4 v141, s[58:59]
	s_waitcnt vmcnt(8)
	s_waitcnt lgkmcnt(0)
	s_barrier
	s_setprio 1
	s_waitcnt lgkmcnt(7)
	v_mfma_f32_16x16x32_bf16 v[126:129], v[134:137], v[180:183], v[126:129]
	v_mfma_f32_16x16x32_bf16 v[126:129], v[152:155], v[184:187], v[126:129]
	s_waitcnt lgkmcnt(5)
	v_mfma_f32_16x16x32_bf16 v[122:125], v[160:163], v[184:187], v[122:125]
	v_mfma_f32_16x16x32_bf16 v[122:125], v[156:159], v[180:183], v[122:125]
	s_waitcnt lgkmcnt(3)
	v_mfma_f32_16x16x32_bf16 v[106:109], v[156:159], v[188:191], v[106:109]
	v_mfma_f32_16x16x32_bf16 v[106:109], v[160:163], v[192:195], v[106:109]
	s_waitcnt lgkmcnt(1)
	v_mfma_f32_16x16x32_bf16 v[110:113], v[152:155], v[192:195], v[110:113]
	v_mfma_f32_16x16x32_bf16 v[110:113], v[134:137], v[188:191], v[110:113]
	v_mfma_f32_16x16x32_bf16 v[94:97], v[134:137], v[196:199], v[94:97]
	v_mfma_f32_16x16x32_bf16 v[94:97], v[152:155], v[200:203], v[94:97]
	v_mfma_f32_16x16x32_bf16 v[90:93], v[160:163], v[200:203], v[90:93]
	v_mfma_f32_16x16x32_bf16 v[90:93], v[156:159], v[196:199], v[90:93]
	v_mfma_f32_16x16x32_bf16 v[74:77], v[156:159], v[204:207], v[74:77]
	v_mfma_f32_16x16x32_bf16 v[74:77], v[160:163], v[208:211], v[74:77]
	s_waitcnt lgkmcnt(0)
	v_mfma_f32_16x16x32_bf16 v[78:81], v[152:155], v[208:211], v[78:81]
	v_mfma_f32_16x16x32_bf16 v[78:81], v[134:137], v[204:207], v[78:81]
	s_setprio 0
	s_setprio 1
	v_mfma_f32_16x16x32_bf16 v[118:121], v[248:251], v[180:183], v[118:121]
	v_mfma_f32_16x16x32_bf16 v[118:121], v[168:171], v[184:187], v[118:121]
	v_mfma_f32_16x16x32_bf16 v[114:117], v[176:179], v[184:187], v[114:117]
	v_mfma_f32_16x16x32_bf16 v[114:117], v[172:175], v[180:183], v[114:117]
	v_mfma_f32_16x16x32_bf16 v[98:101], v[172:175], v[188:191], v[98:101]
	v_mfma_f32_16x16x32_bf16 v[98:101], v[176:179], v[192:195], v[98:101]
	v_mfma_f32_16x16x32_bf16 v[102:105], v[168:171], v[192:195], v[102:105]
	v_mfma_f32_16x16x32_bf16 v[102:105], v[248:251], v[188:191], v[102:105]
	v_mfma_f32_16x16x32_bf16 v[86:89], v[248:251], v[196:199], v[86:89]
	v_mfma_f32_16x16x32_bf16 v[86:89], v[168:171], v[200:203], v[86:89]
	v_mfma_f32_16x16x32_bf16 v[82:85], v[176:179], v[200:203], v[82:85]
	v_mfma_f32_16x16x32_bf16 v[82:85], v[172:175], v[196:199], v[82:85]
	v_mfma_f32_16x16x32_bf16 v[66:69], v[172:175], v[204:207], v[66:69]
	v_mfma_f32_16x16x32_bf16 v[66:69], v[176:179], v[208:211], v[66:69]
	v_mfma_f32_16x16x32_bf16 v[70:73], v[168:171], v[208:211], v[70:73]
	s_setprio 2
	s_barrier
; #define PG8_STAGE(bufoff, gbase, voff) do { _Pragma("unroll") for (int _i = 0; _i < 2; ++_i) \
;         asm volatile("s_mov_b32 m0, %2\n\ts_nop 0\n\tglobal_load_lds_dwordx4 %0, %1" :: "v"((voff)[_i]), "s"((const char*)(gbase)), "s"(ldsbase + (unsigned)(bufoff) + ldsw + (unsigned)_i * 8192u) : "memory", "m0"); } while (0)
; #define PG8_LDA(dst, b, h) do { _Pragma("unroll") for (int m = 0; m < 4; ++m) _Pragma("unroll") for (int k = 0; k < 2; ++k) dst[m][k] = *(const PG8_LAS bf16x8*)(lds + PG8_SA(b, h) + aoff + m * 2048 + k * 1024); } while (0)
; #define PG8_MMA(ai, bj, At, Bt) do { __builtin_amdgcn_s_setprio(1); _Pragma("unroll") for (int m = 0; m < 4; ++m) _Pragma("unroll") for (int n = 0; n < 2; ++n) _Pragma("unroll") for (int k = 0; k < 2; ++k) \
;         acc[ai][bj][m][n] = __builtin_amdgcn_mfma_f32_16x16x32_bf16(Bt[n][k], At[m][k], acc[ai][bj][m][n], 0, 0, 0); __builtin_amdgcn_s_setprio(0); } while (0)
; #define PG8_WAIT_V(n) asm volatile("s_waitcnt vmcnt(" #n ")" ::: "memory")
; #define PG8_WAIT_L(n) asm volatile("s_waitcnt lgkmcnt(" #n ")" ::: "memory")
; #define PG8_BAR __builtin_amdgcn_s_barrier()
; #define PG8_SCHED __builtin_amdgcn_sched_barrier(0)
; template <class Epi, class Sched, bool ALIGN_EPI = false, bool SP2 = false>
; __device__ __forceinline__ void gemm_phase(PG8_LAS unsigned char* lds, const Gemm g, const Sched& S, const Epi& E) {
;     ...
;             PG8_WAIT_V(8); PG8_WAIT_L(0); PG8_BAR; PG8_MMA(0, 0, At, B0); PG8_MMA(0, 1, At, B1); PG8_BAR; PG8_SCHED;
;             PG8_LDA(At, 1, 1); PG8_STAGE(PG8_SB(1, 0), b3, voffB); PG8_STAGE(PG8_SB(1, 1), b3 + hstep, voffB); PG8_STAGE(PG8_SA(1, 0), a3, voffA);
;             PG8_WAIT_V(8); PG8_WAIT_L(0); PG8_BAR; PG8_MMA(1, 0, At, B0); PG8_MMA(1, 1, At, B1); PG8_BAR; PG8_SCHED;
	v_mfma_f32_16x16x32_bf16 v[70:73], v[248:251], v[204:207], v[70:73]
	s_setprio 0
	ds_read_b128 v[180:183], v147 offset:49152
	ds_read_b128 v[184:187], v147 offset:50176
	ds_read_b128 v[188:191], v147 offset:51200
	ds_read_b128 v[192:195], v147 offset:52224
	ds_read_b128 v[196:199], v147 offset:53248
	ds_read_b128 v[200:203], v147 offset:54272
	ds_read_b128 v[252:255], v147 offset:55296
	ds_read_b128 v[208:211], v147 offset:56320
	s_add_u32 s58, s66, 0x80
	s_addc_u32 s59, s67, 0
	s_mov_b32 m0, s88
	s_nop 0
	global_load_lds_dwordx4 v140, s[58:59]
	s_nop 0
	s_mov_b32 m0, s89
	s_nop 0
	global_load_lds_dwordx4 v142, s[58:59]
	s_add_u32 s58, s66, 0x2b0080
	s_addc_u32 s59, s67, 0
	s_mov_b32 m0, s92
	s_nop 0
	global_load_lds_dwordx4 v140, s[58:59]
	s_nop 0
	s_mov_b32 m0, s93
	s_nop 0
	global_load_lds_dwordx4 v142, s[58:59]
	s_nop 0
	s_mov_b32 m0, s90
	s_nop 0
	global_load_lds_dwordx4 v1, s[62:63]
	s_nop 0
	s_mov_b32 m0, s91
	s_nop 0
	global_load_lds_dwordx4 v141, s[62:63]
	s_waitcnt vmcnt(8)
	s_waitcnt lgkmcnt(0)
	s_barrier
	s_setprio 1
	s_waitcnt lgkmcnt(7)
	v_mfma_f32_16x16x32_bf16 v[62:65], v[134:137], v[180:183], v[62:65]
	v_mfma_f32_16x16x32_bf16 v[62:65], v[152:155], v[184:187], v[62:65]
	s_waitcnt lgkmcnt(5)
	v_mfma_f32_16x16x32_bf16 v[58:61], v[160:163], v[184:187], v[58:61]
	v_mfma_f32_16x16x32_bf16 v[58:61], v[156:159], v[180:183], v[58:61]
	s_waitcnt lgkmcnt(3)
	v_mfma_f32_16x16x32_bf16 v[42:45], v[156:159], v[188:191], v[42:45]
	v_mfma_f32_16x16x32_bf16 v[42:45], v[160:163], v[192:195], v[42:45]
	s_waitcnt lgkmcnt(1)
	v_mfma_f32_16x16x32_bf16 v[46:49], v[152:155], v[192:195], v[46:49]
	v_mfma_f32_16x16x32_bf16 v[46:49], v[134:137], v[188:191], v[46:49]
	v_mfma_f32_16x16x32_bf16 v[30:33], v[134:137], v[196:199], v[30:33]
	v_mfma_f32_16x16x32_bf16 v[30:33], v[152:155], v[200:203], v[30:33]
	v_mfma_f32_16x16x32_bf16 v[26:29], v[160:163], v[200:203], v[26:29]
	v_mfma_f32_16x16x32_bf16 v[26:29], v[156:159], v[196:199], v[26:29]
	v_mfma_f32_16x16x32_bf16 v[10:13], v[156:159], v[252:255], v[10:13]
	v_mfma_f32_16x16x32_bf16 v[10:13], v[160:163], v[208:211], v[10:13]
	s_waitcnt lgkmcnt(0)
	v_mfma_f32_16x16x32_bf16 v[14:17], v[152:155], v[208:211], v[14:17]
	v_mfma_f32_16x16x32_bf16 v[14:17], v[134:137], v[252:255], v[14:17]
	s_setprio 0
	s_setprio 1
	v_mfma_f32_16x16x32_bf16 v[54:57], v[248:251], v[180:183], v[54:57]
	v_mfma_f32_16x16x32_bf16 v[54:57], v[168:171], v[184:187], v[54:57]
	v_mfma_f32_16x16x32_bf16 v[50:53], v[176:179], v[184:187], v[50:53]
	v_mfma_f32_16x16x32_bf16 v[50:53], v[172:175], v[180:183], v[50:53]
	v_mfma_f32_16x16x32_bf16 v[34:37], v[172:175], v[188:191], v[34:37]
	v_mfma_f32_16x16x32_bf16 v[34:37], v[176:179], v[192:195], v[34:37]
	v_mfma_f32_16x16x32_bf16 v[38:41], v[168:171], v[192:195], v[38:41]
	v_mfma_f32_16x16x32_bf16 v[38:41], v[248:251], v[188:191], v[38:41]
	v_mfma_f32_16x16x32_bf16 v[22:25], v[248:251], v[196:199], v[22:25]
	v_mfma_f32_16x16x32_bf16 v[22:25], v[168:171], v[200:203], v[22:25]
	v_mfma_f32_16x16x32_bf16 v[18:21], v[176:179], v[200:203], v[18:21]
	v_mfma_f32_16x16x32_bf16 v[18:21], v[172:175], v[196:199], v[18:21]
	v_mfma_f32_16x16x32_bf16 v[2:5], v[172:175], v[252:255], v[2:5]
	v_mfma_f32_16x16x32_bf16 v[2:5], v[176:179], v[208:211], v[2:5]
	v_mfma_f32_16x16x32_bf16 v[6:9], v[168:171], v[208:211], v[6:9]
	s_setprio 2
	s_barrier
	v_mfma_f32_16x16x32_bf16 v[6:9], v[248:251], v[252:255], v[6:9]
	s_setprio 0
	s_add_i32 s57, s57, 2
	s_add_u32 s53, s53, 0x100
	s_addc_u32 s54, s54, 0
	s_add_u32 s55, s55, 0x100
	s_addc_u32 s56, s56, 0
	s_add_u32 s50, s50, 0x100
	s_addc_u32 s51, s51, 0
	s_cmpk_gt_u32 s57, 0xa9
	s_cbranch_scc0 .LBB0_234
	s_and_b64 vcc, exec, s[16:17]
	s_cbranch_vccz .LBB0_237
	s_barrier

; #define PG8_STAGE(bufoff, gbase, voff) do { _Pragma("unroll") for (int _i = 0; _i < 2; ++_i) \
;         asm volatile("s_mov_b32 m0, %2\n\ts_nop 0\n\tglobal_load_lds_dwordx4 %0, %1" :: "v"((voff)[_i]), "s"((const char*)(gbase)), "s"(ldsbase + (unsigned)(bufoff) + ldsw + (unsigned)_i * 8192u) : "memory", "m0"); } while (0)
; #define PG8_LDA(dst, b, h) do { _Pragma("unroll") for (int m = 0; m < 4; ++m) _Pragma("unroll") for (int k = 0; k < 2; ++k) dst[m][k] = *(const PG8_LAS bf16x8*)(lds + PG8_SA(b, h) + aoff + m * 2048 + k * 1024); } while (0)
; #define PG8_LDB(dst, b, h) do { _Pragma("unroll") for (int n = 0; n < 2; ++n) _Pragma("unroll") for (int k = 0; k < 2; ++k) dst[n][k] = *(const PG8_LAS bf16x8*)(lds + PG8_SB(b, h) + boff + n * 2048 + k * 1024); } while (0)
; #define PG8_MMA(ai, bj, At, Bt) do { __builtin_amdgcn_s_setprio(1); _Pragma("unroll") for (int m = 0; m < 4; ++m) _Pragma("unroll") for (int n = 0; n < 2; ++n) _Pragma("unroll") for (int k = 0; k < 2; ++k) \
;         acc[ai][bj][m][n] = __builtin_amdgcn_mfma_f32_16x16x32_bf16(Bt[n][k], At[m][k], acc[ai][bj][m][n], 0, 0, 0); __builtin_amdgcn_s_setprio(0); } while (0)
; #define PG8_WAIT_V(n) asm volatile("s_waitcnt vmcnt(" #n ")" ::: "memory")
; #define PG8_BAR __builtin_amdgcn_s_barrier()
; template <class Epi, class Sched, bool ALIGN_EPI = false, bool SP2 = false>
; __device__ __forceinline__ void gemm_phase(PG8_LAS unsigned char* lds, const Gemm g, const Sched& S, const Epi& E) {
;     ...
;             const bool last = (t == nt - 2);
;             const char* a1 = cA + (size_t)(t + 1) * kstep;
;             const char* a2 = last ? nA : cA + (size_t)(t + 2) * kstep; const char* b2 = last ? nB : cB + (size_t)(t + 2) * kstep;
;             const char* a3 = a2 + kstep; const char* b3 = b2 + kstep;
;             if (last && has_next) S.a_ready(nxt);
;             if constexpr (epi_has_mid<Epi>::value) { if (t == Epi::MID_T) E.mid(acc, cur, wr, wc, fr, fq); }
;             if constexpr (SP2) {
;             PG8_LDB(B0, 0, 0); PG8_LDB(B1, 0, 1); PG8_SCHED; PG8_LDA(At, 0, 0); PG8_STAGE(PG8_SA(1, 1), a1 + hstep, voffA);
;             PG8_WAIT_V(8); PG8_WAIT_L(0); PG8_BAR; PG8_MMA(0, 0, At, B0); PG8_MMA(0, 1, At, B1); PG8_BAR; PG8_SCHED;
;             PG8_LDA(At, 0, 1); PG8_STAGE(PG8_SB(0, 0), b2, voffB); PG8_STAGE(PG8_SB(0, 1), b2 + hstep, voffB); PG8_STAGE(PG8_SA(0, 0), a2, voffA);
.LBB0_325:
	v_add_u32_e32 v138, 0x10000, v151
	ds_read_b128 v[154:157], v138
	ds_read_b128 v[158:161], v138 offset:1024
	ds_read_b128 v[162:165], v138 offset:2048
	ds_read_b128 v[166:169], v138 offset:3072
	v_add_u32_e32 v138, 0x14000, v151
	s_add_u32 s8, s82, 0x100
	ds_read_b128 v[170:173], v138
	ds_read_b128 v[174:177], v138 offset:1024
	ds_read_b128 v[178:181], v138 offset:2048
	ds_read_b128 v[182:185], v138 offset:3072
	s_addc_u32 s9, s83, 0
	s_and_b64 s[60:61], s[62:63], exec
	s_cselect_b32 s84, s54, s8
	s_cselect_b32 s85, s19, s9
	s_cselect_b32 s63, s17, s57
	s_cselect_b32 s62, s55, s56
	s_add_u32 s66, s84, 0x80
	s_addc_u32 s67, s85, 0
	s_add_u32 s76, s62, 0x80
	s_addc_u32 s77, s63, 0
	ds_read_b128 v[186:189], v152
	ds_read_b128 v[190:193], v152 offset:1024
	ds_read_b128 v[194:197], v152 offset:2048
	ds_read_b128 v[198:201], v152 offset:3072
	ds_read_b128 v[202:205], v152 offset:4096
	ds_read_b128 v[206:209], v152 offset:5120
	ds_read_b128 v[210:213], v152 offset:6144
	ds_read_b128 v[214:217], v152 offset:7168
	s_add_u32 s60, s82, 0x100080
	s_addc_u32 s61, s83, 0
	s_mov_b32 m0, s97
	s_nop 0
	global_load_lds_dwordx4 v141, s[60:61]
	s_nop 0
	s_mov_b32 m0, s70
	s_nop 0
	global_load_lds_dwordx4 v143, s[60:61]
	s_waitcnt vmcnt(8)
	s_waitcnt lgkmcnt(0)
	s_barrier
	s_setprio 1
	s_waitcnt lgkmcnt(7)
	v_mfma_f32_16x16x32_bf16 v[126:129], v[154:157], v[186:189], v[126:129]
	v_mfma_f32_16x16x32_bf16 v[126:129], v[158:161], v[190:193], v[126:129]
	s_waitcnt lgkmcnt(5)
	v_mfma_f32_16x16x32_bf16 v[122:125], v[166:169], v[190:193], v[122:125]
	v_mfma_f32_16x16x32_bf16 v[122:125], v[162:165], v[186:189], v[122:125]
	s_waitcnt lgkmcnt(3)
	v_mfma_f32_16x16x32_bf16 v[106:109], v[162:165], v[194:197], v[106:109]
	v_mfma_f32_16x16x32_bf16 v[106:109], v[166:169], v[198:201], v[106:109]
	s_waitcnt lgkmcnt(1)
	v_mfma_f32_16x16x32_bf16 v[110:113], v[158:161], v[198:201], v[110:113]
	v_mfma_f32_16x16x32_bf16 v[110:113], v[154:157], v[194:197], v[110:113]
	v_mfma_f32_16x16x32_bf16 v[94:97], v[154:157], v[202:205], v[94:97]
	v_mfma_f32_16x16x32_bf16 v[94:97], v[158:161], v[206:209], v[94:97]
	v_mfma_f32_16x16x32_bf16 v[90:93], v[166:169], v[206:209], v[90:93]
	v_mfma_f32_16x16x32_bf16 v[90:93], v[162:165], v[202:205], v[90:93]
	v_mfma_f32_16x16x32_bf16 v[74:77], v[162:165], v[210:213], v[74:77]
	v_mfma_f32_16x16x32_bf16 v[74:77], v[166:169], v[214:217], v[74:77]
	s_waitcnt lgkmcnt(0)
	v_mfma_f32_16x16x32_bf16 v[78:81], v[158:161], v[214:217], v[78:81]
	v_mfma_f32_16x16x32_bf16 v[78:81], v[154:157], v[210:213], v[78:81]
	s_setprio 0
	s_setprio 1
	v_mfma_f32_16x16x32_bf16 v[118:121], v[170:173], v[186:189], v[118:121]
	v_mfma_f32_16x16x32_bf16 v[118:121], v[174:177], v[190:193], v[118:121]
	v_mfma_f32_16x16x32_bf16 v[114:117], v[182:185], v[190:193], v[114:117]
	v_mfma_f32_16x16x32_bf16 v[114:117], v[178:181], v[186:189], v[114:117]
	v_mfma_f32_16x16x32_bf16 v[98:101], v[178:181], v[194:197], v[98:101]
	v_mfma_f32_16x16x32_bf16 v[98:101], v[182:185], v[198:201], v[98:101]
	v_mfma_f32_16x16x32_bf16 v[102:105], v[174:177], v[198:201], v[102:105]
	v_mfma_f32_16x16x32_bf16 v[102:105], v[170:173], v[194:197], v[102:105]
	v_mfma_f32_16x16x32_bf16 v[86:89], v[170:173], v[202:205], v[86:89]
	v_mfma_f32_16x16x32_bf16 v[86:89], v[174:177], v[206:209], v[86:89]
	v_mfma_f32_16x16x32_bf16 v[82:85], v[182:185], v[206:209], v[82:85]
	v_mfma_f32_16x16x32_bf16 v[82:85], v[178:181], v[202:205], v[82:85]
	v_mfma_f32_16x16x32_bf16 v[66:69], v[178:181], v[210:213], v[66:69]
	v_mfma_f32_16x16x32_bf16 v[66:69], v[182:185], v[214:217], v[66:69]
	v_mfma_f32_16x16x32_bf16 v[70:73], v[174:177], v[214:217], v[70:73]
	s_setprio 2
	s_barrier
	v_mfma_f32_16x16x32_bf16 v[70:73], v[170:173], v[210:213], v[70:73]
	s_setprio 0
	ds_read_b128 v[186:189], v152 offset:16384
	ds_read_b128 v[190:193], v152 offset:17408
	ds_read_b128 v[194:197], v152 offset:18432
	ds_read_b128 v[198:201], v152 offset:19456
	ds_read_b128 v[202:205], v152 offset:20480
	ds_read_b128 v[206:209], v152 offset:21504
	ds_read_b128 v[252:255], v152 offset:22528
	ds_read_b128 v[214:217], v152 offset:23552
	s_mov_b32 m0, s68
	s_nop 0
	global_load_lds_dwordx4 v142, s[62:63]
	s_add_u32 s60, s62, 0x100000
	s_mov_b32 m0, s69
	s_nop 0
	global_load_lds_dwordx4 v144, s[62:63]
	s_addc_u32 s61, s63, 0
	s_mov_b32 m0, s81
	s_nop 0
	global_load_lds_dwordx4 v142, s[60:61]
	s_nop 0
	s_mov_b32 m0, s86
	s_nop 0
	global_load_lds_dwordx4 v144, s[60:61]
	s_nop 0
	s_mov_b32 m0, s65
	s_nop 0
	global_load_lds_dwordx4 v141, s[84:85]
	s_nop 0
	s_mov_b32 m0, s87
	s_nop 0
	global_load_lds_dwordx4 v143, s[84:85]
	s_waitcnt vmcnt(8)
	s_waitcnt lgkmcnt(0)
	s_barrier
; #define PG8_STAGE(bufoff, gbase, voff) do { _Pragma("unroll") for (int _i = 0; _i < 2; ++_i) \
;         asm volatile("s_mov_b32 m0, %2\n\ts_nop 0\n\tglobal_load_lds_dwordx4 %0, %1" :: "v"((voff)[_i]), "s"((const char*)(gbase)), "s"(ldsbase + (unsigned)(bufoff) + ldsw + (unsigned)_i * 8192u) : "memory", "m0"); } while (0)
; #define PG8_LDA(dst, b, h) do { _Pragma("unroll") for (int m = 0; m < 4; ++m) _Pragma("unroll") for (int k = 0; k < 2; ++k) dst[m][k] = *(const PG8_LAS bf16x8*)(lds + PG8_SA(b, h) + aoff + m * 2048 + k * 1024); } while (0)
; #define PG8_LDB(dst, b, h) do { _Pragma("unroll") for (int n = 0; n < 2; ++n) _Pragma("unroll") for (int k = 0; k < 2; ++k) dst[n][k] = *(const PG8_LAS bf16x8*)(lds + PG8_SB(b, h) + boff + n * 2048 + k * 1024); } while (0)
; #define PG8_MMA(ai, bj, At, Bt) do { __builtin_amdgcn_s_setprio(1); _Pragma("unroll") for (int m = 0; m < 4; ++m) _Pragma("unroll") for (int n = 0; n < 2; ++n) _Pragma("unroll") for (int k = 0; k < 2; ++k) \
;         acc[ai][bj][m][n] = __builtin_amdgcn_mfma_f32_16x16x32_bf16(Bt[n][k], At[m][k], acc[ai][bj][m][n], 0, 0, 0); __builtin_amdgcn_s_setprio(0); } while (0)
; #define PG8_WAIT_V(n) asm volatile("s_waitcnt vmcnt(" #n ")" ::: "memory")
; #define PG8_WAIT_L(n) asm volatile("s_waitcnt lgkmcnt(" #n ")" ::: "memory")
; #define PG8_BAR __builtin_amdgcn_s_barrier()
; #define PG8_SCHED __builtin_amdgcn_sched_barrier(0)
; template <class Epi, class Sched, bool ALIGN_EPI = false, bool SP2 = false>
; __device__ __forceinline__ void gemm_phase(PG8_LAS unsigned char* lds, const Gemm g, const Sched& S, const Epi& E) {
;     ...
;             PG8_WAIT_V(8); PG8_WAIT_L(0); PG8_BAR; PG8_MMA(1, 0, At, B0); PG8_MMA(1, 1, At, B1); PG8_BAR; PG8_SCHED;
;             PG8_LDB(B0, 1, 0); PG8_LDB(B1, 1, 1); PG8_SCHED; PG8_LDA(At, 1, 0); PG8_STAGE(PG8_SA(0, 1), a2 + hstep, voffA);
;             PG8_WAIT_V(8); PG8_WAIT_L(0); PG8_BAR; PG8_MMA(0, 0, At, B0); PG8_MMA(0, 1, At, B1); PG8_BAR; PG8_SCHED;
	s_setprio 1
	s_waitcnt lgkmcnt(7)
	v_mfma_f32_16x16x32_bf16 v[62:65], v[154:157], v[186:189], v[62:65]
	v_mfma_f32_16x16x32_bf16 v[62:65], v[158:161], v[190:193], v[62:65]
	s_waitcnt lgkmcnt(5)
	v_mfma_f32_16x16x32_bf16 v[58:61], v[166:169], v[190:193], v[58:61]
	v_mfma_f32_16x16x32_bf16 v[58:61], v[162:165], v[186:189], v[58:61]
	s_waitcnt lgkmcnt(3)
	v_mfma_f32_16x16x32_bf16 v[42:45], v[162:165], v[194:197], v[42:45]
	v_mfma_f32_16x16x32_bf16 v[42:45], v[166:169], v[198:201], v[42:45]
	s_waitcnt lgkmcnt(1)
	v_mfma_f32_16x16x32_bf16 v[46:49], v[158:161], v[198:201], v[46:49]
	v_mfma_f32_16x16x32_bf16 v[46:49], v[154:157], v[194:197], v[46:49]
	v_mfma_f32_16x16x32_bf16 v[30:33], v[154:157], v[202:205], v[30:33]
	v_mfma_f32_16x16x32_bf16 v[30:33], v[158:161], v[206:209], v[30:33]
	v_mfma_f32_16x16x32_bf16 v[26:29], v[166:169], v[206:209], v[26:29]
	v_mfma_f32_16x16x32_bf16 v[26:29], v[162:165], v[202:205], v[26:29]
	v_mfma_f32_16x16x32_bf16 v[10:13], v[162:165], v[252:255], v[10:13]
	v_mfma_f32_16x16x32_bf16 v[10:13], v[166:169], v[214:217], v[10:13]
	s_waitcnt lgkmcnt(0)
	v_mfma_f32_16x16x32_bf16 v[14:17], v[158:161], v[214:217], v[14:17]
	v_mfma_f32_16x16x32_bf16 v[14:17], v[154:157], v[252:255], v[14:17]
	s_setprio 0
	s_setprio 1
	v_mfma_f32_16x16x32_bf16 v[54:57], v[170:173], v[186:189], v[54:57]
	v_mfma_f32_16x16x32_bf16 v[54:57], v[174:177], v[190:193], v[54:57]
	v_mfma_f32_16x16x32_bf16 v[50:53], v[182:185], v[190:193], v[50:53]
	v_mfma_f32_16x16x32_bf16 v[50:53], v[178:181], v[186:189], v[50:53]
	v_mfma_f32_16x16x32_bf16 v[34:37], v[178:181], v[194:197], v[34:37]
	v_mfma_f32_16x16x32_bf16 v[34:37], v[182:185], v[198:201], v[34:37]
	v_mfma_f32_16x16x32_bf16 v[38:41], v[174:177], v[198:201], v[38:41]
	v_mfma_f32_16x16x32_bf16 v[38:41], v[170:173], v[194:197], v[38:41]
	v_mfma_f32_16x16x32_bf16 v[22:25], v[170:173], v[202:205], v[22:25]
	v_mfma_f32_16x16x32_bf16 v[22:25], v[174:177], v[206:209], v[22:25]
	v_mfma_f32_16x16x32_bf16 v[18:21], v[182:185], v[206:209], v[18:21]
	v_mfma_f32_16x16x32_bf16 v[18:21], v[178:181], v[202:205], v[18:21]
	v_mfma_f32_16x16x32_bf16 v[2:5], v[178:181], v[252:255], v[2:5]
	v_mfma_f32_16x16x32_bf16 v[2:5], v[182:185], v[214:217], v[2:5]
	v_mfma_f32_16x16x32_bf16 v[6:9], v[174:177], v[214:217], v[6:9]
	s_setprio 2
	s_barrier
	v_mfma_f32_16x16x32_bf16 v[6:9], v[170:173], v[252:255], v[6:9]
	s_setprio 0
	v_add_u32_e32 v138, 0x18000, v151
	ds_read_b128 v[154:157], v138
	ds_read_b128 v[158:161], v138 offset:1024
	ds_read_b128 v[162:165], v138 offset:2048
	ds_read_b128 v[166:169], v138 offset:3072
	v_add_u32_e32 v138, 0x1c000, v151
	ds_read_b128 v[248:251], v138
	ds_read_b128 v[174:177], v138 offset:1024
	ds_read_b128 v[178:181], v138 offset:2048
	ds_read_b128 v[182:185], v138 offset:3072
	ds_read_b128 v[186:189], v152 offset:32768
	ds_read_b128 v[190:193], v152 offset:33792
	ds_read_b128 v[194:197], v152 offset:34816
	ds_read_b128 v[198:201], v152 offset:35840
	ds_read_b128 v[202:205], v152 offset:36864
	ds_read_b128 v[206:209], v152 offset:37888
	ds_read_b128 v[210:213], v152 offset:38912
	ds_read_b128 v[214:217], v152 offset:39936
	s_add_u32 s60, s84, 0x100000
	s_addc_u32 s61, s85, 0
	s_mov_b32 m0, s88
	s_nop 0
	global_load_lds_dwordx4 v141, s[60:61]
	s_nop 0
	s_mov_b32 m0, s89
	s_nop 0
	global_load_lds_dwordx4 v143, s[60:61]
	s_waitcnt vmcnt(8)
	s_waitcnt lgkmcnt(0)
	s_barrier
	s_setprio 1
	s_waitcnt lgkmcnt(7)
	v_mfma_f32_16x16x32_bf16 v[126:129], v[154:157], v[186:189], v[126:129]
	v_mfma_f32_16x16x32_bf16 v[126:129], v[158:161], v[190:193], v[126:129]
	s_waitcnt lgkmcnt(5)
	v_mfma_f32_16x16x32_bf16 v[122:125], v[166:169], v[190:193], v[122:125]
	v_mfma_f32_16x16x32_bf16 v[122:125], v[162:165], v[186:189], v[122:125]
	s_waitcnt lgkmcnt(3)
	v_mfma_f32_16x16x32_bf16 v[106:109], v[162:165], v[194:197], v[106:109]
	v_mfma_f32_16x16x32_bf16 v[106:109], v[166:169], v[198:201], v[106:109]
	s_waitcnt lgkmcnt(1)
	v_mfma_f32_16x16x32_bf16 v[110:113], v[158:161], v[198:201], v[110:113]
	v_mfma_f32_16x16x32_bf16 v[110:113], v[154:157], v[194:197], v[110:113]
	v_mfma_f32_16x16x32_bf16 v[94:97], v[154:157], v[202:205], v[94:97]
	v_mfma_f32_16x16x32_bf16 v[94:97], v[158:161], v[206:209], v[94:97]
	v_mfma_f32_16x16x32_bf16 v[90:93], v[166:169], v[206:209], v[90:93]
	v_mfma_f32_16x16x32_bf16 v[90:93], v[162:165], v[202:205], v[90:93]
	v_mfma_f32_16x16x32_bf16 v[74:77], v[162:165], v[210:213], v[74:77]
	v_mfma_f32_16x16x32_bf16 v[74:77], v[166:169], v[214:217], v[74:77]
	s_waitcnt lgkmcnt(0)
	v_mfma_f32_16x16x32_bf16 v[78:81], v[158:161], v[214:217], v[78:81]
	v_mfma_f32_16x16x32_bf16 v[78:81], v[154:157], v[210:213], v[78:81]
	s_setprio 0
	s_setprio 1
	v_mfma_f32_16x16x32_bf16 v[118:121], v[248:251], v[186:189], v[118:121]
	v_mfma_f32_16x16x32_bf16 v[118:121], v[174:177], v[190:193], v[118:121]
	v_mfma_f32_16x16x32_bf16 v[114:117], v[182:185], v[190:193], v[114:117]
	v_mfma_f32_16x16x32_bf16 v[114:117], v[178:181], v[186:189], v[114:117]
	v_mfma_f32_16x16x32_bf16 v[98:101], v[178:181], v[194:197], v[98:101]
	v_mfma_f32_16x16x32_bf16 v[98:101], v[182:185], v[198:201], v[98:101]
	v_mfma_f32_16x16x32_bf16 v[102:105], v[174:177], v[198:201], v[102:105]
	v_mfma_f32_16x16x32_bf16 v[102:105], v[248:251], v[194:197], v[102:105]
	v_mfma_f32_16x16x32_bf16 v[86:89], v[248:251], v[202:205], v[86:89]
	v_mfma_f32_16x16x32_bf16 v[86:89], v[174:177], v[206:209], v[86:89]
	v_mfma_f32_16x16x32_bf16 v[82:85], v[182:185], v[206:209], v[82:85]
	v_mfma_f32_16x16x32_bf16 v[82:85], v[178:181], v[202:205], v[82:85]
	v_mfma_f32_16x16x32_bf16 v[66:69], v[178:181], v[210:213], v[66:69]
	v_mfma_f32_16x16x32_bf16 v[66:69], v[182:185], v[214:217], v[66:69]
	v_mfma_f32_16x16x32_bf16 v[70:73], v[174:177], v[214:217], v[70:73]
	s_setprio 2
	s_barrier
; #define PG8_STAGE(bufoff, gbase, voff) do { _Pragma("unroll") for (int _i = 0; _i < 2; ++_i) \
;         asm volatile("s_mov_b32 m0, %2\n\ts_nop 0\n\tglobal_load_lds_dwordx4 %0, %1" :: "v"((voff)[_i]), "s"((const char*)(gbase)), "s"(ldsbase + (unsigned)(bufoff) + ldsw + (unsigned)_i * 8192u) : "memory", "m0"); } while (0)
; #define PG8_LDA(dst, b, h) do { _Pragma("unroll") for (int m = 0; m < 4; ++m) _Pragma("unroll") for (int k = 0; k < 2; ++k) dst[m][k] = *(const PG8_LAS bf16x8*)(lds + PG8_SA(b, h) + aoff + m * 2048 + k * 1024); } while (0)
; #define PG8_MMA(ai, bj, At, Bt) do { __builtin_amdgcn_s_setprio(1); _Pragma("unroll") for (int m = 0; m < 4; ++m) _Pragma("unroll") for (int n = 0; n < 2; ++n) _Pragma("unroll") for (int k = 0; k < 2; ++k) \
;         acc[ai][bj][m][n] = __builtin_amdgcn_mfma_f32_16x16x32_bf16(Bt[n][k], At[m][k], acc[ai][bj][m][n], 0, 0, 0); __builtin_amdgcn_s_setprio(0); } while (0)
; #define PG8_WAIT_V(n) asm volatile("s_waitcnt vmcnt(" #n ")" ::: "memory")
; #define PG8_WAIT_L(n) asm volatile("s_waitcnt lgkmcnt(" #n ")" ::: "memory")
; #define PG8_BAR __builtin_amdgcn_s_barrier()
; #define PG8_SCHED __builtin_amdgcn_sched_barrier(0)
; template <class Epi, class Sched, bool ALIGN_EPI = false, bool SP2 = false>
; __device__ __forceinline__ void gemm_phase(PG8_LAS unsigned char* lds, const Gemm g, const Sched& S, const Epi& E) {
;     ...
;             PG8_WAIT_V(8); PG8_WAIT_L(0); PG8_BAR; PG8_MMA(0, 0, At, B0); PG8_MMA(0, 1, At, B1); PG8_BAR; PG8_SCHED;
;             PG8_LDA(At, 1, 1); PG8_STAGE(PG8_SB(1, 0), b3, voffB); PG8_STAGE(PG8_SB(1, 1), b3 + hstep, voffB); PG8_STAGE(PG8_SA(1, 0), a3, voffA);
;             PG8_WAIT_V(8); PG8_WAIT_L(0); PG8_BAR; PG8_MMA(1, 0, At, B0); PG8_MMA(1, 1, At, B1); PG8_BAR; PG8_SCHED;
	v_mfma_f32_16x16x32_bf16 v[70:73], v[248:251], v[210:213], v[70:73]
	s_setprio 0
	ds_read_b128 v[186:189], v152 offset:49152
	ds_read_b128 v[190:193], v152 offset:50176
	ds_read_b128 v[194:197], v152 offset:51200
	ds_read_b128 v[198:201], v152 offset:52224
	ds_read_b128 v[202:205], v152 offset:53248
	ds_read_b128 v[206:209], v152 offset:54272
	ds_read_b128 v[252:255], v152 offset:55296
	ds_read_b128 v[214:217], v152 offset:56320
	s_mov_b32 m0, s90
	s_nop 0
	global_load_lds_dwordx4 v142, s[76:77]
	s_add_u32 s60, s62, 0x100080
	s_mov_b32 m0, s91
	s_nop 0
	global_load_lds_dwordx4 v144, s[76:77]
	s_addc_u32 s61, s63, 0
	s_mov_b32 m0, s95
	s_nop 0
	global_load_lds_dwordx4 v142, s[60:61]
	s_nop 0
	s_mov_b32 m0, s96
	s_nop 0
	global_load_lds_dwordx4 v144, s[60:61]
	s_nop 0
	s_mov_b32 m0, s92
	s_nop 0
	global_load_lds_dwordx4 v141, s[66:67]
	s_nop 0
	s_mov_b32 m0, s94
	s_nop 0
	global_load_lds_dwordx4 v143, s[66:67]
	s_waitcnt vmcnt(8)
	s_waitcnt lgkmcnt(0)
	s_barrier
	s_setprio 1
	s_waitcnt lgkmcnt(7)
	v_mfma_f32_16x16x32_bf16 v[62:65], v[154:157], v[186:189], v[62:65]
	v_mfma_f32_16x16x32_bf16 v[62:65], v[158:161], v[190:193], v[62:65]
	s_waitcnt lgkmcnt(5)
	v_mfma_f32_16x16x32_bf16 v[58:61], v[166:169], v[190:193], v[58:61]
	v_mfma_f32_16x16x32_bf16 v[58:61], v[162:165], v[186:189], v[58:61]
	s_waitcnt lgkmcnt(3)
	v_mfma_f32_16x16x32_bf16 v[42:45], v[162:165], v[194:197], v[42:45]
	v_mfma_f32_16x16x32_bf16 v[42:45], v[166:169], v[198:201], v[42:45]
	s_waitcnt lgkmcnt(1)
	v_mfma_f32_16x16x32_bf16 v[46:49], v[158:161], v[198:201], v[46:49]
	v_mfma_f32_16x16x32_bf16 v[46:49], v[154:157], v[194:197], v[46:49]
	v_mfma_f32_16x16x32_bf16 v[30:33], v[154:157], v[202:205], v[30:33]
	v_mfma_f32_16x16x32_bf16 v[30:33], v[158:161], v[206:209], v[30:33]
	v_mfma_f32_16x16x32_bf16 v[26:29], v[166:169], v[206:209], v[26:29]
	v_mfma_f32_16x16x32_bf16 v[26:29], v[162:165], v[202:205], v[26:29]
	v_mfma_f32_16x16x32_bf16 v[10:13], v[162:165], v[252:255], v[10:13]
	v_mfma_f32_16x16x32_bf16 v[10:13], v[166:169], v[214:217], v[10:13]
	s_waitcnt lgkmcnt(0)
	v_mfma_f32_16x16x32_bf16 v[14:17], v[158:161], v[214:217], v[14:17]
	v_mfma_f32_16x16x32_bf16 v[14:17], v[154:157], v[252:255], v[14:17]
	s_setprio 0
	s_setprio 1
	v_mfma_f32_16x16x32_bf16 v[54:57], v[248:251], v[186:189], v[54:57]
	v_mfma_f32_16x16x32_bf16 v[54:57], v[174:177], v[190:193], v[54:57]
	v_mfma_f32_16x16x32_bf16 v[50:53], v[182:185], v[190:193], v[50:53]
	v_mfma_f32_16x16x32_bf16 v[50:53], v[178:181], v[186:189], v[50:53]
	v_mfma_f32_16x16x32_bf16 v[34:37], v[178:181], v[194:197], v[34:37]
	v_mfma_f32_16x16x32_bf16 v[34:37], v[182:185], v[198:201], v[34:37]
	v_mfma_f32_16x16x32_bf16 v[38:41], v[174:177], v[198:201], v[38:41]
	v_mfma_f32_16x16x32_bf16 v[38:41], v[248:251], v[194:197], v[38:41]
	v_mfma_f32_16x16x32_bf16 v[22:25], v[248:251], v[202:205], v[22:25]
	v_mfma_f32_16x16x32_bf16 v[22:25], v[174:177], v[206:209], v[22:25]
	v_mfma_f32_16x16x32_bf16 v[18:21], v[182:185], v[206:209], v[18:21]
	v_mfma_f32_16x16x32_bf16 v[18:21], v[178:181], v[202:205], v[18:21]
	v_mfma_f32_16x16x32_bf16 v[2:5], v[178:181], v[252:255], v[2:5]
	v_mfma_f32_16x16x32_bf16 v[2:5], v[182:185], v[214:217], v[2:5]
	v_mfma_f32_16x16x32_bf16 v[6:9], v[174:177], v[214:217], v[6:9]
	s_setprio 2
	s_barrier
	v_mfma_f32_16x16x32_bf16 v[6:9], v[248:251], v[252:255], v[6:9]
	s_setprio 0
	s_add_i32 s58, s58, 2
	s_add_u32 s56, s56, 0x100
	s_addc_u32 s57, s57, 0
	s_cmp_gt_u32 s58, 61
	s_cbranch_scc1 .LBB0_316
	s_mov_b64 s[82:83], s[8:9]
	s_branch .LBB0_320

; #define PG8_STAGE(bufoff, gbase, voff) do { _Pragma("unroll") for (int _i = 0; _i < 2; ++_i) \
;         asm volatile("s_mov_b32 m0, %2\n\ts_nop 0\n\tglobal_load_lds_dwordx4 %0, %1" :: "v"((voff)[_i]), "s"((const char*)(gbase)), "s"(ldsbase + (unsigned)(bufoff) + ldsw + (unsigned)_i * 8192u) : "memory", "m0"); } while (0)
; #define PG8_LDA(dst, b, h) do { _Pragma("unroll") for (int m = 0; m < 4; ++m) _Pragma("unroll") for (int k = 0; k < 2; ++k) dst[m][k] = *(const PG8_LAS bf16x8*)(lds + PG8_SA(b, h) + aoff + m * 2048 + k * 1024); } while (0)
; #define PG8_LDB(dst, b, h) do { _Pragma("unroll") for (int n = 0; n < 2; ++n) _Pragma("unroll") for (int k = 0; k < 2; ++k) dst[n][k] = *(const PG8_LAS bf16x8*)(lds + PG8_SB(b, h) + boff + n * 2048 + k * 1024); } while (0)
; #define PG8_MMA(ai, bj, At, Bt) do { __builtin_amdgcn_s_setprio(1); _Pragma("unroll") for (int m = 0; m < 4; ++m) _Pragma("unroll") for (int n = 0; n < 2; ++n) _Pragma("unroll") for (int k = 0; k < 2; ++k) \
;         acc[ai][bj][m][n] = __builtin_amdgcn_mfma_f32_16x16x32_bf16(Bt[n][k], At[m][k], acc[ai][bj][m][n], 0, 0, 0); __builtin_amdgcn_s_setprio(0); } while (0)
; template <class Epi, class Sched, bool ALIGN_EPI = false, bool SP2 = false>
; __device__ __forceinline__ void gemm_phase(PG8_LAS unsigned char* lds, const Gemm g, const Sched& S, const Epi& E) {
;     ...
;             const bool last = (t == nt - 2);
;             const char* a1 = cA + (size_t)(t + 1) * kstep;
;             const char* a2 = last ? nA : cA + (size_t)(t + 2) * kstep; const char* b2 = last ? nB : cB + (size_t)(t + 2) * kstep;
;             const char* a3 = a2 + kstep; const char* b3 = b2 + kstep;
;             if (last && has_next) S.a_ready(nxt);
;             if constexpr (epi_has_mid<Epi>::value) { if (t == Epi::MID_T) E.mid(acc, cur, wr, wc, fr, fq); }
;             if constexpr (SP2) {
;             PG8_LDB(B0, 0, 0); PG8_LDB(B1, 0, 1); PG8_SCHED; PG8_LDA(At, 0, 0); PG8_STAGE(PG8_SA(1, 1), a1 + hstep, voffA);
;             PG8_WAIT_V(8); PG8_WAIT_L(0); PG8_BAR; PG8_MMA(0, 0, At, B0); PG8_MMA(0, 1, At, B1); PG8_BAR; PG8_SCHED;
;             PG8_LDA(At, 0, 1); PG8_STAGE(PG8_SB(0, 0), b2, voffB); PG8_STAGE(PG8_SB(0, 1), b2 + hstep, voffB); PG8_STAGE(PG8_SA(0, 0), a2, voffA);
;             PG8_WAIT_V(8); PG8_WAIT_L(0); PG8_BAR; PG8_MMA(1, 0, At, B0); PG8_MMA(1, 1, At, B1); PG8_BAR; PG8_SCHED;
.LBB0_698:
	ds_read_b128 v[134:137], v145
	ds_read_b128 v[152:155], v145 offset:1024
	ds_read_b128 v[156:159], v145 offset:2048
	ds_read_b128 v[160:163], v145 offset:3072
	ds_read_b128 v[164:167], v146
	ds_read_b128 v[168:171], v146 offset:1024
	ds_read_b128 v[172:175], v146 offset:2048
	ds_read_b128 v[176:179], v146 offset:3072
	s_cmp_eq_u32 s69, 60
	s_cselect_b32 s48, s41, s53
	s_cselect_b32 s49, s19, s58
	s_cselect_b32 s46, s52, s59
	s_cselect_b32 s47, s17, s68
	s_add_u32 s44, s48, 0x80
	s_addc_u32 s45, s49, 0
	ds_read_b128 v[180:183], v147
	ds_read_b128 v[184:187], v147 offset:1024
	ds_read_b128 v[188:191], v147 offset:2048
	ds_read_b128 v[192:195], v147 offset:3072
	ds_read_b128 v[196:199], v147 offset:4096
	ds_read_b128 v[200:203], v147 offset:5120
	ds_read_b128 v[204:207], v147 offset:6144
	ds_read_b128 v[208:211], v147 offset:7168
	s_mov_b32 m0, s67
	s_nop 0
	global_load_lds_dwordx4 v1, s[42:43]
	s_nop 0
	s_mov_b32 m0, s74
	s_nop 0
	global_load_lds_dwordx4 v141, s[42:43]
	s_waitcnt vmcnt(8)
	s_waitcnt lgkmcnt(0)
	s_barrier
	s_setprio 1
	s_waitcnt lgkmcnt(7)
	v_mfma_f32_16x16x32_bf16 v[126:129], v[134:137], v[180:183], v[126:129]
	v_mfma_f32_16x16x32_bf16 v[126:129], v[152:155], v[184:187], v[126:129]
	s_waitcnt lgkmcnt(5)
	v_mfma_f32_16x16x32_bf16 v[122:125], v[160:163], v[184:187], v[122:125]
	v_mfma_f32_16x16x32_bf16 v[122:125], v[156:159], v[180:183], v[122:125]
	s_waitcnt lgkmcnt(3)
	v_mfma_f32_16x16x32_bf16 v[106:109], v[156:159], v[188:191], v[106:109]
	v_mfma_f32_16x16x32_bf16 v[106:109], v[160:163], v[192:195], v[106:109]
	s_waitcnt lgkmcnt(1)
	v_mfma_f32_16x16x32_bf16 v[110:113], v[152:155], v[192:195], v[110:113]
	v_mfma_f32_16x16x32_bf16 v[110:113], v[134:137], v[188:191], v[110:113]
	v_mfma_f32_16x16x32_bf16 v[94:97], v[134:137], v[196:199], v[94:97]
	v_mfma_f32_16x16x32_bf16 v[94:97], v[152:155], v[200:203], v[94:97]
	v_mfma_f32_16x16x32_bf16 v[90:93], v[160:163], v[200:203], v[90:93]
	v_mfma_f32_16x16x32_bf16 v[90:93], v[156:159], v[196:199], v[90:93]
	v_mfma_f32_16x16x32_bf16 v[74:77], v[156:159], v[204:207], v[74:77]
	v_mfma_f32_16x16x32_bf16 v[74:77], v[160:163], v[208:211], v[74:77]
	s_waitcnt lgkmcnt(0)
	v_mfma_f32_16x16x32_bf16 v[78:81], v[152:155], v[208:211], v[78:81]
	v_mfma_f32_16x16x32_bf16 v[78:81], v[134:137], v[204:207], v[78:81]
	s_setprio 0
	s_setprio 1
	v_mfma_f32_16x16x32_bf16 v[118:121], v[164:167], v[180:183], v[118:121]
	v_mfma_f32_16x16x32_bf16 v[118:121], v[168:171], v[184:187], v[118:121]
	v_mfma_f32_16x16x32_bf16 v[114:117], v[176:179], v[184:187], v[114:117]
	v_mfma_f32_16x16x32_bf16 v[114:117], v[172:175], v[180:183], v[114:117]
	v_mfma_f32_16x16x32_bf16 v[98:101], v[172:175], v[188:191], v[98:101]
	v_mfma_f32_16x16x32_bf16 v[98:101], v[176:179], v[192:195], v[98:101]
	v_mfma_f32_16x16x32_bf16 v[102:105], v[168:171], v[192:195], v[102:105]
	v_mfma_f32_16x16x32_bf16 v[102:105], v[164:167], v[188:191], v[102:105]
	v_mfma_f32_16x16x32_bf16 v[86:89], v[164:167], v[196:199], v[86:89]
	v_mfma_f32_16x16x32_bf16 v[86:89], v[168:171], v[200:203], v[86:89]
	v_mfma_f32_16x16x32_bf16 v[82:85], v[176:179], v[200:203], v[82:85]
	v_mfma_f32_16x16x32_bf16 v[82:85], v[172:175], v[196:199], v[82:85]
	v_mfma_f32_16x16x32_bf16 v[66:69], v[172:175], v[204:207], v[66:69]
	v_mfma_f32_16x16x32_bf16 v[66:69], v[176:179], v[208:211], v[66:69]
	v_mfma_f32_16x16x32_bf16 v[70:73], v[168:171], v[208:211], v[70:73]
	s_setprio 2
	s_barrier
	v_mfma_f32_16x16x32_bf16 v[70:73], v[164:167], v[204:207], v[70:73]
	s_setprio 0
	ds_read_b128 v[180:183], v147 offset:16384
	ds_read_b128 v[184:187], v147 offset:17408
	ds_read_b128 v[188:191], v147 offset:18432
	ds_read_b128 v[192:195], v147 offset:19456
	ds_read_b128 v[196:199], v147 offset:20480
	ds_read_b128 v[200:203], v147 offset:21504
	ds_read_b128 v[252:255], v147 offset:22528
	ds_read_b128 v[208:211], v147 offset:23552
	s_mov_b32 m0, s35
	s_nop 0
	global_load_lds_dwordx4 v140, s[46:47]
	s_add_u32 s70, s46, 0x100000
	s_mov_b32 m0, s50
	s_nop 0
	global_load_lds_dwordx4 v142, s[46:47]
	s_addc_u32 s71, s47, 0
	s_mov_b32 m0, s51
	s_nop 0
	global_load_lds_dwordx4 v140, s[70:71]
	s_nop 0
	s_mov_b32 m0, s54
	s_nop 0
	global_load_lds_dwordx4 v142, s[70:71]
	s_nop 0
	s_mov_b32 m0, s3
	s_nop 0
	global_load_lds_dwordx4 v1, s[48:49]
	s_nop 0
	s_mov_b32 m0, s55
	s_nop 0
	global_load_lds_dwordx4 v141, s[48:49]
	s_waitcnt vmcnt(8)
	s_waitcnt lgkmcnt(0)
	s_barrier
	s_setprio 1
	s_waitcnt lgkmcnt(7)
	v_mfma_f32_16x16x32_bf16 v[62:65], v[134:137], v[180:183], v[62:65]
	v_mfma_f32_16x16x32_bf16 v[62:65], v[152:155], v[184:187], v[62:65]
	s_waitcnt lgkmcnt(5)
	v_mfma_f32_16x16x32_bf16 v[58:61], v[160:163], v[184:187], v[58:61]
	v_mfma_f32_16x16x32_bf16 v[58:61], v[156:159], v[180:183], v[58:61]
	s_waitcnt lgkmcnt(3)
	v_mfma_f32_16x16x32_bf16 v[42:45], v[156:159], v[188:191], v[42:45]
	v_mfma_f32_16x16x32_bf16 v[42:45], v[160:163], v[192:195], v[42:45]
	s_waitcnt lgkmcnt(1)
	v_mfma_f32_16x16x32_bf16 v[46:49], v[152:155], v[192:195], v[46:49]
	v_mfma_f32_16x16x32_bf16 v[46:49], v[134:137], v[188:191], v[46:49]
	v_mfma_f32_16x16x32_bf16 v[30:33], v[134:137], v[196:199], v[30:33]
	v_mfma_f32_16x16x32_bf16 v[30:33], v[152:155], v[200:203], v[30:33]
	v_mfma_f32_16x16x32_bf16 v[26:29], v[160:163], v[200:203], v[26:29]
	v_mfma_f32_16x16x32_bf16 v[26:29], v[156:159], v[196:199], v[26:29]
	v_mfma_f32_16x16x32_bf16 v[10:13], v[156:159], v[252:255], v[10:13]
	v_mfma_f32_16x16x32_bf16 v[10:13], v[160:163], v[208:211], v[10:13]
	s_waitcnt lgkmcnt(0)
	v_mfma_f32_16x16x32_bf16 v[14:17], v[152:155], v[208:211], v[14:17]
	v_mfma_f32_16x16x32_bf16 v[14:17], v[134:137], v[252:255], v[14:17]
	s_setprio 0
	s_setprio 1
	v_mfma_f32_16x16x32_bf16 v[54:57], v[164:167], v[180:183], v[54:57]
	v_mfma_f32_16x16x32_bf16 v[54:57], v[168:171], v[184:187], v[54:57]
	v_mfma_f32_16x16x32_bf16 v[50:53], v[176:179], v[184:187], v[50:53]
	v_mfma_f32_16x16x32_bf16 v[50:53], v[172:175], v[180:183], v[50:53]
	v_mfma_f32_16x16x32_bf16 v[34:37], v[172:175], v[188:191], v[34:37]
	v_mfma_f32_16x16x32_bf16 v[34:37], v[176:179], v[192:195], v[34:37]
	v_mfma_f32_16x16x32_bf16 v[38:41], v[168:171], v[192:195], v[38:41]
	v_mfma_f32_16x16x32_bf16 v[38:41], v[164:167], v[188:191], v[38:41]
	v_mfma_f32_16x16x32_bf16 v[22:25], v[164:167], v[196:199], v[22:25]
	v_mfma_f32_16x16x32_bf16 v[22:25], v[168:171], v[200:203], v[22:25]
	v_mfma_f32_16x16x32_bf16 v[18:21], v[176:179], v[200:203], v[18:21]
	v_mfma_f32_16x16x32_bf16 v[18:21], v[172:175], v[196:199], v[18:21]
	v_mfma_f32_16x16x32_bf16 v[2:5], v[172:175], v[252:255], v[2:5]
	v_mfma_f32_16x16x32_bf16 v[2:5], v[176:179], v[208:211], v[2:5]
	v_mfma_f32_16x16x32_bf16 v[6:9], v[168:171], v[208:211], v[6:9]
	s_setprio 2
	s_barrier
; #define PG8_STAGE(bufoff, gbase, voff) do { _Pragma("unroll") for (int _i = 0; _i < 2; ++_i) \
;         asm volatile("s_mov_b32 m0, %2\n\ts_nop 0\n\tglobal_load_lds_dwordx4 %0, %1" :: "v"((voff)[_i]), "s"((const char*)(gbase)), "s"(ldsbase + (unsigned)(bufoff) + ldsw + (unsigned)_i * 8192u) : "memory", "m0"); } while (0)
; #define PG8_LDA(dst, b, h) do { _Pragma("unroll") for (int m = 0; m < 4; ++m) _Pragma("unroll") for (int k = 0; k < 2; ++k) dst[m][k] = *(const PG8_LAS bf16x8*)(lds + PG8_SA(b, h) + aoff + m * 2048 + k * 1024); } while (0)
; #define PG8_LDB(dst, b, h) do { _Pragma("unroll") for (int n = 0; n < 2; ++n) _Pragma("unroll") for (int k = 0; k < 2; ++k) dst[n][k] = *(const PG8_LAS bf16x8*)(lds + PG8_SB(b, h) + boff + n * 2048 + k * 1024); } while (0)
; #define PG8_MMA(ai, bj, At, Bt) do { __builtin_amdgcn_s_setprio(1); _Pragma("unroll") for (int m = 0; m < 4; ++m) _Pragma("unroll") for (int n = 0; n < 2; ++n) _Pragma("unroll") for (int k = 0; k < 2; ++k) \
;         acc[ai][bj][m][n] = __builtin_amdgcn_mfma_f32_16x16x32_bf16(Bt[n][k], At[m][k], acc[ai][bj][m][n], 0, 0, 0); __builtin_amdgcn_s_setprio(0); } while (0)
; #define PG8_WAIT_V(n) asm volatile("s_waitcnt vmcnt(" #n ")" ::: "memory")
; #define PG8_WAIT_L(n) asm volatile("s_waitcnt lgkmcnt(" #n ")" ::: "memory")
; #define PG8_BAR __builtin_amdgcn_s_barrier()
; #define PG8_SCHED __builtin_amdgcn_sched_barrier(0)
; template <class Epi, class Sched, bool ALIGN_EPI = false, bool SP2 = false>
; __device__ __forceinline__ void gemm_phase(PG8_LAS unsigned char* lds, const Gemm g, const Sched& S, const Epi& E) {
;     ...
;             PG8_WAIT_V(8); PG8_WAIT_L(0); PG8_BAR; PG8_MMA(1, 0, At, B0); PG8_MMA(1, 1, At, B1); PG8_BAR; PG8_SCHED;
;             PG8_LDB(B0, 1, 0); PG8_LDB(B1, 1, 1); PG8_SCHED; PG8_LDA(At, 1, 0); PG8_STAGE(PG8_SA(0, 1), a2 + hstep, voffA);
;             PG8_WAIT_V(8); PG8_WAIT_L(0); PG8_BAR; PG8_MMA(0, 0, At, B0); PG8_MMA(0, 1, At, B1); PG8_BAR; PG8_SCHED;
	v_mfma_f32_16x16x32_bf16 v[6:9], v[164:167], v[252:255], v[6:9]
	s_setprio 0
	ds_read_b128 v[134:137], v148
	ds_read_b128 v[152:155], v148 offset:1024
	ds_read_b128 v[156:159], v148 offset:2048
	ds_read_b128 v[160:163], v148 offset:3072
	ds_read_b128 v[248:251], v149
	ds_read_b128 v[168:171], v149 offset:1024
	ds_read_b128 v[172:175], v149 offset:2048
	ds_read_b128 v[176:179], v149 offset:3072
	ds_read_b128 v[180:183], v147 offset:32768
	ds_read_b128 v[184:187], v147 offset:33792
	ds_read_b128 v[188:191], v147 offset:34816
	ds_read_b128 v[192:195], v147 offset:35840
	ds_read_b128 v[196:199], v147 offset:36864
	ds_read_b128 v[200:203], v147 offset:37888
	ds_read_b128 v[204:207], v147 offset:38912
	ds_read_b128 v[208:211], v147 offset:39936
	s_add_u32 s48, s48, 0x100000
	s_addc_u32 s49, s49, 0
	s_mov_b32 m0, s56
	s_nop 0
	global_load_lds_dwordx4 v1, s[48:49]
	s_nop 0
	s_mov_b32 m0, s57
	s_nop 0
	global_load_lds_dwordx4 v141, s[48:49]
	s_waitcnt vmcnt(8)
	s_waitcnt lgkmcnt(0)
	s_barrier
	s_setprio 1
	s_waitcnt lgkmcnt(7)
	v_mfma_f32_16x16x32_bf16 v[126:129], v[134:137], v[180:183], v[126:129]
	v_mfma_f32_16x16x32_bf16 v[126:129], v[152:155], v[184:187], v[126:129]
	s_waitcnt lgkmcnt(5)
	v_mfma_f32_16x16x32_bf16 v[122:125], v[160:163], v[184:187], v[122:125]
	v_mfma_f32_16x16x32_bf16 v[122:125], v[156:159], v[180:183], v[122:125]
	s_waitcnt lgkmcnt(3)
	v_mfma_f32_16x16x32_bf16 v[106:109], v[156:159], v[188:191], v[106:109]
	v_mfma_f32_16x16x32_bf16 v[106:109], v[160:163], v[192:195], v[106:109]
	s_waitcnt lgkmcnt(1)
	v_mfma_f32_16x16x32_bf16 v[110:113], v[152:155], v[192:195], v[110:113]
	v_mfma_f32_16x16x32_bf16 v[110:113], v[134:137], v[188:191], v[110:113]
	v_mfma_f32_16x16x32_bf16 v[94:97], v[134:137], v[196:199], v[94:97]
	v_mfma_f32_16x16x32_bf16 v[94:97], v[152:155], v[200:203], v[94:97]
	v_mfma_f32_16x16x32_bf16 v[90:93], v[160:163], v[200:203], v[90:93]
	v_mfma_f32_16x16x32_bf16 v[90:93], v[156:159], v[196:199], v[90:93]
	v_mfma_f32_16x16x32_bf16 v[74:77], v[156:159], v[204:207], v[74:77]
	v_mfma_f32_16x16x32_bf16 v[74:77], v[160:163], v[208:211], v[74:77]
	s_waitcnt lgkmcnt(0)
	v_mfma_f32_16x16x32_bf16 v[78:81], v[152:155], v[208:211], v[78:81]
	v_mfma_f32_16x16x32_bf16 v[78:81], v[134:137], v[204:207], v[78:81]
	s_setprio 0
	s_setprio 1
	v_mfma_f32_16x16x32_bf16 v[118:121], v[248:251], v[180:183], v[118:121]
	v_mfma_f32_16x16x32_bf16 v[118:121], v[168:171], v[184:187], v[118:121]
	v_mfma_f32_16x16x32_bf16 v[114:117], v[176:179], v[184:187], v[114:117]
	v_mfma_f32_16x16x32_bf16 v[114:117], v[172:175], v[180:183], v[114:117]
	v_mfma_f32_16x16x32_bf16 v[98:101], v[172:175], v[188:191], v[98:101]
	v_mfma_f32_16x16x32_bf16 v[98:101], v[176:179], v[192:195], v[98:101]
	v_mfma_f32_16x16x32_bf16 v[102:105], v[168:171], v[192:195], v[102:105]
	v_mfma_f32_16x16x32_bf16 v[102:105], v[248:251], v[188:191], v[102:105]
	v_mfma_f32_16x16x32_bf16 v[86:89], v[248:251], v[196:199], v[86:89]
	v_mfma_f32_16x16x32_bf16 v[86:89], v[168:171], v[200:203], v[86:89]
	v_mfma_f32_16x16x32_bf16 v[82:85], v[176:179], v[200:203], v[82:85]
	v_mfma_f32_16x16x32_bf16 v[82:85], v[172:175], v[196:199], v[82:85]
	v_mfma_f32_16x16x32_bf16 v[66:69], v[172:175], v[204:207], v[66:69]
	v_mfma_f32_16x16x32_bf16 v[66:69], v[176:179], v[208:211], v[66:69]
	v_mfma_f32_16x16x32_bf16 v[70:73], v[168:171], v[208:211], v[70:73]
	s_setprio 2
	s_barrier
; #define PG8_STAGE(bufoff, gbase, voff) do { _Pragma("unroll") for (int _i = 0; _i < 2; ++_i) \
;         asm volatile("s_mov_b32 m0, %2\n\ts_nop 0\n\tglobal_load_lds_dwordx4 %0, %1" :: "v"((voff)[_i]), "s"((const char*)(gbase)), "s"(ldsbase + (unsigned)(bufoff) + ldsw + (unsigned)_i * 8192u) : "memory", "m0"); } while (0)
; #define PG8_LDA(dst, b, h) do { _Pragma("unroll") for (int m = 0; m < 4; ++m) _Pragma("unroll") for (int k = 0; k < 2; ++k) dst[m][k] = *(const PG8_LAS bf16x8*)(lds + PG8_SA(b, h) + aoff + m * 2048 + k * 1024); } while (0)
; #define PG8_MMA(ai, bj, At, Bt) do { __builtin_amdgcn_s_setprio(1); _Pragma("unroll") for (int m = 0; m < 4; ++m) _Pragma("unroll") for (int n = 0; n < 2; ++n) _Pragma("unroll") for (int k = 0; k < 2; ++k) \
;         acc[ai][bj][m][n] = __builtin_amdgcn_mfma_f32_16x16x32_bf16(Bt[n][k], At[m][k], acc[ai][bj][m][n], 0, 0, 0); __builtin_amdgcn_s_setprio(0); } while (0)
; #define PG8_WAIT_V(n) asm volatile("s_waitcnt vmcnt(" #n ")" ::: "memory")
; #define PG8_WAIT_L(n) asm volatile("s_waitcnt lgkmcnt(" #n ")" ::: "memory")
; #define PG8_BAR __builtin_amdgcn_s_barrier()
; #define PG8_SCHED __builtin_amdgcn_sched_barrier(0)
; template <class Epi, class Sched, bool ALIGN_EPI = false, bool SP2 = false>
; __device__ __forceinline__ void gemm_phase(PG8_LAS unsigned char* lds, const Gemm g, const Sched& S, const Epi& E) {
;     ...
;             PG8_WAIT_V(8); PG8_WAIT_L(0); PG8_BAR; PG8_MMA(0, 0, At, B0); PG8_MMA(0, 1, At, B1); PG8_BAR; PG8_SCHED;
;             PG8_LDA(At, 1, 1); PG8_STAGE(PG8_SB(1, 0), b3, voffB); PG8_STAGE(PG8_SB(1, 1), b3 + hstep, voffB); PG8_STAGE(PG8_SA(1, 0), a3, voffA);
;             PG8_WAIT_V(8); PG8_WAIT_L(0); PG8_BAR; PG8_MMA(1, 0, At, B0); PG8_MMA(1, 1, At, B1); PG8_BAR; PG8_SCHED;
	v_mfma_f32_16x16x32_bf16 v[70:73], v[248:251], v[204:207], v[70:73]
	s_setprio 0
	ds_read_b128 v[180:183], v147 offset:49152
	ds_read_b128 v[184:187], v147 offset:50176
	ds_read_b128 v[188:191], v147 offset:51200
	ds_read_b128 v[192:195], v147 offset:52224
	ds_read_b128 v[196:199], v147 offset:53248
	ds_read_b128 v[200:203], v147 offset:54272
	ds_read_b128 v[252:255], v147 offset:55296
	ds_read_b128 v[208:211], v147 offset:56320
	s_add_u32 s48, s46, 0x80
	s_addc_u32 s49, s47, 0
	s_mov_b32 m0, s61
	s_nop 0
	global_load_lds_dwordx4 v140, s[48:49]
	s_add_u32 s46, s46, 0x100080
	s_mov_b32 m0, s62
	s_nop 0
	global_load_lds_dwordx4 v142, s[48:49]
	s_addc_u32 s47, s47, 0
	s_mov_b32 m0, s65
	s_nop 0
	global_load_lds_dwordx4 v140, s[46:47]
	s_nop 0
	s_mov_b32 m0, s66
	s_nop 0
	global_load_lds_dwordx4 v142, s[46:47]
	s_nop 0
	s_mov_b32 m0, s63
	s_nop 0
	global_load_lds_dwordx4 v1, s[44:45]
	s_nop 0
	s_mov_b32 m0, s64
	s_nop 0
	global_load_lds_dwordx4 v141, s[44:45]
	s_waitcnt vmcnt(8)
	s_waitcnt lgkmcnt(0)
	s_barrier
	s_setprio 1
	s_waitcnt lgkmcnt(7)
	v_mfma_f32_16x16x32_bf16 v[62:65], v[134:137], v[180:183], v[62:65]
	v_mfma_f32_16x16x32_bf16 v[62:65], v[152:155], v[184:187], v[62:65]
	s_waitcnt lgkmcnt(5)
	v_mfma_f32_16x16x32_bf16 v[58:61], v[160:163], v[184:187], v[58:61]
	v_mfma_f32_16x16x32_bf16 v[58:61], v[156:159], v[180:183], v[58:61]
	s_waitcnt lgkmcnt(3)
	v_mfma_f32_16x16x32_bf16 v[42:45], v[156:159], v[188:191], v[42:45]
	v_mfma_f32_16x16x32_bf16 v[42:45], v[160:163], v[192:195], v[42:45]
	s_waitcnt lgkmcnt(1)
	v_mfma_f32_16x16x32_bf16 v[46:49], v[152:155], v[192:195], v[46:49]
	v_mfma_f32_16x16x32_bf16 v[46:49], v[134:137], v[188:191], v[46:49]
	v_mfma_f32_16x16x32_bf16 v[30:33], v[134:137], v[196:199], v[30:33]
	v_mfma_f32_16x16x32_bf16 v[30:33], v[152:155], v[200:203], v[30:33]
	v_mfma_f32_16x16x32_bf16 v[26:29], v[160:163], v[200:203], v[26:29]
	v_mfma_f32_16x16x32_bf16 v[26:29], v[156:159], v[196:199], v[26:29]
	v_mfma_f32_16x16x32_bf16 v[10:13], v[156:159], v[252:255], v[10:13]
	v_mfma_f32_16x16x32_bf16 v[10:13], v[160:163], v[208:211], v[10:13]
	s_waitcnt lgkmcnt(0)
	v_mfma_f32_16x16x32_bf16 v[14:17], v[152:155], v[208:211], v[14:17]
	v_mfma_f32_16x16x32_bf16 v[14:17], v[134:137], v[252:255], v[14:17]
	s_setprio 0
	s_setprio 1
	v_mfma_f32_16x16x32_bf16 v[54:57], v[248:251], v[180:183], v[54:57]
	v_mfma_f32_16x16x32_bf16 v[54:57], v[168:171], v[184:187], v[54:57]
	v_mfma_f32_16x16x32_bf16 v[50:53], v[176:179], v[184:187], v[50:53]
	v_mfma_f32_16x16x32_bf16 v[50:53], v[172:175], v[180:183], v[50:53]
	v_mfma_f32_16x16x32_bf16 v[34:37], v[172:175], v[188:191], v[34:37]
	v_mfma_f32_16x16x32_bf16 v[34:37], v[176:179], v[192:195], v[34:37]
	v_mfma_f32_16x16x32_bf16 v[38:41], v[168:171], v[192:195], v[38:41]
	v_mfma_f32_16x16x32_bf16 v[38:41], v[248:251], v[188:191], v[38:41]
	v_mfma_f32_16x16x32_bf16 v[22:25], v[248:251], v[196:199], v[22:25]
	v_mfma_f32_16x16x32_bf16 v[22:25], v[168:171], v[200:203], v[22:25]
	v_mfma_f32_16x16x32_bf16 v[18:21], v[176:179], v[200:203], v[18:21]
	v_mfma_f32_16x16x32_bf16 v[18:21], v[172:175], v[196:199], v[18:21]
	v_mfma_f32_16x16x32_bf16 v[2:5], v[172:175], v[252:255], v[2:5]
	v_mfma_f32_16x16x32_bf16 v[2:5], v[176:179], v[208:211], v[2:5]
	v_mfma_f32_16x16x32_bf16 v[6:9], v[168:171], v[208:211], v[6:9]
	s_setprio 2
	s_barrier
	v_mfma_f32_16x16x32_bf16 v[6:9], v[248:251], v[252:255], v[6:9]
	s_setprio 0
	s_add_i32 s69, s69, 2
	s_add_u32 s53, s53, 0x100
	s_addc_u32 s58, s58, 0
	s_add_u32 s59, s59, 0x100
	s_addc_u32 s68, s68, 0
	s_add_u32 s42, s42, 0x100
	s_addc_u32 s43, s43, 0
	s_cmp_gt_u32 s69, 61
	s_cbranch_scc0 .LBB0_698
	s_and_b64 vcc, exec, s[14:15]
	s_cbranch_vccz .LBB0_701
	s_barrier

; #define PG8_STAGE(bufoff, gbase, voff) do { _Pragma("unroll") for (int _i = 0; _i < 2; ++_i) \
;         asm volatile("s_mov_b32 m0, %2\n\ts_nop 0\n\tglobal_load_lds_dwordx4 %0, %1" :: "v"((voff)[_i]), "s"((const char*)(gbase)), "s"(ldsbase + (unsigned)(bufoff) + ldsw + (unsigned)_i * 8192u) : "memory", "m0"); } while (0)
; #define PG8_LDA(dst, b, h) do { _Pragma("unroll") for (int m = 0; m < 4; ++m) _Pragma("unroll") for (int k = 0; k < 2; ++k) dst[m][k] = *(const PG8_LAS bf16x8*)(lds + PG8_SA(b, h) + aoff + m * 2048 + k * 1024); } while (0)
; #define PG8_LDB(dst, b, h) do { _Pragma("unroll") for (int n = 0; n < 2; ++n) _Pragma("unroll") for (int k = 0; k < 2; ++k) dst[n][k] = *(const PG8_LAS bf16x8*)(lds + PG8_SB(b, h) + boff + n * 2048 + k * 1024); } while (0)
; #define PG8_MMA(ai, bj, At, Bt) do { __builtin_amdgcn_s_setprio(1); _Pragma("unroll") for (int m = 0; m < 4; ++m) _Pragma("unroll") for (int n = 0; n < 2; ++n) _Pragma("unroll") for (int k = 0; k < 2; ++k) \
;         acc[ai][bj][m][n] = __builtin_amdgcn_mfma_f32_16x16x32_bf16(Bt[n][k], At[m][k], acc[ai][bj][m][n], 0, 0, 0); __builtin_amdgcn_s_setprio(0); } while (0)
; #define PG8_WAIT_V(n) asm volatile("s_waitcnt vmcnt(" #n ")" ::: "memory")
; #define PG8_BAR __builtin_amdgcn_s_barrier()
; template <class Epi, class Sched, bool ALIGN_EPI = false, bool SP2 = false>
; __device__ __forceinline__ void gemm_phase(PG8_LAS unsigned char* lds, const Gemm g, const Sched& S, const Epi& E) {
;     ...
;             const bool last = (t == nt - 2);
;             const char* a1 = cA + (size_t)(t + 1) * kstep;
;             const char* a2 = last ? nA : cA + (size_t)(t + 2) * kstep; const char* b2 = last ? nB : cB + (size_t)(t + 2) * kstep;
;             const char* a3 = a2 + kstep; const char* b3 = b2 + kstep;
;             if (last && has_next) S.a_ready(nxt);
;             if constexpr (epi_has_mid<Epi>::value) { if (t == Epi::MID_T) E.mid(acc, cur, wr, wc, fr, fq); }
;             if constexpr (SP2) {
;             PG8_LDB(B0, 0, 0); PG8_LDB(B1, 0, 1); PG8_SCHED; PG8_LDA(At, 0, 0); PG8_STAGE(PG8_SA(1, 1), a1 + hstep, voffA);
;             PG8_WAIT_V(8); PG8_WAIT_L(0); PG8_BAR; PG8_MMA(0, 0, At, B0); PG8_MMA(0, 1, At, B1); PG8_BAR; PG8_SCHED;
;             PG8_LDA(At, 0, 1); PG8_STAGE(PG8_SB(0, 0), b2, voffB); PG8_STAGE(PG8_SB(0, 1), b2 + hstep, voffB); PG8_STAGE(PG8_SA(0, 0), a2, voffA);
.LBB0_789:
	v_add_u32_e32 v164, 0x10000, v149
	v_add_u32_e32 v180, 0x14000, v149
	s_add_u32 s8, s40, 0x100
	s_waitcnt lgkmcnt(0)
	ds_read_b128 v[152:155], v164
	ds_read_b128 v[156:159], v164 offset:1024
	ds_read_b128 v[160:163], v164 offset:2048
	ds_read_b128 v[164:167], v164 offset:3072
	ds_read_b128 v[168:171], v180
	ds_read_b128 v[172:175], v180 offset:1024
	ds_read_b128 v[176:179], v180 offset:2048
	ds_read_b128 v[180:183], v180 offset:3072
	s_addc_u32 s9, s41, 0
	s_and_b64 s[38:39], s[38:39], exec
	s_cselect_b32 s46, s59, s8
	s_cselect_b32 s47, s17, s9
	s_cselect_b32 s39, s15, s75
	s_cselect_b32 s38, s71, s74
	s_add_u32 s42, s46, 0x80
	s_addc_u32 s43, s47, 0
	s_add_u32 s44, s38, 0x80
	s_addc_u32 s45, s39, 0
	ds_read_b128 v[184:187], v150
	ds_read_b128 v[188:191], v150 offset:1024
	ds_read_b128 v[192:195], v150 offset:2048
	ds_read_b128 v[196:199], v150 offset:3072
	ds_read_b128 v[200:203], v150 offset:4096
	ds_read_b128 v[204:207], v150 offset:5120
	ds_read_b128 v[208:211], v150 offset:6144
	ds_read_b128 v[212:215], v150 offset:7168
	s_add_u32 s40, s40, 0x100080
	s_addc_u32 s41, s41, 0
	s_mov_b32 m0, s64
	s_nop 0
	global_load_lds_dwordx4 v139, s[40:41]
	s_nop 0
	s_mov_b32 m0, s65
	s_nop 0
	global_load_lds_dwordx4 v141, s[40:41]
	s_waitcnt vmcnt(8)
	s_waitcnt lgkmcnt(0)
	s_barrier
	s_setprio 1
	s_waitcnt lgkmcnt(7)
	v_mfma_f32_16x16x32_bf16 v[126:129], v[152:155], v[184:187], v[126:129]
	v_mfma_f32_16x16x32_bf16 v[126:129], v[156:159], v[188:191], v[126:129]
	s_waitcnt lgkmcnt(5)
	v_mfma_f32_16x16x32_bf16 v[122:125], v[164:167], v[188:191], v[122:125]
	v_mfma_f32_16x16x32_bf16 v[122:125], v[160:163], v[184:187], v[122:125]
	s_waitcnt lgkmcnt(3)
	v_mfma_f32_16x16x32_bf16 v[106:109], v[160:163], v[192:195], v[106:109]
	v_mfma_f32_16x16x32_bf16 v[106:109], v[164:167], v[196:199], v[106:109]
	s_waitcnt lgkmcnt(1)
	v_mfma_f32_16x16x32_bf16 v[110:113], v[156:159], v[196:199], v[110:113]
	v_mfma_f32_16x16x32_bf16 v[110:113], v[152:155], v[192:195], v[110:113]
	v_mfma_f32_16x16x32_bf16 v[94:97], v[152:155], v[200:203], v[94:97]
	v_mfma_f32_16x16x32_bf16 v[94:97], v[156:159], v[204:207], v[94:97]
	v_mfma_f32_16x16x32_bf16 v[90:93], v[164:167], v[204:207], v[90:93]
	v_mfma_f32_16x16x32_bf16 v[90:93], v[160:163], v[200:203], v[90:93]
	v_mfma_f32_16x16x32_bf16 v[74:77], v[160:163], v[208:211], v[74:77]
	v_mfma_f32_16x16x32_bf16 v[74:77], v[164:167], v[212:215], v[74:77]
	s_waitcnt lgkmcnt(0)
	v_mfma_f32_16x16x32_bf16 v[78:81], v[156:159], v[212:215], v[78:81]
	v_mfma_f32_16x16x32_bf16 v[78:81], v[152:155], v[208:211], v[78:81]
	s_setprio 0
	s_setprio 1
	v_mfma_f32_16x16x32_bf16 v[118:121], v[168:171], v[184:187], v[118:121]
	v_mfma_f32_16x16x32_bf16 v[118:121], v[172:175], v[188:191], v[118:121]
	v_mfma_f32_16x16x32_bf16 v[114:117], v[180:183], v[188:191], v[114:117]
	v_mfma_f32_16x16x32_bf16 v[114:117], v[176:179], v[184:187], v[114:117]
	v_mfma_f32_16x16x32_bf16 v[98:101], v[176:179], v[192:195], v[98:101]
	v_mfma_f32_16x16x32_bf16 v[98:101], v[180:183], v[196:199], v[98:101]
	v_mfma_f32_16x16x32_bf16 v[102:105], v[172:175], v[196:199], v[102:105]
	v_mfma_f32_16x16x32_bf16 v[102:105], v[168:171], v[192:195], v[102:105]
	v_mfma_f32_16x16x32_bf16 v[86:89], v[168:171], v[200:203], v[86:89]
	v_mfma_f32_16x16x32_bf16 v[86:89], v[172:175], v[204:207], v[86:89]
	v_mfma_f32_16x16x32_bf16 v[82:85], v[180:183], v[204:207], v[82:85]
	v_mfma_f32_16x16x32_bf16 v[82:85], v[176:179], v[200:203], v[82:85]
	v_mfma_f32_16x16x32_bf16 v[66:69], v[176:179], v[208:211], v[66:69]
	v_mfma_f32_16x16x32_bf16 v[66:69], v[180:183], v[212:215], v[66:69]
	v_mfma_f32_16x16x32_bf16 v[70:73], v[172:175], v[212:215], v[70:73]
	s_setprio 2
	s_barrier
	v_mfma_f32_16x16x32_bf16 v[70:73], v[168:171], v[208:211], v[70:73]
	s_setprio 0
	ds_read_b128 v[184:187], v150 offset:16384
	ds_read_b128 v[188:191], v150 offset:17408
	ds_read_b128 v[192:195], v150 offset:18432
	ds_read_b128 v[196:199], v150 offset:19456
	ds_read_b128 v[200:203], v150 offset:20480
	ds_read_b128 v[204:207], v150 offset:21504
	ds_read_b128 v[252:255], v150 offset:22528
	ds_read_b128 v[212:215], v150 offset:23552
	s_mov_b32 m0, s49
	s_nop 0
	global_load_lds_dwordx4 v140, s[38:39]
	s_add_u32 s40, s38, 0x100000
	s_mov_b32 m0, s50
	s_nop 0
	global_load_lds_dwordx4 v142, s[38:39]
	s_addc_u32 s41, s39, 0
	s_mov_b32 m0, s51
	s_nop 0
	global_load_lds_dwordx4 v140, s[40:41]
	s_nop 0
	s_mov_b32 m0, s52
	s_nop 0
	global_load_lds_dwordx4 v142, s[40:41]
	s_nop 0
	s_mov_b32 m0, s37
	s_nop 0
	global_load_lds_dwordx4 v139, s[46:47]
	s_nop 0
	s_mov_b32 m0, s53
	s_nop 0
	global_load_lds_dwordx4 v141, s[46:47]
	s_waitcnt vmcnt(8)
	s_waitcnt lgkmcnt(0)
	s_barrier
; #define PG8_STAGE(bufoff, gbase, voff) do { _Pragma("unroll") for (int _i = 0; _i < 2; ++_i) \
;         asm volatile("s_mov_b32 m0, %2\n\ts_nop 0\n\tglobal_load_lds_dwordx4 %0, %1" :: "v"((voff)[_i]), "s"((const char*)(gbase)), "s"(ldsbase + (unsigned)(bufoff) + ldsw + (unsigned)_i * 8192u) : "memory", "m0"); } while (0)
; #define PG8_LDA(dst, b, h) do { _Pragma("unroll") for (int m = 0; m < 4; ++m) _Pragma("unroll") for (int k = 0; k < 2; ++k) dst[m][k] = *(const PG8_LAS bf16x8*)(lds + PG8_SA(b, h) + aoff + m * 2048 + k * 1024); } while (0)
; #define PG8_LDB(dst, b, h) do { _Pragma("unroll") for (int n = 0; n < 2; ++n) _Pragma("unroll") for (int k = 0; k < 2; ++k) dst[n][k] = *(const PG8_LAS bf16x8*)(lds + PG8_SB(b, h) + boff + n * 2048 + k * 1024); } while (0)
; #define PG8_MMA(ai, bj, At, Bt) do { __builtin_amdgcn_s_setprio(1); _Pragma("unroll") for (int m = 0; m < 4; ++m) _Pragma("unroll") for (int n = 0; n < 2; ++n) _Pragma("unroll") for (int k = 0; k < 2; ++k) \
;         acc[ai][bj][m][n] = __builtin_amdgcn_mfma_f32_16x16x32_bf16(Bt[n][k], At[m][k], acc[ai][bj][m][n], 0, 0, 0); __builtin_amdgcn_s_setprio(0); } while (0)
; #define PG8_WAIT_V(n) asm volatile("s_waitcnt vmcnt(" #n ")" ::: "memory")
; #define PG8_WAIT_L(n) asm volatile("s_waitcnt lgkmcnt(" #n ")" ::: "memory")
; #define PG8_BAR __builtin_amdgcn_s_barrier()
; #define PG8_SCHED __builtin_amdgcn_sched_barrier(0)
; template <class Epi, class Sched, bool ALIGN_EPI = false, bool SP2 = false>
; __device__ __forceinline__ void gemm_phase(PG8_LAS unsigned char* lds, const Gemm g, const Sched& S, const Epi& E) {
;     ...
;             PG8_WAIT_V(8); PG8_WAIT_L(0); PG8_BAR; PG8_MMA(1, 0, At, B0); PG8_MMA(1, 1, At, B1); PG8_BAR; PG8_SCHED;
;             PG8_LDB(B0, 1, 0); PG8_LDB(B1, 1, 1); PG8_SCHED; PG8_LDA(At, 1, 0); PG8_STAGE(PG8_SA(0, 1), a2 + hstep, voffA);
;             PG8_WAIT_V(8); PG8_WAIT_L(0); PG8_BAR; PG8_MMA(0, 0, At, B0); PG8_MMA(0, 1, At, B1); PG8_BAR; PG8_SCHED;
	s_setprio 1
	s_waitcnt lgkmcnt(7)
	v_mfma_f32_16x16x32_bf16 v[62:65], v[152:155], v[184:187], v[62:65]
	v_mfma_f32_16x16x32_bf16 v[62:65], v[156:159], v[188:191], v[62:65]
	s_waitcnt lgkmcnt(5)
	v_mfma_f32_16x16x32_bf16 v[58:61], v[164:167], v[188:191], v[58:61]
	v_mfma_f32_16x16x32_bf16 v[58:61], v[160:163], v[184:187], v[58:61]
	s_waitcnt lgkmcnt(3)
	v_mfma_f32_16x16x32_bf16 v[42:45], v[160:163], v[192:195], v[42:45]
	v_mfma_f32_16x16x32_bf16 v[42:45], v[164:167], v[196:199], v[42:45]
	s_waitcnt lgkmcnt(1)
	v_mfma_f32_16x16x32_bf16 v[46:49], v[156:159], v[196:199], v[46:49]
	v_mfma_f32_16x16x32_bf16 v[46:49], v[152:155], v[192:195], v[46:49]
	v_mfma_f32_16x16x32_bf16 v[30:33], v[152:155], v[200:203], v[30:33]
	v_mfma_f32_16x16x32_bf16 v[30:33], v[156:159], v[204:207], v[30:33]
	v_mfma_f32_16x16x32_bf16 v[26:29], v[164:167], v[204:207], v[26:29]
	v_mfma_f32_16x16x32_bf16 v[26:29], v[160:163], v[200:203], v[26:29]
	v_mfma_f32_16x16x32_bf16 v[10:13], v[160:163], v[252:255], v[10:13]
	v_mfma_f32_16x16x32_bf16 v[10:13], v[164:167], v[212:215], v[10:13]
	s_waitcnt lgkmcnt(0)
	v_mfma_f32_16x16x32_bf16 v[14:17], v[156:159], v[212:215], v[14:17]
	v_mfma_f32_16x16x32_bf16 v[14:17], v[152:155], v[252:255], v[14:17]
	s_setprio 0
	s_setprio 1
	v_mfma_f32_16x16x32_bf16 v[54:57], v[168:171], v[184:187], v[54:57]
	v_mfma_f32_16x16x32_bf16 v[54:57], v[172:175], v[188:191], v[54:57]
	v_mfma_f32_16x16x32_bf16 v[50:53], v[180:183], v[188:191], v[50:53]
	v_mfma_f32_16x16x32_bf16 v[50:53], v[176:179], v[184:187], v[50:53]
	v_mfma_f32_16x16x32_bf16 v[34:37], v[176:179], v[192:195], v[34:37]
	v_mfma_f32_16x16x32_bf16 v[34:37], v[180:183], v[196:199], v[34:37]
	v_mfma_f32_16x16x32_bf16 v[38:41], v[172:175], v[196:199], v[38:41]
	v_mfma_f32_16x16x32_bf16 v[38:41], v[168:171], v[192:195], v[38:41]
	v_mfma_f32_16x16x32_bf16 v[22:25], v[168:171], v[200:203], v[22:25]
	v_mfma_f32_16x16x32_bf16 v[22:25], v[172:175], v[204:207], v[22:25]
	v_mfma_f32_16x16x32_bf16 v[18:21], v[180:183], v[204:207], v[18:21]
	v_mfma_f32_16x16x32_bf16 v[18:21], v[176:179], v[200:203], v[18:21]
	v_mfma_f32_16x16x32_bf16 v[2:5], v[176:179], v[252:255], v[2:5]
	v_mfma_f32_16x16x32_bf16 v[2:5], v[180:183], v[212:215], v[2:5]
	v_mfma_f32_16x16x32_bf16 v[6:9], v[172:175], v[212:215], v[6:9]
	s_setprio 2
	s_barrier
	v_mfma_f32_16x16x32_bf16 v[6:9], v[168:171], v[252:255], v[6:9]
	s_setprio 0
	v_add_u32_e32 v164, 0x18000, v149
	v_add_u32_e32 v180, 0x1c000, v149
	ds_read_b128 v[152:155], v164
	ds_read_b128 v[156:159], v164 offset:1024
	ds_read_b128 v[160:163], v164 offset:2048
	ds_read_b128 v[164:167], v164 offset:3072
	ds_read_b128 v[248:251], v180
	ds_read_b128 v[172:175], v180 offset:1024
	ds_read_b128 v[176:179], v180 offset:2048
	ds_read_b128 v[180:183], v180 offset:3072
	ds_read_b128 v[184:187], v150 offset:32768
	ds_read_b128 v[188:191], v150 offset:33792
	ds_read_b128 v[192:195], v150 offset:34816
	ds_read_b128 v[196:199], v150 offset:35840
	ds_read_b128 v[200:203], v150 offset:36864
	ds_read_b128 v[204:207], v150 offset:37888
	ds_read_b128 v[208:211], v150 offset:38912
	ds_read_b128 v[212:215], v150 offset:39936
	s_add_u32 s40, s46, 0x100000
	s_addc_u32 s41, s47, 0
	s_mov_b32 m0, s54
	s_nop 0
	global_load_lds_dwordx4 v139, s[40:41]
	s_nop 0
	s_mov_b32 m0, s55
	s_nop 0
	global_load_lds_dwordx4 v141, s[40:41]
	s_waitcnt vmcnt(8)
	s_waitcnt lgkmcnt(0)
	s_barrier
	s_setprio 1
	s_waitcnt lgkmcnt(7)
	v_mfma_f32_16x16x32_bf16 v[126:129], v[152:155], v[184:187], v[126:129]
	v_mfma_f32_16x16x32_bf16 v[126:129], v[156:159], v[188:191], v[126:129]
	s_waitcnt lgkmcnt(5)
	v_mfma_f32_16x16x32_bf16 v[122:125], v[164:167], v[188:191], v[122:125]
	v_mfma_f32_16x16x32_bf16 v[122:125], v[160:163], v[184:187], v[122:125]
	s_waitcnt lgkmcnt(3)
	v_mfma_f32_16x16x32_bf16 v[106:109], v[160:163], v[192:195], v[106:109]
	v_mfma_f32_16x16x32_bf16 v[106:109], v[164:167], v[196:199], v[106:109]
	s_waitcnt lgkmcnt(1)
	v_mfma_f32_16x16x32_bf16 v[110:113], v[156:159], v[196:199], v[110:113]
	v_mfma_f32_16x16x32_bf16 v[110:113], v[152:155], v[192:195], v[110:113]
	v_mfma_f32_16x16x32_bf16 v[94:97], v[152:155], v[200:203], v[94:97]
	v_mfma_f32_16x16x32_bf16 v[94:97], v[156:159], v[204:207], v[94:97]
	v_mfma_f32_16x16x32_bf16 v[90:93], v[164:167], v[204:207], v[90:93]
	v_mfma_f32_16x16x32_bf16 v[90:93], v[160:163], v[200:203], v[90:93]
	v_mfma_f32_16x16x32_bf16 v[74:77], v[160:163], v[208:211], v[74:77]
	v_mfma_f32_16x16x32_bf16 v[74:77], v[164:167], v[212:215], v[74:77]
	s_waitcnt lgkmcnt(0)
	v_mfma_f32_16x16x32_bf16 v[78:81], v[156:159], v[212:215], v[78:81]
	v_mfma_f32_16x16x32_bf16 v[78:81], v[152:155], v[208:211], v[78:81]
	s_setprio 0
	s_setprio 1
	v_mfma_f32_16x16x32_bf16 v[118:121], v[248:251], v[184:187], v[118:121]
	v_mfma_f32_16x16x32_bf16 v[118:121], v[172:175], v[188:191], v[118:121]
	v_mfma_f32_16x16x32_bf16 v[114:117], v[180:183], v[188:191], v[114:117]
	v_mfma_f32_16x16x32_bf16 v[114:117], v[176:179], v[184:187], v[114:117]
	v_mfma_f32_16x16x32_bf16 v[98:101], v[176:179], v[192:195], v[98:101]
	v_mfma_f32_16x16x32_bf16 v[98:101], v[180:183], v[196:199], v[98:101]
	v_mfma_f32_16x16x32_bf16 v[102:105], v[172:175], v[196:199], v[102:105]
	v_mfma_f32_16x16x32_bf16 v[102:105], v[248:251], v[192:195], v[102:105]
	v_mfma_f32_16x16x32_bf16 v[86:89], v[248:251], v[200:203], v[86:89]
	v_mfma_f32_16x16x32_bf16 v[86:89], v[172:175], v[204:207], v[86:89]
	v_mfma_f32_16x16x32_bf16 v[82:85], v[180:183], v[204:207], v[82:85]
	v_mfma_f32_16x16x32_bf16 v[82:85], v[176:179], v[200:203], v[82:85]
	v_mfma_f32_16x16x32_bf16 v[66:69], v[176:179], v[208:211], v[66:69]
	v_mfma_f32_16x16x32_bf16 v[66:69], v[180:183], v[212:215], v[66:69]
	v_mfma_f32_16x16x32_bf16 v[70:73], v[172:175], v[212:215], v[70:73]
	s_setprio 2
	s_barrier
; #define PG8_STAGE(bufoff, gbase, voff) do { _Pragma("unroll") for (int _i = 0; _i < 2; ++_i) \
;         asm volatile("s_mov_b32 m0, %2\n\ts_nop 0\n\tglobal_load_lds_dwordx4 %0, %1" :: "v"((voff)[_i]), "s"((const char*)(gbase)), "s"(ldsbase + (unsigned)(bufoff) + ldsw + (unsigned)_i * 8192u) : "memory", "m0"); } while (0)
; #define PG8_LDA(dst, b, h) do { _Pragma("unroll") for (int m = 0; m < 4; ++m) _Pragma("unroll") for (int k = 0; k < 2; ++k) dst[m][k] = *(const PG8_LAS bf16x8*)(lds + PG8_SA(b, h) + aoff + m * 2048 + k * 1024); } while (0)
; #define PG8_MMA(ai, bj, At, Bt) do { __builtin_amdgcn_s_setprio(1); _Pragma("unroll") for (int m = 0; m < 4; ++m) _Pragma("unroll") for (int n = 0; n < 2; ++n) _Pragma("unroll") for (int k = 0; k < 2; ++k) \
;         acc[ai][bj][m][n] = __builtin_amdgcn_mfma_f32_16x16x32_bf16(Bt[n][k], At[m][k], acc[ai][bj][m][n], 0, 0, 0); __builtin_amdgcn_s_setprio(0); } while (0)
; #define PG8_WAIT_V(n) asm volatile("s_waitcnt vmcnt(" #n ")" ::: "memory")
; #define PG8_WAIT_L(n) asm volatile("s_waitcnt lgkmcnt(" #n ")" ::: "memory")
; #define PG8_BAR __builtin_amdgcn_s_barrier()
; #define PG8_SCHED __builtin_amdgcn_sched_barrier(0)
; template <class Epi, class Sched, bool ALIGN_EPI = false, bool SP2 = false>
; __device__ __forceinline__ void gemm_phase(PG8_LAS unsigned char* lds, const Gemm g, const Sched& S, const Epi& E) {
;     ...
;             PG8_WAIT_V(8); PG8_WAIT_L(0); PG8_BAR; PG8_MMA(0, 0, At, B0); PG8_MMA(0, 1, At, B1); PG8_BAR; PG8_SCHED;
;             PG8_LDA(At, 1, 1); PG8_STAGE(PG8_SB(1, 0), b3, voffB); PG8_STAGE(PG8_SB(1, 1), b3 + hstep, voffB); PG8_STAGE(PG8_SA(1, 0), a3, voffA);
;             PG8_WAIT_V(8); PG8_WAIT_L(0); PG8_BAR; PG8_MMA(1, 0, At, B0); PG8_MMA(1, 1, At, B1); PG8_BAR; PG8_SCHED;
	v_mfma_f32_16x16x32_bf16 v[70:73], v[248:251], v[208:211], v[70:73]
	s_setprio 0
	ds_read_b128 v[184:187], v150 offset:49152
	ds_read_b128 v[188:191], v150 offset:50176
	ds_read_b128 v[192:195], v150 offset:51200
	ds_read_b128 v[196:199], v150 offset:52224
	ds_read_b128 v[200:203], v150 offset:53248
	ds_read_b128 v[204:207], v150 offset:54272
	ds_read_b128 v[252:255], v150 offset:55296
	ds_read_b128 v[212:215], v150 offset:56320
	s_mov_b32 m0, s56
	s_nop 0
	global_load_lds_dwordx4 v140, s[44:45]
	s_add_u32 s38, s38, 0x100080
	s_mov_b32 m0, s57
	s_nop 0
	global_load_lds_dwordx4 v142, s[44:45]
	s_addc_u32 s39, s39, 0
	s_mov_b32 m0, s62
	s_nop 0
	global_load_lds_dwordx4 v140, s[38:39]
	s_nop 0
	s_mov_b32 m0, s63
	s_nop 0
	global_load_lds_dwordx4 v142, s[38:39]
	s_nop 0
	s_mov_b32 m0, s60
	s_nop 0
	global_load_lds_dwordx4 v139, s[42:43]
	s_nop 0
	s_mov_b32 m0, s61
	s_nop 0
	global_load_lds_dwordx4 v141, s[42:43]
	s_waitcnt vmcnt(8)
	s_waitcnt lgkmcnt(0)
	s_barrier
	s_setprio 1
	s_waitcnt lgkmcnt(7)
	v_mfma_f32_16x16x32_bf16 v[62:65], v[152:155], v[184:187], v[62:65]
	v_mfma_f32_16x16x32_bf16 v[62:65], v[156:159], v[188:191], v[62:65]
	s_waitcnt lgkmcnt(5)
	v_mfma_f32_16x16x32_bf16 v[58:61], v[164:167], v[188:191], v[58:61]
	v_mfma_f32_16x16x32_bf16 v[58:61], v[160:163], v[184:187], v[58:61]
	s_waitcnt lgkmcnt(3)
	v_mfma_f32_16x16x32_bf16 v[42:45], v[160:163], v[192:195], v[42:45]
	v_mfma_f32_16x16x32_bf16 v[42:45], v[164:167], v[196:199], v[42:45]
	s_waitcnt lgkmcnt(1)
	v_mfma_f32_16x16x32_bf16 v[46:49], v[156:159], v[196:199], v[46:49]
	v_mfma_f32_16x16x32_bf16 v[46:49], v[152:155], v[192:195], v[46:49]
	v_mfma_f32_16x16x32_bf16 v[30:33], v[152:155], v[200:203], v[30:33]
	v_mfma_f32_16x16x32_bf16 v[30:33], v[156:159], v[204:207], v[30:33]
	v_mfma_f32_16x16x32_bf16 v[26:29], v[164:167], v[204:207], v[26:29]
	v_mfma_f32_16x16x32_bf16 v[26:29], v[160:163], v[200:203], v[26:29]
	v_mfma_f32_16x16x32_bf16 v[10:13], v[160:163], v[252:255], v[10:13]
	v_mfma_f32_16x16x32_bf16 v[10:13], v[164:167], v[212:215], v[10:13]
	s_waitcnt lgkmcnt(0)
	v_mfma_f32_16x16x32_bf16 v[14:17], v[156:159], v[212:215], v[14:17]
	v_mfma_f32_16x16x32_bf16 v[14:17], v[152:155], v[252:255], v[14:17]
	s_setprio 0
	s_setprio 1
	v_mfma_f32_16x16x32_bf16 v[54:57], v[248:251], v[184:187], v[54:57]
	v_mfma_f32_16x16x32_bf16 v[54:57], v[172:175], v[188:191], v[54:57]
	v_mfma_f32_16x16x32_bf16 v[50:53], v[180:183], v[188:191], v[50:53]
	v_mfma_f32_16x16x32_bf16 v[50:53], v[176:179], v[184:187], v[50:53]
	v_mfma_f32_16x16x32_bf16 v[34:37], v[176:179], v[192:195], v[34:37]
	v_mfma_f32_16x16x32_bf16 v[34:37], v[180:183], v[196:199], v[34:37]
	v_mfma_f32_16x16x32_bf16 v[38:41], v[172:175], v[196:199], v[38:41]
	v_mfma_f32_16x16x32_bf16 v[38:41], v[248:251], v[192:195], v[38:41]
	v_mfma_f32_16x16x32_bf16 v[22:25], v[248:251], v[200:203], v[22:25]
	v_mfma_f32_16x16x32_bf16 v[22:25], v[172:175], v[204:207], v[22:25]
	v_mfma_f32_16x16x32_bf16 v[18:21], v[180:183], v[204:207], v[18:21]
	v_mfma_f32_16x16x32_bf16 v[18:21], v[176:179], v[200:203], v[18:21]
	v_mfma_f32_16x16x32_bf16 v[2:5], v[176:179], v[252:255], v[2:5]
	v_mfma_f32_16x16x32_bf16 v[2:5], v[180:183], v[212:215], v[2:5]
	v_mfma_f32_16x16x32_bf16 v[6:9], v[172:175], v[212:215], v[6:9]
	s_setprio 2
	s_barrier
	v_mfma_f32_16x16x32_bf16 v[6:9], v[248:251], v[252:255], v[6:9]
	s_setprio 0
	s_add_i32 s76, s76, 2
	s_add_u32 s74, s74, 0x100
	s_addc_u32 s75, s75, 0
	s_cmp_gt_u32 s76, 61
	s_cbranch_scc1 .LBB0_780
	s_mov_b64 s[40:41], s[8:9]
	s_branch .LBB0_784

; #define PG8_STAGE(bufoff, gbase, voff) do { _Pragma("unroll") for (int _i = 0; _i < 2; ++_i) \
;         asm volatile("s_mov_b32 m0, %2\n\ts_nop 0\n\tglobal_load_lds_dwordx4 %0, %1" :: "v"((voff)[_i]), "s"((const char*)(gbase)), "s"(ldsbase + (unsigned)(bufoff) + ldsw + (unsigned)_i * 8192u) : "memory", "m0"); } while (0)
; #define PG8_LDA(dst, b, h) do { _Pragma("unroll") for (int m = 0; m < 4; ++m) _Pragma("unroll") for (int k = 0; k < 2; ++k) dst[m][k] = *(const PG8_LAS bf16x8*)(lds + PG8_SA(b, h) + aoff + m * 2048 + k * 1024); } while (0)
; #define PG8_LDB(dst, b, h) do { _Pragma("unroll") for (int n = 0; n < 2; ++n) _Pragma("unroll") for (int k = 0; k < 2; ++k) dst[n][k] = *(const PG8_LAS bf16x8*)(lds + PG8_SB(b, h) + boff + n * 2048 + k * 1024); } while (0)
; #define PG8_MMA(ai, bj, At, Bt) do { __builtin_amdgcn_s_setprio(1); _Pragma("unroll") for (int m = 0; m < 4; ++m) _Pragma("unroll") for (int n = 0; n < 2; ++n) _Pragma("unroll") for (int k = 0; k < 2; ++k) \
;         acc[ai][bj][m][n] = __builtin_amdgcn_mfma_f32_16x16x32_bf16(Bt[n][k], At[m][k], acc[ai][bj][m][n], 0, 0, 0); __builtin_amdgcn_s_setprio(0); } while (0)
; #define PG8_WAIT_V(n) asm volatile("s_waitcnt vmcnt(" #n ")" ::: "memory")
; #define PG8_BAR __builtin_amdgcn_s_barrier()
; template <class Epi, class Sched, bool ALIGN_EPI = false, bool SP2 = false>
; __device__ __forceinline__ void gemm_phase(PG8_LAS unsigned char* lds, const Gemm g, const Sched& S, const Epi& E) {
;     ...
;             const bool last = (t == nt - 2);
;             const char* a1 = cA + (size_t)(t + 1) * kstep;
;             const char* a2 = last ? nA : cA + (size_t)(t + 2) * kstep; const char* b2 = last ? nB : cB + (size_t)(t + 2) * kstep;
;             const char* a3 = a2 + kstep; const char* b3 = b2 + kstep;
;             if (last && has_next) S.a_ready(nxt);
;             if constexpr (epi_has_mid<Epi>::value) { if (t == Epi::MID_T) E.mid(acc, cur, wr, wc, fr, fq); }
;             if constexpr (SP2) {
;             PG8_LDB(B0, 0, 0); PG8_LDB(B1, 0, 1); PG8_SCHED; PG8_LDA(At, 0, 0); PG8_STAGE(PG8_SA(1, 1), a1 + hstep, voffA);
;             PG8_WAIT_V(8); PG8_WAIT_L(0); PG8_BAR; PG8_MMA(0, 0, At, B0); PG8_MMA(0, 1, At, B1); PG8_BAR; PG8_SCHED;
;             PG8_LDA(At, 0, 1); PG8_STAGE(PG8_SB(0, 0), b2, voffB); PG8_STAGE(PG8_SB(0, 1), b2 + hstep, voffB); PG8_STAGE(PG8_SA(0, 0), a2, voffA);
.LBB0_873:
	ds_read_b128 v[134:137], v145
	ds_read_b128 v[150:153], v145 offset:1024
	ds_read_b128 v[154:157], v145 offset:2048
	ds_read_b128 v[158:161], v145 offset:3072
	ds_read_b128 v[162:165], v146
	ds_read_b128 v[166:169], v146 offset:1024
	ds_read_b128 v[170:173], v146 offset:2048
	ds_read_b128 v[174:177], v146 offset:3072
	s_add_u32 s38, s36, 0x100
	s_addc_u32 s39, s37, 0
	s_cmpk_eq_i32 s69, 0xa8
	s_cselect_b32 s44, s4, s38
	s_cselect_b32 s45, s5, s39
	s_cselect_b32 s42, s22, s67
	s_cselect_b32 s43, s23, s68
	s_add_u32 s40, s44, 0x80
	s_addc_u32 s41, s45, 0
	ds_read_b128 v[178:181], v147
	ds_read_b128 v[182:185], v147 offset:1024
	ds_read_b128 v[186:189], v147 offset:2048
	ds_read_b128 v[190:193], v147 offset:3072
	ds_read_b128 v[194:197], v147 offset:4096
	ds_read_b128 v[198:201], v147 offset:5120
	ds_read_b128 v[202:205], v147 offset:6144
	ds_read_b128 v[206:209], v147 offset:7168
	s_add_u32 s36, s36, 0x2b0080
	s_addc_u32 s37, s37, 0
	s_mov_b32 m0, s60
	s_nop 0
	global_load_lds_dwordx4 v1, s[36:37]
	s_nop 0
	s_mov_b32 m0, s61
	s_nop 0
	global_load_lds_dwordx4 v141, s[36:37]
	s_waitcnt vmcnt(8)
	s_waitcnt lgkmcnt(0)
	s_barrier
	s_setprio 1
	s_waitcnt lgkmcnt(7)
	v_mfma_f32_16x16x32_bf16 v[126:129], v[134:137], v[178:181], v[126:129]
	v_mfma_f32_16x16x32_bf16 v[126:129], v[150:153], v[182:185], v[126:129]
	s_waitcnt lgkmcnt(5)
	v_mfma_f32_16x16x32_bf16 v[122:125], v[158:161], v[182:185], v[122:125]
	v_mfma_f32_16x16x32_bf16 v[122:125], v[154:157], v[178:181], v[122:125]
	s_waitcnt lgkmcnt(3)
	v_mfma_f32_16x16x32_bf16 v[106:109], v[154:157], v[186:189], v[106:109]
	v_mfma_f32_16x16x32_bf16 v[106:109], v[158:161], v[190:193], v[106:109]
	s_waitcnt lgkmcnt(1)
	v_mfma_f32_16x16x32_bf16 v[110:113], v[150:153], v[190:193], v[110:113]
	v_mfma_f32_16x16x32_bf16 v[110:113], v[134:137], v[186:189], v[110:113]
	v_mfma_f32_16x16x32_bf16 v[94:97], v[134:137], v[194:197], v[94:97]
	v_mfma_f32_16x16x32_bf16 v[94:97], v[150:153], v[198:201], v[94:97]
	v_mfma_f32_16x16x32_bf16 v[90:93], v[158:161], v[198:201], v[90:93]
	v_mfma_f32_16x16x32_bf16 v[90:93], v[154:157], v[194:197], v[90:93]
	v_mfma_f32_16x16x32_bf16 v[74:77], v[154:157], v[202:205], v[74:77]
	v_mfma_f32_16x16x32_bf16 v[74:77], v[158:161], v[206:209], v[74:77]
	s_waitcnt lgkmcnt(0)
	v_mfma_f32_16x16x32_bf16 v[78:81], v[150:153], v[206:209], v[78:81]
	v_mfma_f32_16x16x32_bf16 v[78:81], v[134:137], v[202:205], v[78:81]
	s_setprio 0
	s_setprio 1
	v_mfma_f32_16x16x32_bf16 v[118:121], v[162:165], v[178:181], v[118:121]
	v_mfma_f32_16x16x32_bf16 v[118:121], v[166:169], v[182:185], v[118:121]
	v_mfma_f32_16x16x32_bf16 v[114:117], v[174:177], v[182:185], v[114:117]
	v_mfma_f32_16x16x32_bf16 v[114:117], v[170:173], v[178:181], v[114:117]
	v_mfma_f32_16x16x32_bf16 v[98:101], v[170:173], v[186:189], v[98:101]
	v_mfma_f32_16x16x32_bf16 v[98:101], v[174:177], v[190:193], v[98:101]
	v_mfma_f32_16x16x32_bf16 v[102:105], v[166:169], v[190:193], v[102:105]
	v_mfma_f32_16x16x32_bf16 v[102:105], v[162:165], v[186:189], v[102:105]
	v_mfma_f32_16x16x32_bf16 v[86:89], v[162:165], v[194:197], v[86:89]
	v_mfma_f32_16x16x32_bf16 v[86:89], v[166:169], v[198:201], v[86:89]
	v_mfma_f32_16x16x32_bf16 v[82:85], v[174:177], v[198:201], v[82:85]
	v_mfma_f32_16x16x32_bf16 v[82:85], v[170:173], v[194:197], v[82:85]
	v_mfma_f32_16x16x32_bf16 v[66:69], v[170:173], v[202:205], v[66:69]
	v_mfma_f32_16x16x32_bf16 v[66:69], v[174:177], v[206:209], v[66:69]
	v_mfma_f32_16x16x32_bf16 v[70:73], v[166:169], v[206:209], v[70:73]
	s_setprio 2
	s_barrier
	v_mfma_f32_16x16x32_bf16 v[70:73], v[162:165], v[202:205], v[70:73]
	s_setprio 0
	ds_read_b128 v[178:181], v147 offset:16384
	ds_read_b128 v[182:185], v147 offset:17408
	ds_read_b128 v[186:189], v147 offset:18432
	ds_read_b128 v[190:193], v147 offset:19456
	ds_read_b128 v[194:197], v147 offset:20480
	ds_read_b128 v[198:201], v147 offset:21504
	ds_read_b128 v[252:255], v147 offset:22528
	ds_read_b128 v[206:209], v147 offset:23552
	s_mov_b32 m0, s47
	s_nop 0
	global_load_lds_dwordx4 v140, s[42:43]
	s_add_u32 s36, s42, 0x2b0000
	s_mov_b32 m0, s48
	s_nop 0
	global_load_lds_dwordx4 v142, s[42:43]
	s_addc_u32 s37, s43, 0
	s_mov_b32 m0, s49
	s_nop 0
	global_load_lds_dwordx4 v140, s[36:37]
	s_nop 0
	s_mov_b32 m0, s50
	s_nop 0
	global_load_lds_dwordx4 v142, s[36:37]
	s_nop 0
	s_mov_b32 m0, s46
	s_nop 0
	global_load_lds_dwordx4 v1, s[44:45]
	s_nop 0
	s_mov_b32 m0, s51
	s_nop 0
	global_load_lds_dwordx4 v141, s[44:45]
	s_waitcnt vmcnt(8)
	s_waitcnt lgkmcnt(0)
	s_barrier
; #define PG8_STAGE(bufoff, gbase, voff) do { _Pragma("unroll") for (int _i = 0; _i < 2; ++_i) \
;         asm volatile("s_mov_b32 m0, %2\n\ts_nop 0\n\tglobal_load_lds_dwordx4 %0, %1" :: "v"((voff)[_i]), "s"((const char*)(gbase)), "s"(ldsbase + (unsigned)(bufoff) + ldsw + (unsigned)_i * 8192u) : "memory", "m0"); } while (0)
; #define PG8_LDA(dst, b, h) do { _Pragma("unroll") for (int m = 0; m < 4; ++m) _Pragma("unroll") for (int k = 0; k < 2; ++k) dst[m][k] = *(const PG8_LAS bf16x8*)(lds + PG8_SA(b, h) + aoff + m * 2048 + k * 1024); } while (0)
; #define PG8_LDB(dst, b, h) do { _Pragma("unroll") for (int n = 0; n < 2; ++n) _Pragma("unroll") for (int k = 0; k < 2; ++k) dst[n][k] = *(const PG8_LAS bf16x8*)(lds + PG8_SB(b, h) + boff + n * 2048 + k * 1024); } while (0)
; #define PG8_MMA(ai, bj, At, Bt) do { __builtin_amdgcn_s_setprio(1); _Pragma("unroll") for (int m = 0; m < 4; ++m) _Pragma("unroll") for (int n = 0; n < 2; ++n) _Pragma("unroll") for (int k = 0; k < 2; ++k) \
;         acc[ai][bj][m][n] = __builtin_amdgcn_mfma_f32_16x16x32_bf16(Bt[n][k], At[m][k], acc[ai][bj][m][n], 0, 0, 0); __builtin_amdgcn_s_setprio(0); } while (0)
; #define PG8_WAIT_V(n) asm volatile("s_waitcnt vmcnt(" #n ")" ::: "memory")
; #define PG8_WAIT_L(n) asm volatile("s_waitcnt lgkmcnt(" #n ")" ::: "memory")
; #define PG8_BAR __builtin_amdgcn_s_barrier()
; #define PG8_SCHED __builtin_amdgcn_sched_barrier(0)
; template <class Epi, class Sched, bool ALIGN_EPI = false, bool SP2 = false>
; __device__ __forceinline__ void gemm_phase(PG8_LAS unsigned char* lds, const Gemm g, const Sched& S, const Epi& E) {
;     ...
;             PG8_WAIT_V(8); PG8_WAIT_L(0); PG8_BAR; PG8_MMA(1, 0, At, B0); PG8_MMA(1, 1, At, B1); PG8_BAR; PG8_SCHED;
;             PG8_LDB(B0, 1, 0); PG8_LDB(B1, 1, 1); PG8_SCHED; PG8_LDA(At, 1, 0); PG8_STAGE(PG8_SA(0, 1), a2 + hstep, voffA);
;             PG8_WAIT_V(8); PG8_WAIT_L(0); PG8_BAR; PG8_MMA(0, 0, At, B0); PG8_MMA(0, 1, At, B1); PG8_BAR; PG8_SCHED;
	s_setprio 1
	s_waitcnt lgkmcnt(7)
	v_mfma_f32_16x16x32_bf16 v[62:65], v[134:137], v[178:181], v[62:65]
	v_mfma_f32_16x16x32_bf16 v[62:65], v[150:153], v[182:185], v[62:65]
	s_waitcnt lgkmcnt(5)
	v_mfma_f32_16x16x32_bf16 v[58:61], v[158:161], v[182:185], v[58:61]
	v_mfma_f32_16x16x32_bf16 v[58:61], v[154:157], v[178:181], v[58:61]
	s_waitcnt lgkmcnt(3)
	v_mfma_f32_16x16x32_bf16 v[42:45], v[154:157], v[186:189], v[42:45]
	v_mfma_f32_16x16x32_bf16 v[42:45], v[158:161], v[190:193], v[42:45]
	s_waitcnt lgkmcnt(1)
	v_mfma_f32_16x16x32_bf16 v[46:49], v[150:153], v[190:193], v[46:49]
	v_mfma_f32_16x16x32_bf16 v[46:49], v[134:137], v[186:189], v[46:49]
	v_mfma_f32_16x16x32_bf16 v[30:33], v[134:137], v[194:197], v[30:33]
	v_mfma_f32_16x16x32_bf16 v[30:33], v[150:153], v[198:201], v[30:33]
	v_mfma_f32_16x16x32_bf16 v[26:29], v[158:161], v[198:201], v[26:29]
	v_mfma_f32_16x16x32_bf16 v[26:29], v[154:157], v[194:197], v[26:29]
	v_mfma_f32_16x16x32_bf16 v[10:13], v[154:157], v[252:255], v[10:13]
	v_mfma_f32_16x16x32_bf16 v[10:13], v[158:161], v[206:209], v[10:13]
	s_waitcnt lgkmcnt(0)
	v_mfma_f32_16x16x32_bf16 v[14:17], v[150:153], v[206:209], v[14:17]
	v_mfma_f32_16x16x32_bf16 v[14:17], v[134:137], v[252:255], v[14:17]
	s_setprio 0
	s_setprio 1
	v_mfma_f32_16x16x32_bf16 v[54:57], v[162:165], v[178:181], v[54:57]
	v_mfma_f32_16x16x32_bf16 v[54:57], v[166:169], v[182:185], v[54:57]
	v_mfma_f32_16x16x32_bf16 v[50:53], v[174:177], v[182:185], v[50:53]
	v_mfma_f32_16x16x32_bf16 v[50:53], v[170:173], v[178:181], v[50:53]
	v_mfma_f32_16x16x32_bf16 v[34:37], v[170:173], v[186:189], v[34:37]
	v_mfma_f32_16x16x32_bf16 v[34:37], v[174:177], v[190:193], v[34:37]
	v_mfma_f32_16x16x32_bf16 v[38:41], v[166:169], v[190:193], v[38:41]
	v_mfma_f32_16x16x32_bf16 v[38:41], v[162:165], v[186:189], v[38:41]
	v_mfma_f32_16x16x32_bf16 v[22:25], v[162:165], v[194:197], v[22:25]
	v_mfma_f32_16x16x32_bf16 v[22:25], v[166:169], v[198:201], v[22:25]
	v_mfma_f32_16x16x32_bf16 v[18:21], v[174:177], v[198:201], v[18:21]
	v_mfma_f32_16x16x32_bf16 v[18:21], v[170:173], v[194:197], v[18:21]
	v_mfma_f32_16x16x32_bf16 v[2:5], v[170:173], v[252:255], v[2:5]
	v_mfma_f32_16x16x32_bf16 v[2:5], v[174:177], v[206:209], v[2:5]
	v_mfma_f32_16x16x32_bf16 v[6:9], v[166:169], v[206:209], v[6:9]
	s_setprio 2
	s_barrier
	v_mfma_f32_16x16x32_bf16 v[6:9], v[162:165], v[252:255], v[6:9]
	s_setprio 0
	ds_read_b128 v[134:137], v148
	ds_read_b128 v[150:153], v148 offset:1024
	ds_read_b128 v[154:157], v148 offset:2048
	ds_read_b128 v[158:161], v148 offset:3072
	ds_read_b128 v[248:251], v149
	ds_read_b128 v[166:169], v149 offset:1024
	ds_read_b128 v[170:173], v149 offset:2048
	ds_read_b128 v[174:177], v149 offset:3072
	ds_read_b128 v[178:181], v147 offset:32768
	ds_read_b128 v[182:185], v147 offset:33792
	ds_read_b128 v[186:189], v147 offset:34816
	ds_read_b128 v[190:193], v147 offset:35840
	ds_read_b128 v[194:197], v147 offset:36864
	ds_read_b128 v[198:201], v147 offset:37888
	ds_read_b128 v[202:205], v147 offset:38912
	ds_read_b128 v[206:209], v147 offset:39936
	s_add_u32 s36, s44, 0x2b0000
	s_addc_u32 s37, s45, 0
	s_mov_b32 m0, s52
	s_nop 0
	global_load_lds_dwordx4 v1, s[36:37]
	s_nop 0
	s_mov_b32 m0, s53
	s_nop 0
	global_load_lds_dwordx4 v141, s[36:37]
	s_waitcnt vmcnt(8)
	s_waitcnt lgkmcnt(0)
	s_barrier
	s_setprio 1
	s_waitcnt lgkmcnt(7)
	v_mfma_f32_16x16x32_bf16 v[126:129], v[134:137], v[178:181], v[126:129]
	v_mfma_f32_16x16x32_bf16 v[126:129], v[150:153], v[182:185], v[126:129]
	s_waitcnt lgkmcnt(5)
	v_mfma_f32_16x16x32_bf16 v[122:125], v[158:161], v[182:185], v[122:125]
	v_mfma_f32_16x16x32_bf16 v[122:125], v[154:157], v[178:181], v[122:125]
	s_waitcnt lgkmcnt(3)
	v_mfma_f32_16x16x32_bf16 v[106:109], v[154:157], v[186:189], v[106:109]
	v_mfma_f32_16x16x32_bf16 v[106:109], v[158:161], v[190:193], v[106:109]
	s_waitcnt lgkmcnt(1)
	v_mfma_f32_16x16x32_bf16 v[110:113], v[150:153], v[190:193], v[110:113]
	v_mfma_f32_16x16x32_bf16 v[110:113], v[134:137], v[186:189], v[110:113]
	v_mfma_f32_16x16x32_bf16 v[94:97], v[134:137], v[194:197], v[94:97]
	v_mfma_f32_16x16x32_bf16 v[94:97], v[150:153], v[198:201], v[94:97]
	v_mfma_f32_16x16x32_bf16 v[90:93], v[158:161], v[198:201], v[90:93]
	v_mfma_f32_16x16x32_bf16 v[90:93], v[154:157], v[194:197], v[90:93]
	v_mfma_f32_16x16x32_bf16 v[74:77], v[154:157], v[202:205], v[74:77]
	v_mfma_f32_16x16x32_bf16 v[74:77], v[158:161], v[206:209], v[74:77]
	s_waitcnt lgkmcnt(0)
	v_mfma_f32_16x16x32_bf16 v[78:81], v[150:153], v[206:209], v[78:81]
	v_mfma_f32_16x16x32_bf16 v[78:81], v[134:137], v[202:205], v[78:81]
	s_setprio 0
	s_setprio 1
	v_mfma_f32_16x16x32_bf16 v[118:121], v[248:251], v[178:181], v[118:121]
	v_mfma_f32_16x16x32_bf16 v[118:121], v[166:169], v[182:185], v[118:121]
	v_mfma_f32_16x16x32_bf16 v[114:117], v[174:177], v[182:185], v[114:117]
	v_mfma_f32_16x16x32_bf16 v[114:117], v[170:173], v[178:181], v[114:117]
	v_mfma_f32_16x16x32_bf16 v[98:101], v[170:173], v[186:189], v[98:101]
	v_mfma_f32_16x16x32_bf16 v[98:101], v[174:177], v[190:193], v[98:101]
	v_mfma_f32_16x16x32_bf16 v[102:105], v[166:169], v[190:193], v[102:105]
	v_mfma_f32_16x16x32_bf16 v[102:105], v[248:251], v[186:189], v[102:105]
	v_mfma_f32_16x16x32_bf16 v[86:89], v[248:251], v[194:197], v[86:89]
	v_mfma_f32_16x16x32_bf16 v[86:89], v[166:169], v[198:201], v[86:89]
	v_mfma_f32_16x16x32_bf16 v[82:85], v[174:177], v[198:201], v[82:85]
	v_mfma_f32_16x16x32_bf16 v[82:85], v[170:173], v[194:197], v[82:85]
	v_mfma_f32_16x16x32_bf16 v[66:69], v[170:173], v[202:205], v[66:69]
	v_mfma_f32_16x16x32_bf16 v[66:69], v[174:177], v[206:209], v[66:69]
	v_mfma_f32_16x16x32_bf16 v[70:73], v[166:169], v[206:209], v[70:73]
	s_setprio 2
	s_barrier
; #define PG8_STAGE(bufoff, gbase, voff) do { _Pragma("unroll") for (int _i = 0; _i < 2; ++_i) \
;         asm volatile("s_mov_b32 m0, %2\n\ts_nop 0\n\tglobal_load_lds_dwordx4 %0, %1" :: "v"((voff)[_i]), "s"((const char*)(gbase)), "s"(ldsbase + (unsigned)(bufoff) + ldsw + (unsigned)_i * 8192u) : "memory", "m0"); } while (0)
; #define PG8_LDA(dst, b, h) do { _Pragma("unroll") for (int m = 0; m < 4; ++m) _Pragma("unroll") for (int k = 0; k < 2; ++k) dst[m][k] = *(const PG8_LAS bf16x8*)(lds + PG8_SA(b, h) + aoff + m * 2048 + k * 1024); } while (0)
; #define PG8_MMA(ai, bj, At, Bt) do { __builtin_amdgcn_s_setprio(1); _Pragma("unroll") for (int m = 0; m < 4; ++m) _Pragma("unroll") for (int n = 0; n < 2; ++n) _Pragma("unroll") for (int k = 0; k < 2; ++k) \
;         acc[ai][bj][m][n] = __builtin_amdgcn_mfma_f32_16x16x32_bf16(Bt[n][k], At[m][k], acc[ai][bj][m][n], 0, 0, 0); __builtin_amdgcn_s_setprio(0); } while (0)
; #define PG8_WAIT_V(n) asm volatile("s_waitcnt vmcnt(" #n ")" ::: "memory")
; #define PG8_WAIT_L(n) asm volatile("s_waitcnt lgkmcnt(" #n ")" ::: "memory")
; #define PG8_BAR __builtin_amdgcn_s_barrier()
; #define PG8_SCHED __builtin_amdgcn_sched_barrier(0)
; template <class Epi, class Sched, bool ALIGN_EPI = false, bool SP2 = false>
; __device__ __forceinline__ void gemm_phase(PG8_LAS unsigned char* lds, const Gemm g, const Sched& S, const Epi& E) {
;     ...
;             PG8_WAIT_V(8); PG8_WAIT_L(0); PG8_BAR; PG8_MMA(0, 0, At, B0); PG8_MMA(0, 1, At, B1); PG8_BAR; PG8_SCHED;
;             PG8_LDA(At, 1, 1); PG8_STAGE(PG8_SB(1, 0), b3, voffB); PG8_STAGE(PG8_SB(1, 1), b3 + hstep, voffB); PG8_STAGE(PG8_SA(1, 0), a3, voffA);
;             PG8_WAIT_V(8); PG8_WAIT_L(0); PG8_BAR; PG8_MMA(1, 0, At, B0); PG8_MMA(1, 1, At, B1); PG8_BAR; PG8_SCHED;
	v_mfma_f32_16x16x32_bf16 v[70:73], v[248:251], v[202:205], v[70:73]
	s_setprio 0
	ds_read_b128 v[178:181], v147 offset:49152
	ds_read_b128 v[182:185], v147 offset:50176
	ds_read_b128 v[186:189], v147 offset:51200
	ds_read_b128 v[190:193], v147 offset:52224
	ds_read_b128 v[194:197], v147 offset:53248
	ds_read_b128 v[198:201], v147 offset:54272
	ds_read_b128 v[252:255], v147 offset:55296
	ds_read_b128 v[206:209], v147 offset:56320
	s_add_u32 s36, s42, 0x80
	s_addc_u32 s37, s43, 0
	s_mov_b32 m0, s54
	s_nop 0
	global_load_lds_dwordx4 v140, s[36:37]
	s_nop 0
	s_mov_b32 m0, s55
	s_nop 0
	global_load_lds_dwordx4 v142, s[36:37]
	s_add_u32 s36, s42, 0x2b0080
	s_addc_u32 s37, s43, 0
	s_mov_b32 m0, s58
	s_nop 0
	global_load_lds_dwordx4 v140, s[36:37]
	s_nop 0
	s_mov_b32 m0, s59
	s_nop 0
	global_load_lds_dwordx4 v142, s[36:37]
	s_nop 0
	s_mov_b32 m0, s56
	s_nop 0
	global_load_lds_dwordx4 v1, s[40:41]
	s_nop 0
	s_mov_b32 m0, s57
	s_nop 0
	global_load_lds_dwordx4 v141, s[40:41]
	s_waitcnt vmcnt(8)
	s_waitcnt lgkmcnt(0)
	s_barrier
	s_setprio 1
	s_waitcnt lgkmcnt(7)
	v_mfma_f32_16x16x32_bf16 v[62:65], v[134:137], v[178:181], v[62:65]
	v_mfma_f32_16x16x32_bf16 v[62:65], v[150:153], v[182:185], v[62:65]
	s_waitcnt lgkmcnt(5)
	v_mfma_f32_16x16x32_bf16 v[58:61], v[158:161], v[182:185], v[58:61]
	v_mfma_f32_16x16x32_bf16 v[58:61], v[154:157], v[178:181], v[58:61]
	s_waitcnt lgkmcnt(3)
	v_mfma_f32_16x16x32_bf16 v[42:45], v[154:157], v[186:189], v[42:45]
	v_mfma_f32_16x16x32_bf16 v[42:45], v[158:161], v[190:193], v[42:45]
	s_waitcnt lgkmcnt(1)
	v_mfma_f32_16x16x32_bf16 v[46:49], v[150:153], v[190:193], v[46:49]
	v_mfma_f32_16x16x32_bf16 v[46:49], v[134:137], v[186:189], v[46:49]
	v_mfma_f32_16x16x32_bf16 v[30:33], v[134:137], v[194:197], v[30:33]
	v_mfma_f32_16x16x32_bf16 v[30:33], v[150:153], v[198:201], v[30:33]
	v_mfma_f32_16x16x32_bf16 v[26:29], v[158:161], v[198:201], v[26:29]
	v_mfma_f32_16x16x32_bf16 v[26:29], v[154:157], v[194:197], v[26:29]
	v_mfma_f32_16x16x32_bf16 v[10:13], v[154:157], v[252:255], v[10:13]
	v_mfma_f32_16x16x32_bf16 v[10:13], v[158:161], v[206:209], v[10:13]
	s_waitcnt lgkmcnt(0)
	v_mfma_f32_16x16x32_bf16 v[14:17], v[150:153], v[206:209], v[14:17]
	v_mfma_f32_16x16x32_bf16 v[14:17], v[134:137], v[252:255], v[14:17]
	s_setprio 0
	s_setprio 1
	v_mfma_f32_16x16x32_bf16 v[54:57], v[248:251], v[178:181], v[54:57]
	v_mfma_f32_16x16x32_bf16 v[54:57], v[166:169], v[182:185], v[54:57]
	v_mfma_f32_16x16x32_bf16 v[50:53], v[174:177], v[182:185], v[50:53]
	v_mfma_f32_16x16x32_bf16 v[50:53], v[170:173], v[178:181], v[50:53]
	v_mfma_f32_16x16x32_bf16 v[34:37], v[170:173], v[186:189], v[34:37]
	v_mfma_f32_16x16x32_bf16 v[34:37], v[174:177], v[190:193], v[34:37]
	v_mfma_f32_16x16x32_bf16 v[38:41], v[166:169], v[190:193], v[38:41]
	v_mfma_f32_16x16x32_bf16 v[38:41], v[248:251], v[186:189], v[38:41]
	v_mfma_f32_16x16x32_bf16 v[22:25], v[248:251], v[194:197], v[22:25]
	v_mfma_f32_16x16x32_bf16 v[22:25], v[166:169], v[198:201], v[22:25]
	v_mfma_f32_16x16x32_bf16 v[18:21], v[174:177], v[198:201], v[18:21]
	v_mfma_f32_16x16x32_bf16 v[18:21], v[170:173], v[194:197], v[18:21]
	v_mfma_f32_16x16x32_bf16 v[2:5], v[170:173], v[252:255], v[2:5]
	v_mfma_f32_16x16x32_bf16 v[2:5], v[174:177], v[206:209], v[2:5]
	v_mfma_f32_16x16x32_bf16 v[6:9], v[166:169], v[206:209], v[6:9]
	s_setprio 2
	s_barrier
	v_mfma_f32_16x16x32_bf16 v[6:9], v[248:251], v[252:255], v[6:9]
	s_setprio 0
	s_add_i32 s69, s69, 2
	s_add_u32 s67, s67, 0x100
	s_addc_u32 s68, s68, 0
	s_cmpk_gt_u32 s69, 0xa9
	s_mov_b64 s[36:37], s[38:39]
	s_cbranch_scc0 .LBB0_873
	s_and_b64 vcc, exec, s[10:11]
	s_cbranch_vccz .LBB0_876
	s_barrier
